# GEMM8 epilogue: cache the 8 row-rstd values across tiles with the same M panel (skip ssq reload+reduce); GEMM9 fused epilogue: batched residual/exchange loads; ret_out: finish ldf/ldb loads at loop to
# speedup vs baseline: 1.0156x; 1.0020x over previous
; #define MMA16(b, a, c) __builtin_amdgcn_mfma_f32_16x16x32_bf16((b), (a), (c), 0, 0, 0)
; __device__ __forceinline__ void ret_out_phase(const Params& p, LAS unsigned char* lds, int G) {
;     ...
;         { const bf16_t* gsrc = proj + (size_t)(row0 + il) * DIN + 2304 + h * 128 + 4 * fq;
; #pragma unroll
;             for (int n = 0; n < 8; ++n) gv[n] = *(const u32x2*)(gsrc + 16 * n); }
;         {
;             const bf16_t* sf = kvbuf + ((size_t)(c * 4 + h) * 2) * 16384 + stok * 128 + sdch * 8;
; #pragma unroll
;             for (int i = 0; i < 4; ++i) { sfr[i] = *(const u32x4*)(sf + i * 32 * 128); sbr[i] = *(const u32x4*)(sf + 16384 + i * 32 * 128); }
;         }
;         bf16x8 qa[4];
; #pragma unroll
;         for (int k = 0; k < 4; ++k) qa[k] = LDS16(Ql + il * 136 + 32 * k + 8 * fq);
;         f32x4 o1[8];
;         {
;             f32x4 s[8];
; #pragma unroll
;             for (int n = 0; n < 8; ++n) s[n] = (f32x4){0.f, 0.f, 0.f, 0.f};
; #pragma unroll
;             for (int k = 0; k < 4; ++k) {
; #pragma unroll
;                 for (int nh = 0; nh < 2; ++nh) { bf16x8 bf[4];
; #pragma unroll
;                     for (int n = 0; n < 4; ++n) bf[n] = LDS16(Kl + (16 * (4 * nh + n) + fr) * 136 + 32 * k + 8 * fq);
; #pragma unroll
;                     for (int n = 0; n < 4; ++n) s[4 * nh + n] = MMA16(bf[n], qa[k], s[4 * nh + n]); }
;             }
; #pragma unroll
;             for (int n = 0; n < 8; ++n) { f32x4 pvv;
; #pragma unroll
;                 for (int e = 0; e < 4; ++e) { const int j = 16 * n + 4 * fq + e, dlt = il - j; const float coef = dlt > 0 ? ldf2 : ldb2; const float ex = __builtin_amdgcn_exp2f(coef * (float)(dlt > 0 ? dlt : -dlt)); pvv[e] = s[n][e] * (dlt == 0 ? 2.0f : ex); }
.LBB0_697:
	s_and_b32 s52, s63, 0xffffff80
	v_add_u32_e32 v142, s52, v145
	v_mov_b64_e32 v[48:49], s[50:51]
	s_movk_i32 s52, 0x1600
	v_mad_i64_i32 v[48:49], vcc, v142, s52, v[48:49]
	s_lshl_b32 s52, s64, 8
	v_lshl_add_u64 v[48:49], v[48:49], 0, s[52:53]
	v_lshl_add_u64 v[48:49], v[48:49], 0, v[120:121]
	s_mov_b64 s[64:65], 0x1200
	s_movk_i32 s63, 0x1000
	v_lshl_add_u64 v[50:51], v[48:49], 0, s[64:65]
	v_add_co_u32_e32 v48, vcc, s63, v48
	s_mov_b32 s63, 0x8000
	s_nop 0
	v_addc_co_u32_e32 v49, vcc, 0, v49, vcc
	global_load_dwordx2 v[140:141], v[48:49], off offset:512
	global_load_dwordx2 v[138:139], v[50:51], off offset:32
	global_load_dwordx2 v[136:137], v[50:51], off offset:64
	global_load_dwordx2 v[134:135], v[50:51], off offset:96
	global_load_dwordx2 v[132:133], v[50:51], off offset:128
	global_load_dwordx2 v[130:131], v[50:51], off offset:160
	global_load_dwordx2 v[128:129], v[50:51], off offset:192
	global_load_dwordx2 v[126:127], v[50:51], off offset:224
	global_load_dwordx4 v[64:67], v[122:123], off
	v_add_co_u32_e32 v48, vcc, s63, v122
	s_movk_i32 s63, 0x2000
	s_nop 0
	v_addc_co_u32_e32 v49, vcc, 0, v123, vcc
	global_load_dwordx4 v[68:71], v[48:49], off
	v_add_co_u32_e32 v48, vcc, s63, v122
	s_mov_b32 s63, 0xa000
	s_nop 0
	v_addc_co_u32_e32 v49, vcc, 0, v123, vcc
	global_load_dwordx4 v[72:75], v[48:49], off
	v_add_co_u32_e32 v48, vcc, s63, v122
	s_movk_i32 s63, 0x4000
	s_nop 0
	v_addc_co_u32_e32 v49, vcc, 0, v123, vcc
	global_load_dwordx4 v[76:79], v[48:49], off
	v_add_co_u32_e32 v48, vcc, s63, v122
	s_mov_b32 s63, 0xc000
	s_nop 0
	v_addc_co_u32_e32 v49, vcc, 0, v123, vcc
	global_load_dwordx4 v[80:83], v[48:49], off
	v_add_co_u32_e32 v48, vcc, s63, v122
	s_movk_i32 s63, 0x6000
	s_nop 0
	v_addc_co_u32_e32 v49, vcc, 0, v123, vcc
	global_load_dwordx4 v[84:87], v[48:49], off
	v_add_co_u32_e32 v48, vcc, s63, v122
	s_mov_b32 s63, 0xe000
	s_nop 0
	v_addc_co_u32_e32 v49, vcc, 0, v123, vcc
	global_load_dwordx4 v[88:91], v[48:49], off
	v_add_co_u32_e32 v48, vcc, s63, v122
	v_add_u32_e32 v125, v147, v154
	s_nop 0
	v_addc_co_u32_e32 v49, vcc, 0, v123, vcc
	global_load_dwordx4 v[92:95], v[48:49], off
	v_add_u32_e32 v48, v147, v148
	ds_read_b128 v[60:63], v48
	ds_read_b128 v[56:59], v48 offset:64
	ds_read_b128 v[52:55], v48 offset:128
	ds_read_b128 v[48:51], v48 offset:192
	ds_read_b128 v[96:99], v125 offset:34816
	ds_read_b128 v[100:103], v125 offset:39168
	ds_read_b128 v[104:107], v125 offset:43520
	ds_read_b128 v[108:111], v125 offset:47872
	ds_read_b128 v[112:115], v125 offset:52224
	ds_read_b128 v[116:119], v125 offset:56576
	ds_read_b128 v[194:197], v125 offset:60928
	ds_read_b128 v[200:203], v125 offset:65280
	ds_read_b128 v[204:207], v125 offset:34880
	ds_read_b128 v[208:211], v125 offset:39232
	ds_read_b128 v[212:215], v125 offset:43584
	ds_read_b128 v[216:219], v125 offset:47936
	s_waitcnt lgkmcnt(11)
	v_mfma_f32_16x16x32_bf16 v[96:99], v[96:99], v[60:63], 0
	v_readlane_b32 s64, v247, 12
	v_readlane_b32 s65, v247, 13
	v_ashrrev_i32_e32 v143, 31, v142
	s_waitcnt lgkmcnt(10)
	v_mfma_f32_16x16x32_bf16 v[100:103], v[100:103], v[60:63], 0
	v_cndmask_b32_e64 v193, v191, v192, s[64:65]
	v_readlane_b32 s64, v247, 14
	v_readlane_b32 s65, v247, 15
	s_waitcnt lgkmcnt(9)
	v_mfma_f32_16x16x32_bf16 v[104:107], v[104:107], v[60:63], 0
	v_mul_f32_e32 v193, 0x3fb8aa3b, v193
	v_mul_f32_e32 v193, v193, v156
	v_exp_f32_e32 v193, v193
	s_waitcnt lgkmcnt(8)
	v_mfma_f32_16x16x32_bf16 v[108:111], v[108:111], v[60:63], 0
	v_lshl_add_u64 v[122:123], v[122:123], 0, s[54:55]
	s_add_i32 s59, s59, s60
	s_mov_b32 s63, s62
	s_waitcnt lgkmcnt(3)
	v_mfma_f32_16x16x32_bf16 v[96:99], v[204:207], v[56:59], v[96:99]
	s_waitcnt lgkmcnt(2)
	v_mfma_f32_16x16x32_bf16 v[100:103], v[208:211], v[56:59], v[100:103]
	s_waitcnt lgkmcnt(1)
	v_mfma_f32_16x16x32_bf16 v[104:107], v[212:215], v[56:59], v[104:107]
	s_waitcnt lgkmcnt(0)
	v_mfma_f32_16x16x32_bf16 v[108:111], v[216:219], v[56:59], v[108:111]
	ds_read_b128 v[204:207], v125 offset:52288
	ds_read_b128 v[208:211], v125 offset:56640
	ds_read_b128 v[212:215], v125 offset:60992
	ds_read_b128 v[216:219], v125 offset:65344
	v_mfma_f32_16x16x32_bf16 v[112:115], v[112:115], v[60:63], 0
	v_mfma_f32_16x16x32_bf16 v[116:119], v[116:119], v[60:63], 0
	v_mfma_f32_16x16x32_bf16 v[194:197], v[194:197], v[60:63], 0
	v_mfma_f32_16x16x32_bf16 v[200:203], v[200:203], v[60:63], 0
	s_waitcnt lgkmcnt(3)
	v_mfma_f32_16x16x32_bf16 v[112:115], v[204:207], v[56:59], v[112:115]
	s_waitcnt lgkmcnt(2)
	v_mfma_f32_16x16x32_bf16 v[116:119], v[208:211], v[56:59], v[116:119]
	s_waitcnt lgkmcnt(1)
	v_mfma_f32_16x16x32_bf16 v[194:197], v[212:215], v[56:59], v[194:197]
	s_waitcnt lgkmcnt(0)
	v_mfma_f32_16x16x32_bf16 v[200:203], v[216:219], v[56:59], v[200:203]
	ds_read_b128 v[204:207], v125 offset:34944
	ds_read_b128 v[208:211], v125 offset:39296
	ds_read_b128 v[212:215], v125 offset:43648
	ds_read_b128 v[216:219], v125 offset:48000
	s_waitcnt lgkmcnt(3)
	v_mfma_f32_16x16x32_bf16 v[96:99], v[204:207], v[52:55], v[96:99]
	s_waitcnt lgkmcnt(2)
	v_mfma_f32_16x16x32_bf16 v[100:103], v[208:211], v[52:55], v[100:103]
	s_waitcnt lgkmcnt(1)
	v_mfma_f32_16x16x32_bf16 v[104:107], v[212:215], v[52:55], v[104:107]
	s_waitcnt lgkmcnt(0)
	v_mfma_f32_16x16x32_bf16 v[108:111], v[216:219], v[52:55], v[108:111]
	ds_read_b128 v[204:207], v125 offset:52352
	ds_read_b128 v[208:211], v125 offset:56704
	ds_read_b128 v[212:215], v125 offset:61056
	ds_read_b128 v[216:219], v125 offset:65408
	s_waitcnt lgkmcnt(3)
	v_mfma_f32_16x16x32_bf16 v[112:115], v[204:207], v[52:55], v[112:115]
	s_waitcnt lgkmcnt(2)
	v_mfma_f32_16x16x32_bf16 v[204:207], v[208:211], v[52:55], v[116:119]
	s_waitcnt lgkmcnt(1)
; __device__ __forceinline__ unsigned cvt_pk_bf16(float lo, float hi) { unsigned r; asm volatile("v_cvt_pk_bf16_f32 %0, %1, %2" : "=v"(r) : "v"(lo), "v"(hi)); return r; }
; #define LAS __attribute__((address_space(3)))
; __device__ __forceinline__ unsigned cvt_pk_bf16(float lo, float hi) { f32x2_t v = {lo, hi}; bf16x2_t b = __builtin_convertvector(v, bf16x2_t); return __builtin_bit_cast(unsigned, b); }
; #define MMA16(b, a, c) __builtin_amdgcn_mfma_f32_16x16x32_bf16((b), (a), (c), 0, 0, 0)
; __device__ __forceinline__ void ret_out_phase(const Params& p, LAS unsigned char* lds, int G) {
;     ...
;             for (int k = 0; k < 4; ++k) {
; #pragma unroll
;                 for (int nh = 0; nh < 2; ++nh) { bf16x8 bf[4];
; #pragma unroll
;                     for (int n = 0; n < 4; ++n) bf[n] = LDS16(Kl + (16 * (4 * nh + n) + fr) * 136 + 32 * k + 8 * fq);
; #pragma unroll
;                     for (int n = 0; n < 4; ++n) s[4 * nh + n] = MMA16(bf[n], qa[k], s[4 * nh + n]); }
;             }
; #pragma unroll
;             for (int n = 0; n < 8; ++n) { f32x4 pvv;
; #pragma unroll
;                 for (int e = 0; e < 4; ++e) { const int j = 16 * n + 4 * fq + e, dlt = il - j; const float coef = dlt > 0 ? ldf2 : ldb2; const float ex = __builtin_amdgcn_exp2f(coef * (float)(dlt > 0 ? dlt : -dlt)); pvv[e] = s[n][e] * (dlt == 0 ? 2.0f : ex); }
;                 u32x2 w; w.x = cvt_pk_bf16(pvv[0], pvv[1]); w.y = cvt_pk_bf16(pvv[2], pvv[3]);
;                 *(LAS u32x2*)(Pl + il * 136 + 16 * n + 4 * fq) = w; }
	v_mfma_f32_16x16x32_bf16 v[194:197], v[212:215], v[52:55], v[194:197]
	s_waitcnt lgkmcnt(0)
	v_mfma_f32_16x16x32_bf16 v[200:203], v[216:219], v[52:55], v[200:203]
	ds_read_b128 v[116:119], v125 offset:35008
	ds_read_b128 v[208:211], v125 offset:39360
	ds_read_b128 v[212:215], v125 offset:43712
	ds_read_b128 v[216:219], v125 offset:48064
	s_waitcnt lgkmcnt(3)
	v_mfma_f32_16x16x32_bf16 v[220:223], v[116:119], v[48:51], v[96:99]
	s_waitcnt lgkmcnt(2)
	v_mfma_f32_16x16x32_bf16 v[208:211], v[208:211], v[48:51], v[100:103]
	s_waitcnt lgkmcnt(1)
	v_mfma_f32_16x16x32_bf16 v[116:119], v[212:215], v[48:51], v[104:107]
	s_waitcnt lgkmcnt(0)
	v_mfma_f32_16x16x32_bf16 v[108:111], v[216:219], v[48:51], v[108:111]
	ds_read_b128 v[96:99], v125 offset:52416
	ds_read_b128 v[100:103], v125 offset:56768
	ds_read_b128 v[212:215], v125 offset:61120
	ds_read_b128 v[216:219], v125 offset:65472
	s_waitcnt lgkmcnt(2)
	v_mfma_f32_16x16x32_bf16 v[104:107], v[100:103], v[48:51], v[204:207]
	s_waitcnt lgkmcnt(1)
	v_mfma_f32_16x16x32_bf16 v[100:103], v[212:215], v[48:51], v[194:197]
	s_nop 2
	v_cndmask_b32_e64 v194, v191, v192, s[64:65]
	v_mul_f32_e32 v194, 0x3fb8aa3b, v194
	v_mul_f32_e32 v194, v194, v157
	v_exp_f32_e32 v194, v194
	v_readlane_b32 s64, v247, 18
	v_readlane_b32 s65, v247, 19
	v_mfma_f32_16x16x32_bf16 v[112:115], v[96:99], v[48:51], v[112:115]
	s_nop 0
	v_cndmask_b32_e64 v195, v194, 2.0, s[64:65]
	v_readlane_b32 s64, v247, 16
	v_readlane_b32 s65, v247, 17
	s_waitcnt lgkmcnt(0)
	v_mfma_f32_16x16x32_bf16 v[96:99], v[216:219], v[48:51], v[200:203]
	v_cndmask_b32_e64 v194, v193, 2.0, s[64:65]
	v_readlane_b32 s64, v247, 20
	v_readlane_b32 s65, v247, 21
	v_pk_mul_f32 v[194:195], v[194:195], v[220:221]
	s_nop 0
	v_cndmask_b32_e64 v193, v191, v192, s[64:65]
	v_readlane_b32 s64, v247, 22
	v_readlane_b32 s65, v247, 23
	v_mul_f32_e32 v193, 0x3fb8aa3b, v193
	v_mul_f32_e32 v193, v193, v158
	v_cndmask_b32_e64 v196, v191, v192, s[64:65]
	v_mul_f32_e32 v196, 0x3fb8aa3b, v196
	v_mul_f32_e32 v196, v196, v159
	v_exp_f32_e32 v196, v196
	v_exp_f32_e32 v193, v193
	v_readlane_b32 s64, v247, 24
	v_readlane_b32 s65, v247, 25
	v_cvt_pk_bf16_f32 v194, v194, v195
	s_nop 0
	v_cndmask_b32_e64 v197, v196, 2.0, s[64:65]
	v_readlane_b32 s64, v247, 26
	v_readlane_b32 s65, v247, 27
	s_nop 1
	v_cndmask_b32_e64 v196, v193, 2.0, s[64:65]
	v_readlane_b32 s64, v247, 28
	v_readlane_b32 s65, v247, 29
	v_pk_mul_f32 v[196:197], v[196:197], v[222:223]
	s_nop 0
	v_cndmask_b32_e64 v193, v191, v192, s[64:65]
	v_readlane_b32 s64, v247, 30
	v_readlane_b32 s65, v247, 31
	v_cvt_pk_bf16_f32 v195, v196, v197
	v_mul_f32_e32 v193, 0x3fb8aa3b, v193
	v_cndmask_b32_e64 v196, v191, v192, s[64:65]
	v_mul_f32_e32 v196, 0x3fb8aa3b, v196
	v_mul_f32_e32 v196, v196, v161
	v_exp_f32_e32 v196, v196
	v_mul_f32_e32 v193, v193, v160
	v_exp_f32_e32 v193, v193
	v_readlane_b32 s64, v247, 32
	v_readlane_b32 s65, v247, 33
	s_nop 1
	v_cndmask_b32_e64 v197, v196, 2.0, s[64:65]
	v_readlane_b32 s64, v247, 34
	v_readlane_b32 s65, v247, 35
	s_nop 1
	v_cndmask_b32_e64 v196, v193, 2.0, s[64:65]
	v_readlane_b32 s64, v247, 36
	v_readlane_b32 s65, v247, 37
	v_pk_mul_f32 v[196:197], v[196:197], v[208:209]
	s_nop 0
	v_cndmask_b32_e64 v193, v191, v192, s[64:65]
	v_readlane_b32 s64, v247, 38
	v_readlane_b32 s65, v247, 39
	v_mul_f32_e32 v193, 0x3fb8aa3b, v193
	v_mul_f32_e32 v193, v193, v162
	v_cndmask_b32_e64 v199, v191, v192, s[64:65]
	v_mul_f32_e32 v199, 0x3fb8aa3b, v199
	v_mul_f32_e32 v199, v199, v163
	v_exp_f32_e32 v199, v199
	v_exp_f32_e32 v193, v193
	v_readlane_b32 s64, v247, 40
	v_readlane_b32 s65, v247, 41
	v_cvt_pk_bf16_f32 v196, v196, v197
	s_nop 0
	v_cndmask_b32_e64 v201, v199, 2.0, s[64:65]
	v_readlane_b32 s64, v247, 42
	v_readlane_b32 s65, v247, 43
	s_nop 1
	v_cndmask_b32_e64 v200, v193, 2.0, s[64:65]
	v_readlane_b32 s64, v247, 44
	v_readlane_b32 s65, v247, 45
	v_pk_mul_f32 v[200:201], v[200:201], v[210:211]
	s_nop 0
	v_cndmask_b32_e64 v193, v191, v192, s[64:65]
	v_readlane_b32 s64, v247, 46
	v_cvt_pk_bf16_f32 v197, v200, v201
	v_readlane_b32 s65, v247, 47
	ds_write2_b64 v155, v[194:195], v[196:197] offset1:4
	v_mul_f32_e32 v193, 0x3fb8aa3b, v193
	v_cndmask_b32_e64 v194, v191, v192, s[64:65]
	v_mul_f32_e32 v194, 0x3fb8aa3b, v194
	v_mul_f32_e32 v194, v194, v165
	v_exp_f32_e32 v194, v194
	v_mul_f32_e32 v193, v193, v164
	v_exp_f32_e32 v193, v193
	v_readlane_b32 s64, v247, 48
	v_readlane_b32 s65, v247, 49
	s_nop 1
	v_cndmask_b32_e64 v195, v194, 2.0, s[64:65]
	v_readlane_b32 s64, v247, 50
	v_readlane_b32 s65, v247, 51
	s_nop 1
	v_cndmask_b32_e64 v194, v193, 2.0, s[64:65]
	v_readlane_b32 s64, v247, 52
	v_readlane_b32 s65, v247, 53
	v_pk_mul_f32 v[116:117], v[194:195], v[116:117]
	s_nop 0
	v_cndmask_b32_e64 v193, v191, v192, s[64:65]
	v_readlane_b32 s64, v247, 54
	v_readlane_b32 s65, v247, 55
	v_mul_f32_e32 v193, 0x3fb8aa3b, v193
	v_mul_f32_e32 v193, v193, v166
	v_cndmask_b32_e64 v194, v191, v192, s[64:65]
	v_mul_f32_e32 v194, 0x3fb8aa3b, v194
	v_mul_f32_e32 v194, v194, v167
	v_exp_f32_e32 v194, v194
	v_exp_f32_e32 v193, v193
	v_readlane_b32 s64, v247, 56
	v_readlane_b32 s65, v247, 57
	v_cvt_pk_bf16_f32 v116, v116, v117
	s_nop 0
	v_cndmask_b32_e64 v195, v194, 2.0, s[64:65]
	v_readlane_b32 s64, v247, 58
	v_readlane_b32 s65, v247, 59
	s_nop 1
	v_cndmask_b32_e64 v194, v193, 2.0, s[64:65]
	v_readlane_b32 s64, v247, 60
	v_pk_mul_f32 v[118:119], v[194:195], v[118:119]
	v_readlane_b32 s65, v247, 61
	v_cvt_pk_bf16_f32 v117, v118, v119
	s_nop 0
	v_cndmask_b32_e64 v118, v191, v192, s[64:65]
	v_readlane_b32 s64, v247, 62
	v_readlane_b32 s65, v247, 63
	v_mul_f32_e32 v118, 0x3fb8aa3b, v118
	v_mul_f32_e32 v118, v118, v168
	v_cndmask_b32_e64 v119, v191, v192, s[64:65]
; __device__ __forceinline__ unsigned cvt_pk_bf16(float lo, float hi) { unsigned r; asm volatile("v_cvt_pk_bf16_f32 %0, %1, %2" : "=v"(r) : "v"(lo), "v"(hi)); return r; }
; #define LAS __attribute__((address_space(3)))
; __device__ __forceinline__ unsigned cvt_pk_bf16(float lo, float hi) { f32x2_t v = {lo, hi}; bf16x2_t b = __builtin_convertvector(v, bf16x2_t); return __builtin_bit_cast(unsigned, b); }
; __device__ __forceinline__ void ret_out_phase(const Params& p, LAS unsigned char* lds, int G) {
;     ...
;             for (int n = 0; n < 8; ++n) { f32x4 pvv;
; #pragma unroll
;                 for (int e = 0; e < 4; ++e) { const int j = 16 * n + 4 * fq + e, dlt = il - j; const float coef = dlt > 0 ? ldf2 : ldb2; const float ex = __builtin_amdgcn_exp2f(coef * (float)(dlt > 0 ? dlt : -dlt)); pvv[e] = s[n][e] * (dlt == 0 ? 2.0f : ex); }
;                 u32x2 w; w.x = cvt_pk_bf16(pvv[0], pvv[1]); w.y = cvt_pk_bf16(pvv[2], pvv[3]);
;                 *(LAS u32x2*)(Pl + il * 136 + 16 * n + 4 * fq) = w; }
;             asm volatile("s_waitcnt lgkmcnt(0)" ::: "memory");
;             bf16x8 pa[4];
; #pragma unroll
;             for (int k = 0; k < 4; ++k) pa[k] = LDS16(Pl + il * 136 + 32 * k + 8 * fq);
; #pragma unroll
;             for (int n = 0; n < 8; ++n) o1[n] = (f32x4){0.f, 0.f, 0.f, 0.f};
; #pragma unroll
;             for (int k = 0; k < 4; ++k) {
; #pragma unroll
;                 for (int nh = 0; nh < 2; ++nh) { bf16x8 bf[4];
; #pragma unroll
;                     for (int n = 0; n < 4; ++n) bf[n] = tr_frag(Vl + 32 * k * 136 + trb + 16 * (4 * nh + n), 136);
	v_mul_f32_e32 v119, 0x3fb8aa3b, v119
	v_mul_f32_e32 v119, v119, v169
	v_exp_f32_e32 v119, v119
	v_exp_f32_e32 v118, v118
	v_readlane_b32 s64, v246, 0
	v_readlane_b32 s65, v246, 1
	s_nop 1
	v_cndmask_b32_e64 v119, v119, 2.0, s[64:65]
	v_readlane_b32 s64, v246, 2
	v_readlane_b32 s65, v246, 3
	s_nop 1
	v_cndmask_b32_e64 v118, v118, 2.0, s[64:65]
	v_readlane_b32 s64, v246, 4
	v_readlane_b32 s65, v246, 5
	v_pk_mul_f32 v[108:109], v[118:119], v[108:109]
	s_nop 0
	v_cndmask_b32_e64 v118, v191, v192, s[64:65]
	v_readlane_b32 s64, v246, 6
	v_readlane_b32 s65, v246, 7
	v_mul_f32_e32 v118, 0x3fb8aa3b, v118
	v_mul_f32_e32 v118, v118, v170
	v_cndmask_b32_e64 v119, v191, v192, s[64:65]
	v_mul_f32_e32 v119, 0x3fb8aa3b, v119
	v_mul_f32_e32 v119, v119, v171
	v_exp_f32_e32 v118, v118
	v_exp_f32_e32 v119, v119
	v_readlane_b32 s64, v246, 8
	v_readlane_b32 s65, v246, 9
	v_cndmask_b32_e64 v118, v118, 2.0, s[70:71]
	v_cvt_pk_bf16_f32 v108, v108, v109
	v_cndmask_b32_e64 v119, v119, 2.0, s[64:65]
	v_pk_mul_f32 v[110:111], v[118:119], v[110:111]
	s_mov_b64 s[64:65], 0x9000400
	v_cvt_pk_bf16_f32 v109, v110, v111
	ds_write2_b64 v155, v[116:117], v[108:109] offset0:8 offset1:12
	v_cndmask_b32_e64 v108, v191, v192, s[72:73]
	v_cndmask_b32_e64 v109, v191, v192, s[74:75]
	v_cndmask_b32_e64 v110, v191, v192, s[80:81]
	v_cndmask_b32_e64 v111, v191, v192, s[82:83]
	v_mul_f32_e32 v108, 0x3fb8aa3b, v108
	v_mul_f32_e32 v109, 0x3fb8aa3b, v109
	v_mul_f32_e32 v110, 0x3fb8aa3b, v110
	v_mul_f32_e32 v111, 0x3fb8aa3b, v111
	v_mul_f32_e32 v108, v108, v172
	v_mul_f32_e32 v109, v109, v173
	v_mul_f32_e32 v110, v110, v174
	v_mul_f32_e32 v111, v111, v175
	v_exp_f32_e32 v108, v108
	v_exp_f32_e32 v109, v109
	v_exp_f32_e32 v110, v110
	v_exp_f32_e32 v111, v111
	v_cndmask_b32_e64 v108, v108, 2.0, s[78:79]
	v_cndmask_b32_e64 v109, v109, 2.0, s[76:77]
	v_cndmask_b32_e64 v110, v110, 2.0, s[86:87]
	v_cndmask_b32_e64 v111, v111, 2.0, s[84:85]
	v_pk_mul_f32 v[108:109], v[108:109], v[112:113]
	v_pk_mul_f32 v[110:111], v[110:111], v[114:115]
	v_cvt_pk_bf16_f32 v108, v108, v109
	v_cvt_pk_bf16_f32 v109, v110, v111
	v_cndmask_b32_e64 v110, v191, v192, s[66:67]
	v_cndmask_b32_e64 v111, v191, v192, s[90:91]
	v_mul_f32_e32 v110, 0x3fb8aa3b, v110
	v_mul_f32_e32 v111, 0x3fb8aa3b, v111
	v_mul_f32_e32 v110, v110, v176
	v_mul_f32_e32 v111, v111, v177
	v_exp_f32_e32 v110, v110
	v_exp_f32_e32 v111, v111
	v_cndmask_b32_e64 v110, v110, 2.0, s[94:95]
	v_cndmask_b32_e64 v111, v111, 2.0, s[92:93]
	v_pk_mul_f32 v[104:105], v[110:111], v[104:105]
	v_cndmask_b32_e64 v110, v191, v192, s[96:97]
	v_cndmask_b32_e64 v111, v191, v192, s[4:5]
	v_mul_f32_e32 v110, 0x3fb8aa3b, v110
	v_mul_f32_e32 v111, 0x3fb8aa3b, v111
	v_mul_f32_e32 v110, v110, v178
	v_mul_f32_e32 v111, v111, v179
	v_exp_f32_e32 v110, v110
	v_exp_f32_e32 v111, v111
	v_cvt_pk_bf16_f32 v104, v104, v105
	v_cndmask_b32_e64 v110, v110, 2.0, s[2:3]
	v_cndmask_b32_e64 v111, v111, 2.0, s[6:7]
	v_pk_mul_f32 v[106:107], v[110:111], v[106:107]
	s_nop 0
	v_cvt_pk_bf16_f32 v105, v106, v107
	ds_write2_b64 v155, v[108:109], v[104:105] offset0:16 offset1:20
	v_cndmask_b32_e64 v104, v191, v192, s[0:1]
	v_cndmask_b32_e64 v105, v191, v192, s[8:9]
	v_mul_f32_e32 v104, 0x3fb8aa3b, v104
	v_mul_f32_e32 v105, 0x3fb8aa3b, v105
	v_mul_f32_e32 v104, v104, v180
	v_mul_f32_e32 v105, v105, v181
	v_exp_f32_e32 v104, v104
	v_exp_f32_e32 v105, v105
	v_add_u32_e32 v108, v146, v148
	v_cndmask_b32_e64 v104, v104, 2.0, s[12:13]
	v_cndmask_b32_e64 v105, v105, 2.0, s[10:11]
	v_pk_mul_f32 v[100:101], v[104:105], v[100:101]
	v_cndmask_b32_e64 v104, v191, v192, s[14:15]
	v_cndmask_b32_e64 v105, v191, v192, s[16:17]
	v_mul_f32_e32 v104, 0x3fb8aa3b, v104
	v_mul_f32_e32 v105, 0x3fb8aa3b, v105
	v_mul_f32_e32 v104, v104, v182
	v_mul_f32_e32 v105, v105, v183
	v_exp_f32_e32 v104, v104
	v_exp_f32_e32 v105, v105
	v_cvt_pk_bf16_f32 v100, v100, v101
	v_cndmask_b32_e64 v104, v104, 2.0, s[20:21]
	v_cndmask_b32_e64 v105, v105, 2.0, s[18:19]
	v_pk_mul_f32 v[102:103], v[104:105], v[102:103]
	s_nop 0
	v_cvt_pk_bf16_f32 v101, v102, v103
	v_cndmask_b32_e64 v102, v191, v192, s[22:23]
	v_cndmask_b32_e64 v103, v191, v192, s[24:25]
	v_mul_f32_e32 v102, 0x3fb8aa3b, v102
	v_mul_f32_e32 v103, 0x3fb8aa3b, v103
	v_mul_f32_e32 v102, v102, v184
	v_mul_f32_e32 v103, v103, v185
	v_exp_f32_e32 v102, v102
	v_exp_f32_e32 v103, v103
	v_cndmask_b32_e64 v102, v102, 2.0, s[28:29]
	v_cndmask_b32_e64 v103, v103, 2.0, s[26:27]
	v_pk_mul_f32 v[96:97], v[102:103], v[96:97]
	v_cndmask_b32_e64 v102, v191, v192, s[30:31]
	v_cndmask_b32_e64 v103, v191, v192, s[34:35]
	v_mul_f32_e32 v102, 0x3fb8aa3b, v102
	v_mul_f32_e32 v103, 0x3fb8aa3b, v103
	v_mul_f32_e32 v102, v102, v186
	v_mul_f32_e32 v103, v103, v187
	v_exp_f32_e32 v102, v102
	v_exp_f32_e32 v103, v103
	v_cvt_pk_bf16_f32 v96, v96, v97
	v_cndmask_b32_e64 v102, v102, 2.0, s[38:39]
	v_cndmask_b32_e64 v103, v103, 2.0, s[36:37]
	v_pk_mul_f32 v[98:99], v[102:103], v[98:99]
	s_nop 0
	v_cvt_pk_bf16_f32 v97, v98, v99
	ds_write2_b64 v155, v[100:101], v[96:97] offset0:24 offset1:28
	s_waitcnt lgkmcnt(0)
	ds_read_b128 v[96:99], v108
	ds_read_b128 v[100:103], v108 offset:64
	ds_read_b128 v[104:107], v108 offset:128
	ds_read_b128 v[108:111], v108 offset:192
	ds_read_b64_tr_b16 v[114:115], v149 offset:1088
	ds_read_b64_tr_b16 v[112:113], v149
	ds_read_b64_tr_b16 v[116:117], v149 offset:32
	ds_read_b64_tr_b16 v[118:119], v149 offset:1120
	ds_read_b64_tr_b16 v[194:195], v149 offset:64
	ds_read_b64_tr_b16 v[196:197], v149 offset:1152
	ds_read_b64_tr_b16 v[200:201], v149 offset:96
	ds_read_b64_tr_b16 v[202:203], v149 offset:1184
	ds_read_b64_tr_b16 v[204:205], v149 offset:128
	ds_read_b64_tr_b16 v[206:207], v149 offset:1216
	ds_read_b64_tr_b16 v[208:209], v149 offset:160
	ds_read_b64_tr_b16 v[210:211], v149 offset:1248
	ds_read_b64_tr_b16 v[212:213], v149 offset:192
	ds_read_b64_tr_b16 v[214:215], v149 offset:1280
	ds_read_b64_tr_b16 v[216:217], v149 offset:224
	ds_read_b64_tr_b16 v[218:219], v149 offset:1312
	s_waitcnt lgkmcnt(14)
; #define LAS __attribute__((address_space(3)))
; __device__ __forceinline__ float fexp(float x) { return __builtin_amdgcn_exp2f(1.4426950408889634f * x); }
; #define MMA16(b, a, c) __builtin_amdgcn_mfma_f32_16x16x32_bf16((b), (a), (c), 0, 0, 0)
; __device__ __forceinline__ void ret_out_phase(const Params& p, LAS unsigned char* lds, int G) {
;     ...
;             bf16x8 pa[4];
; #pragma unroll
;             for (int k = 0; k < 4; ++k) pa[k] = LDS16(Pl + il * 136 + 32 * k + 8 * fq);
; #pragma unroll
;             for (int n = 0; n < 8; ++n) o1[n] = (f32x4){0.f, 0.f, 0.f, 0.f};
; #pragma unroll
;             for (int k = 0; k < 4; ++k) {
; #pragma unroll
;                 for (int nh = 0; nh < 2; ++nh) { bf16x8 bf[4];
; #pragma unroll
;                     for (int n = 0; n < 4; ++n) bf[n] = tr_frag(Vl + 32 * k * 136 + trb + 16 * (4 * nh + n), 136);
; #pragma unroll
;                     for (int n = 0; n < 4; ++n) o1[4 * nh + n] = MMA16(bf[n], pa[k], o1[4 * nh + n]); }
;             }
;         }
;         __syncthreads();
; #pragma unroll
;         for (int i = 0; i < 4; ++i) { const int dv = stok + 32 * i; *(LAS u32x4*)(Kl + dv * 136 + sdch * 8) = sfr[i]; *(LAS u32x4*)(Pl + dv * 136 + sdch * 8) = sbr[i]; }
;         __syncthreads();
;         {
;             const float ef = fexp(ldf * (float)(il + 1)), eb = fexp(ldb * (float)(128 - il));
	v_mfma_f32_16x16x32_bf16 v[112:115], v[112:115], v[96:99], 0
	s_waitcnt lgkmcnt(12)
	v_mfma_f32_16x16x32_bf16 v[116:119], v[116:119], v[96:99], 0
	s_waitcnt lgkmcnt(10)
	v_mfma_f32_16x16x32_bf16 v[194:197], v[194:197], v[96:99], 0
	s_waitcnt lgkmcnt(8)
	v_mfma_f32_16x16x32_bf16 v[200:203], v[200:203], v[96:99], 0
	s_waitcnt lgkmcnt(6)
	v_mfma_f32_16x16x32_bf16 v[204:207], v[204:207], v[96:99], 0
	s_waitcnt lgkmcnt(4)
	v_mfma_f32_16x16x32_bf16 v[208:211], v[208:211], v[96:99], 0
	s_waitcnt lgkmcnt(2)
	v_mfma_f32_16x16x32_bf16 v[212:215], v[212:215], v[96:99], 0
	s_waitcnt lgkmcnt(0)
	v_mfma_f32_16x16x32_bf16 v[96:99], v[216:219], v[96:99], 0
	ds_read_b64_tr_b16 v[216:217], v149 offset:8704
	ds_read_b64_tr_b16 v[218:219], v149 offset:9792
	ds_read_b64_tr_b16 v[220:221], v149 offset:8736
	ds_read_b64_tr_b16 v[222:223], v149 offset:9824
	ds_read_b64_tr_b16 v[224:225], v149 offset:8768
	ds_read_b64_tr_b16 v[226:227], v149 offset:9856
	ds_read_b64_tr_b16 v[228:229], v149 offset:8800
	ds_read_b64_tr_b16 v[230:231], v149 offset:9888
	s_waitcnt lgkmcnt(6)
	v_mfma_f32_16x16x32_bf16 v[112:115], v[216:219], v[100:103], v[112:115]
	s_waitcnt lgkmcnt(4)
	v_mfma_f32_16x16x32_bf16 v[116:119], v[220:223], v[100:103], v[116:119]
	s_waitcnt lgkmcnt(2)
	v_mfma_f32_16x16x32_bf16 v[194:197], v[224:227], v[100:103], v[194:197]
	s_waitcnt lgkmcnt(0)
	v_mfma_f32_16x16x32_bf16 v[200:203], v[228:231], v[100:103], v[200:203]
	ds_read_b64_tr_b16 v[216:217], v149 offset:8832
	ds_read_b64_tr_b16 v[218:219], v149 offset:9920
	ds_read_b64_tr_b16 v[220:221], v149 offset:8864
	ds_read_b64_tr_b16 v[222:223], v149 offset:9952
	ds_read_b64_tr_b16 v[224:225], v149 offset:8896
	ds_read_b64_tr_b16 v[226:227], v149 offset:9984
	ds_read_b64_tr_b16 v[228:229], v149 offset:8928
	ds_read_b64_tr_b16 v[230:231], v149 offset:10016
	s_waitcnt lgkmcnt(6)
	v_mfma_f32_16x16x32_bf16 v[204:207], v[216:219], v[100:103], v[204:207]
	s_waitcnt lgkmcnt(4)
	v_mfma_f32_16x16x32_bf16 v[208:211], v[220:223], v[100:103], v[208:211]
	s_waitcnt lgkmcnt(2)
	v_mfma_f32_16x16x32_bf16 v[212:215], v[224:227], v[100:103], v[212:215]
	s_waitcnt lgkmcnt(0)
	v_mfma_f32_16x16x32_bf16 v[96:99], v[228:231], v[100:103], v[96:99]
	ds_read_b64_tr_b16 v[100:101], v149 offset:17408
	ds_read_b64_tr_b16 v[102:103], v149 offset:18496
	ds_read_b64_tr_b16 v[216:217], v149 offset:17440
	ds_read_b64_tr_b16 v[218:219], v149 offset:18528
	ds_read_b64_tr_b16 v[220:221], v149 offset:17472
	ds_read_b64_tr_b16 v[222:223], v149 offset:18560
	ds_read_b64_tr_b16 v[224:225], v149 offset:17504
	ds_read_b64_tr_b16 v[226:227], v149 offset:18592
	s_waitcnt lgkmcnt(6)
	v_mfma_f32_16x16x32_bf16 v[100:103], v[100:103], v[104:107], v[112:115]
	s_waitcnt lgkmcnt(4)
	v_mfma_f32_16x16x32_bf16 v[112:115], v[216:219], v[104:107], v[116:119]
	s_waitcnt lgkmcnt(2)
	v_mfma_f32_16x16x32_bf16 v[116:119], v[220:223], v[104:107], v[194:197]
	s_waitcnt lgkmcnt(0)
	v_mfma_f32_16x16x32_bf16 v[194:197], v[224:227], v[104:107], v[200:203]
	s_nop 2
	ds_read_b64_tr_b16 v[200:201], v149 offset:17536
	ds_read_b64_tr_b16 v[202:203], v149 offset:18624
	ds_read_b64_tr_b16 v[216:217], v149 offset:17568
	ds_read_b64_tr_b16 v[218:219], v149 offset:18656
	ds_read_b64_tr_b16 v[220:221], v149 offset:17600
	ds_read_b64_tr_b16 v[222:223], v149 offset:18688
	ds_read_b64_tr_b16 v[224:225], v149 offset:17632
	ds_read_b64_tr_b16 v[226:227], v149 offset:18720
	s_waitcnt lgkmcnt(6)
	v_mfma_f32_16x16x32_bf16 v[200:203], v[200:203], v[104:107], v[204:207]
	s_waitcnt lgkmcnt(4)
	v_mfma_f32_16x16x32_bf16 v[204:207], v[216:219], v[104:107], v[208:211]
	s_waitcnt lgkmcnt(2)
	v_mfma_f32_16x16x32_bf16 v[208:211], v[220:223], v[104:107], v[212:215]
	s_waitcnt lgkmcnt(0)
	v_mfma_f32_16x16x32_bf16 v[96:99], v[224:227], v[104:107], v[96:99]
	ds_read_b64_tr_b16 v[104:105], v149 offset:26112
	ds_read_b64_tr_b16 v[106:107], v149 offset:27200
	ds_read_b64_tr_b16 v[212:213], v149 offset:26144
	ds_read_b64_tr_b16 v[214:215], v149 offset:27232
	ds_read_b64_tr_b16 v[216:217], v149 offset:26176
	ds_read_b64_tr_b16 v[218:219], v149 offset:27264
	ds_read_b64_tr_b16 v[220:221], v149 offset:26208
	ds_read_b64_tr_b16 v[222:223], v149 offset:27296
	s_waitcnt lgkmcnt(6)
	v_mfma_f32_16x16x32_bf16 v[100:103], v[104:107], v[108:111], v[100:103]
	s_waitcnt lgkmcnt(4)
	v_mfma_f32_16x16x32_bf16 v[104:107], v[212:215], v[108:111], v[112:115]
	s_waitcnt lgkmcnt(2)
	v_mfma_f32_16x16x32_bf16 v[112:115], v[216:219], v[108:111], v[116:119]
	s_waitcnt lgkmcnt(0)
	v_mfma_f32_16x16x32_bf16 v[116:119], v[220:223], v[108:111], v[194:197]
	s_nop 2
	ds_read_b64_tr_b16 v[194:195], v149 offset:26240
	ds_read_b64_tr_b16 v[196:197], v149 offset:27328
	ds_read_b64_tr_b16 v[212:213], v149 offset:26272
	ds_read_b64_tr_b16 v[214:215], v149 offset:27360
	ds_read_b64_tr_b16 v[216:217], v149 offset:26304
	ds_read_b64_tr_b16 v[218:219], v149 offset:27392
	ds_read_b64_tr_b16 v[220:221], v149 offset:26336
	ds_read_b64_tr_b16 v[222:223], v149 offset:27424
	s_waitcnt lgkmcnt(0)
	s_barrier
	s_waitcnt vmcnt(7)
	ds_write_b128 v152, v[64:67] offset:34816
	s_waitcnt vmcnt(6)
	ds_write_b128 v188, v[68:71]
	s_waitcnt vmcnt(5)
	ds_write_b128 v152, v[72:75] offset:43520
	s_waitcnt vmcnt(4)
	ds_write_b128 v188, v[76:79] offset:8704
	s_waitcnt vmcnt(3)
	ds_write_b128 v152, v[80:83] offset:52224
	s_waitcnt vmcnt(2)
	ds_write_b128 v188, v[84:87] offset:17408
	s_waitcnt vmcnt(1)
	ds_write_b128 v152, v[88:91] offset:60928
	s_waitcnt vmcnt(0)
	ds_write_b128 v188, v[92:95] offset:26112
	v_mul_f32_e32 v64, v192, v150
	v_mul_f32_e32 v64, 0x3fb8aa3b, v64
	v_exp_f32_e32 v94, v64
	v_mul_f32_e32 v64, v191, v151
	v_mul_f32_e32 v64, 0x3fb8aa3b, v64
	s_waitcnt lgkmcnt(0)
	s_barrier
; #define LAS __attribute__((address_space(3)))
; __device__ __forceinline__ float fexp(float x) { return __builtin_amdgcn_exp2f(1.4426950408889634f * x); }
; #define MMA16(b, a, c) __builtin_amdgcn_mfma_f32_16x16x32_bf16((b), (a), (c), 0, 0, 0)
; __device__ __forceinline__ void ret_out_phase(const Params& p, LAS unsigned char* lds, int G) {
;     ...
;             const float ef = fexp(ldf * (float)(il + 1)), eb = fexp(ldb * (float)(128 - il));
; #pragma unroll
;             for (int pass = 0; pass < 2; ++pass) {
;                 const LAS bf16_t* St = pass ? Pl : Kl; const float ew = pass ? eb : ef;
; #pragma unroll
;                 for (int nh = 0; nh < 2; ++nh) {
;                     f32x4 a[4];
; #pragma unroll
;                     for (int n = 0; n < 4; ++n) a[n] = (f32x4){0.f, 0.f, 0.f, 0.f};
; #pragma unroll
;                     for (int k = 0; k < 4; ++k) {
;                         bf16x8 bf[4];
; #pragma unroll
;                         for (int n = 0; n < 4; ++n) bf[n] = LDS16(St + (16 * (4 * nh + n) + fr) * 136 + 32 * k + 8 * fq);
; #pragma unroll
;                         for (int n = 0; n < 4; ++n) a[n] = MMA16(bf[n], qa[k], a[n]);
;                     }
; #pragma unroll
;                     for (int n = 0; n < 4; ++n) o1[4 * nh + n] = o1[4 * nh + n] + a[n] * ew;
;                 }
	v_exp_f32_e32 v80, v64
	ds_read_b128 v[64:67], v125 offset:34816
	ds_read_b128 v[68:71], v125 offset:39168
	ds_read_b128 v[72:75], v125 offset:43520
	ds_read_b128 v[76:79], v125 offset:47872
	v_mfma_f32_16x16x32_bf16 v[194:197], v[194:197], v[108:111], v[200:203]
	v_add_u32_e32 v81, v146, v154
	v_mfma_f32_16x16x32_bf16 v[200:203], v[212:215], v[108:111], v[204:207]
	v_mfma_f32_16x16x32_bf16 v[204:207], v[216:219], v[108:111], v[208:211]
	v_mfma_f32_16x16x32_bf16 v[96:99], v[220:223], v[108:111], v[96:99]
	ds_read_b128 v[82:85], v125 offset:34880
	ds_read_b128 v[86:89], v125 offset:39232
	ds_read_b128 v[90:93], v125 offset:43584
	ds_read_b128 v[108:111], v125 offset:47936
	s_waitcnt lgkmcnt(7)
	v_mfma_f32_16x16x32_bf16 v[64:67], v[64:67], v[60:63], 0
	s_waitcnt lgkmcnt(6)
	v_mfma_f32_16x16x32_bf16 v[68:71], v[68:71], v[60:63], 0
	s_waitcnt lgkmcnt(5)
	v_mfma_f32_16x16x32_bf16 v[72:75], v[72:75], v[60:63], 0
	s_waitcnt lgkmcnt(4)
	v_mfma_f32_16x16x32_bf16 v[76:79], v[76:79], v[60:63], 0
	s_waitcnt lgkmcnt(3)
	v_mfma_f32_16x16x32_bf16 v[64:67], v[82:85], v[56:59], v[64:67]
	s_waitcnt lgkmcnt(2)
	v_mfma_f32_16x16x32_bf16 v[68:71], v[86:89], v[56:59], v[68:71]
	s_waitcnt lgkmcnt(1)
	v_mfma_f32_16x16x32_bf16 v[72:75], v[90:93], v[56:59], v[72:75]
	s_waitcnt lgkmcnt(0)
	v_mfma_f32_16x16x32_bf16 v[76:79], v[108:111], v[56:59], v[76:79]
	ds_read_b128 v[82:85], v125 offset:34944
	ds_read_b128 v[86:89], v125 offset:39296
	ds_read_b128 v[90:93], v125 offset:43648
	ds_read_b128 v[108:111], v125 offset:48000
	s_waitcnt lgkmcnt(3)
	v_mfma_f32_16x16x32_bf16 v[64:67], v[82:85], v[52:55], v[64:67]
	s_waitcnt lgkmcnt(2)
	v_mfma_f32_16x16x32_bf16 v[68:71], v[86:89], v[52:55], v[68:71]
	s_waitcnt lgkmcnt(1)
	v_mfma_f32_16x16x32_bf16 v[72:75], v[90:93], v[52:55], v[72:75]
	s_waitcnt lgkmcnt(0)
	v_mfma_f32_16x16x32_bf16 v[76:79], v[108:111], v[52:55], v[76:79]
	ds_read_b128 v[82:85], v125 offset:35008
	ds_read_b128 v[86:89], v125 offset:39360
	ds_read_b128 v[90:93], v125 offset:43712
	ds_read_b128 v[108:111], v125 offset:48064
	s_waitcnt lgkmcnt(3)
	v_mfma_f32_16x16x32_bf16 v[64:67], v[82:85], v[48:51], v[64:67]
	s_waitcnt lgkmcnt(2)
	v_mfma_f32_16x16x32_bf16 v[68:71], v[86:89], v[48:51], v[68:71]
	s_waitcnt lgkmcnt(1)
	v_mfma_f32_16x16x32_bf16 v[72:75], v[90:93], v[48:51], v[72:75]
	s_waitcnt lgkmcnt(0)
	v_mfma_f32_16x16x32_bf16 v[76:79], v[108:111], v[48:51], v[76:79]
	s_nop 1
	v_fma_f32 v108, v94, v66, v102
	v_fma_f32 v109, v94, v67, v103
	v_pk_fma_f32 v[110:111], v[94:95], v[64:65], v[100:101] op_sel_hi:[0,1,1]
	v_pk_fma_f32 v[106:107], v[94:95], v[70:71], v[106:107] op_sel_hi:[0,1,1]
	v_pk_fma_f32 v[104:105], v[94:95], v[68:69], v[104:105] op_sel_hi:[0,1,1]
	v_pk_fma_f32 v[114:115], v[94:95], v[74:75], v[114:115] op_sel_hi:[0,1,1]
	v_pk_fma_f32 v[112:113], v[94:95], v[72:73], v[112:113] op_sel_hi:[0,1,1]
	v_pk_fma_f32 v[118:119], v[94:95], v[78:79], v[118:119] op_sel_hi:[0,1,1]
	v_pk_fma_f32 v[116:117], v[94:95], v[76:77], v[116:117] op_sel_hi:[0,1,1]
	ds_read_b128 v[64:67], v125 offset:52224
	ds_read_b128 v[68:71], v125 offset:56576
	ds_read_b128 v[72:75], v125 offset:60928
	ds_read_b128 v[76:79], v125 offset:65280
	ds_read_b128 v[82:85], v125 offset:52288
	ds_read_b128 v[86:89], v125 offset:56640
	ds_read_b128 v[90:93], v125 offset:60992
	ds_read_b128 v[100:103], v125 offset:65344
	s_waitcnt lgkmcnt(7)
	v_mfma_f32_16x16x32_bf16 v[64:67], v[64:67], v[60:63], 0
	s_waitcnt lgkmcnt(6)
	v_mfma_f32_16x16x32_bf16 v[68:71], v[68:71], v[60:63], 0
	s_waitcnt lgkmcnt(5)
	v_mfma_f32_16x16x32_bf16 v[72:75], v[72:75], v[60:63], 0
	s_waitcnt lgkmcnt(4)
	v_mfma_f32_16x16x32_bf16 v[76:79], v[76:79], v[60:63], 0
	s_waitcnt lgkmcnt(3)
	v_mfma_f32_16x16x32_bf16 v[64:67], v[82:85], v[56:59], v[64:67]
	s_waitcnt lgkmcnt(2)
	v_mfma_f32_16x16x32_bf16 v[68:71], v[86:89], v[56:59], v[68:71]
	s_waitcnt lgkmcnt(1)
	v_mfma_f32_16x16x32_bf16 v[72:75], v[90:93], v[56:59], v[72:75]
	s_waitcnt lgkmcnt(0)
	v_mfma_f32_16x16x32_bf16 v[76:79], v[100:103], v[56:59], v[76:79]
	ds_read_b128 v[82:85], v125 offset:52352
	ds_read_b128 v[86:89], v125 offset:56704
	ds_read_b128 v[90:93], v125 offset:61056
	ds_read_b128 v[100:103], v125 offset:65408
	s_waitcnt lgkmcnt(3)
	v_mfma_f32_16x16x32_bf16 v[64:67], v[82:85], v[52:55], v[64:67]
	s_waitcnt lgkmcnt(2)
	v_mfma_f32_16x16x32_bf16 v[68:71], v[86:89], v[52:55], v[68:71]
	s_waitcnt lgkmcnt(1)
	v_mfma_f32_16x16x32_bf16 v[72:75], v[90:93], v[52:55], v[72:75]
	s_waitcnt lgkmcnt(0)
	v_mfma_f32_16x16x32_bf16 v[76:79], v[100:103], v[52:55], v[76:79]
	ds_read_b128 v[82:85], v125 offset:52416
	ds_read_b128 v[86:89], v125 offset:56768
	ds_read_b128 v[90:93], v125 offset:61120
	ds_read_b128 v[100:103], v125 offset:65472
	s_waitcnt lgkmcnt(3)
	v_mfma_f32_16x16x32_bf16 v[64:67], v[82:85], v[48:51], v[64:67]
	s_waitcnt lgkmcnt(2)
	v_mfma_f32_16x16x32_bf16 v[68:71], v[86:89], v[48:51], v[68:71]
	s_waitcnt lgkmcnt(1)
	v_mfma_f32_16x16x32_bf16 v[72:75], v[90:93], v[48:51], v[72:75]
	s_nop 3
	v_fma_f32 v192, v94, v66, v196
	v_fma_f32 v193, v94, v67, v197
	v_pk_fma_f32 v[194:195], v[94:95], v[64:65], v[194:195] op_sel_hi:[0,1,1]
	v_pk_fma_f32 v[196:197], v[94:95], v[70:71], v[202:203] op_sel_hi:[0,1,1]
	s_waitcnt lgkmcnt(0)
	v_mfma_f32_16x16x32_bf16 v[76:79], v[100:103], v[48:51], v[76:79]
	v_fma_f32 v200, v94, v68, v200
	v_fma_f32 v201, v94, v69, v201
	v_pk_fma_f32 v[202:203], v[94:95], v[74:75], v[206:207] op_sel_hi:[0,1,1]
	v_pk_fma_f32 v[204:205], v[94:95], v[72:73], v[204:205] op_sel_hi:[0,1,1]
	s_nop 3
	v_pk_fma_f32 v[206:207], v[94:95], v[78:79], v[98:99] op_sel_hi:[0,1,1]
	v_pk_fma_f32 v[208:209], v[94:95], v[76:77], v[96:97] op_sel_hi:[0,1,1]
	ds_read_b128 v[64:67], v81
	ds_read_b128 v[68:71], v81 offset:4352
	ds_read_b128 v[72:75], v81 offset:8704
	ds_read_b128 v[76:79], v81 offset:13056
	ds_read_b128 v[82:85], v81 offset:64
	ds_read_b128 v[86:89], v81 offset:4416
	ds_read_b128 v[90:93], v81 offset:8768
	ds_read_b128 v[94:97], v81 offset:13120
	s_waitcnt lgkmcnt(7)
; #define MMA16(b, a, c) __builtin_amdgcn_mfma_f32_16x16x32_bf16((b), (a), (c), 0, 0, 0)
; __device__ __forceinline__ void ret_out_phase(const Params& p, LAS unsigned char* lds, int G) {
;     ...
;                     for (int k = 0; k < 4; ++k) {
;                         bf16x8 bf[4];
; #pragma unroll
;                         for (int n = 0; n < 4; ++n) bf[n] = LDS16(St + (16 * (4 * nh + n) + fr) * 136 + 32 * k + 8 * fq);
; #pragma unroll
;                         for (int n = 0; n < 4; ++n) a[n] = MMA16(bf[n], qa[k], a[n]);
;                     }
; #pragma unroll
;                     for (int n = 0; n < 4; ++n) o1[4 * nh + n] = o1[4 * nh + n] + a[n] * ew;
;                 }
;             }
;         }
;         float sm = 0.f;
; #pragma unroll
;         for (int n = 0; n < 8; ++n) sm += (o1[n][0] + o1[n][1]) + (o1[n][2] + o1[n][3]);
;         sm += __shfl_xor(sm, 16); sm += __shfl_xor(sm, 32);
	v_mfma_f32_16x16x32_bf16 v[64:67], v[64:67], v[60:63], 0
	s_waitcnt lgkmcnt(6)
	v_mfma_f32_16x16x32_bf16 v[68:71], v[68:71], v[60:63], 0
	s_waitcnt lgkmcnt(5)
	v_mfma_f32_16x16x32_bf16 v[72:75], v[72:75], v[60:63], 0
	s_waitcnt lgkmcnt(4)
	v_mfma_f32_16x16x32_bf16 v[76:79], v[76:79], v[60:63], 0
	s_waitcnt lgkmcnt(3)
	v_mfma_f32_16x16x32_bf16 v[64:67], v[82:85], v[56:59], v[64:67]
	s_waitcnt lgkmcnt(2)
	v_mfma_f32_16x16x32_bf16 v[68:71], v[86:89], v[56:59], v[68:71]
	s_waitcnt lgkmcnt(1)
	v_mfma_f32_16x16x32_bf16 v[72:75], v[90:93], v[56:59], v[72:75]
	s_waitcnt lgkmcnt(0)
	v_mfma_f32_16x16x32_bf16 v[76:79], v[94:97], v[56:59], v[76:79]
	ds_read_b128 v[82:85], v81 offset:128
	ds_read_b128 v[86:89], v81 offset:4480
	ds_read_b128 v[90:93], v81 offset:8832
	ds_read_b128 v[94:97], v81 offset:13184
	s_waitcnt lgkmcnt(3)
	v_mfma_f32_16x16x32_bf16 v[64:67], v[82:85], v[52:55], v[64:67]
	s_waitcnt lgkmcnt(2)
	v_mfma_f32_16x16x32_bf16 v[68:71], v[86:89], v[52:55], v[68:71]
	s_waitcnt lgkmcnt(1)
	v_mfma_f32_16x16x32_bf16 v[72:75], v[90:93], v[52:55], v[72:75]
	s_waitcnt lgkmcnt(0)
	v_mfma_f32_16x16x32_bf16 v[76:79], v[94:97], v[52:55], v[76:79]
	ds_read_b128 v[82:85], v81 offset:192
	ds_read_b128 v[86:89], v81 offset:4544
	ds_read_b128 v[90:93], v81 offset:8896
	ds_read_b128 v[94:97], v81 offset:13248
	s_waitcnt lgkmcnt(3)
	v_mfma_f32_16x16x32_bf16 v[64:67], v[82:85], v[48:51], v[64:67]
	s_waitcnt lgkmcnt(2)
	v_mfma_f32_16x16x32_bf16 v[68:71], v[86:89], v[48:51], v[68:71]
	s_waitcnt lgkmcnt(1)
	v_mfma_f32_16x16x32_bf16 v[82:85], v[90:93], v[48:51], v[72:75]
	s_waitcnt lgkmcnt(0)
	v_mfma_f32_16x16x32_bf16 v[86:89], v[94:97], v[48:51], v[76:79]
	s_nop 3
	v_fma_f32 v72, v80, v70, v106
	v_fma_f32 v73, v80, v71, v107
	v_pk_fma_f32 v[74:75], v[80:81], v[68:69], v[104:105] op_sel_hi:[0,1,1]
	v_pk_fma_f32 v[68:69], v[80:81], v[84:85], v[114:115] op_sel_hi:[0,1,1]
	v_pk_fma_f32 v[76:77], v[80:81], v[66:67], v[108:109] op_sel_hi:[0,1,1]
	v_pk_fma_f32 v[78:79], v[80:81], v[64:65], v[110:111] op_sel_hi:[0,1,1]
	v_pk_fma_f32 v[70:71], v[80:81], v[82:83], v[112:113] op_sel_hi:[0,1,1]
	v_pk_fma_f32 v[64:65], v[80:81], v[88:89], v[118:119] op_sel_hi:[0,1,1]
	v_pk_fma_f32 v[66:67], v[80:81], v[86:87], v[116:117] op_sel_hi:[0,1,1]
	ds_read_b128 v[82:85], v81 offset:17408
	ds_read_b128 v[86:89], v81 offset:21760
	ds_read_b128 v[90:93], v81 offset:26112
	ds_read_b128 v[94:97], v81 offset:30464
	s_waitcnt lgkmcnt(3)
	v_mfma_f32_16x16x32_bf16 v[82:85], v[82:85], v[60:63], 0
	s_waitcnt lgkmcnt(2)
	v_mfma_f32_16x16x32_bf16 v[86:89], v[86:89], v[60:63], 0
	s_waitcnt lgkmcnt(1)
	v_mfma_f32_16x16x32_bf16 v[90:93], v[90:93], v[60:63], 0
	s_waitcnt lgkmcnt(0)
	v_mfma_f32_16x16x32_bf16 v[60:63], v[94:97], v[60:63], 0
	ds_read_b128 v[94:97], v81 offset:17472
	ds_read_b128 v[98:101], v81 offset:21824
	ds_read_b128 v[102:105], v81 offset:26176
	ds_read_b128 v[106:109], v81 offset:30528
	s_waitcnt lgkmcnt(3)
	v_mfma_f32_16x16x32_bf16 v[82:85], v[94:97], v[56:59], v[82:85]
	s_waitcnt lgkmcnt(2)
	v_mfma_f32_16x16x32_bf16 v[86:89], v[98:101], v[56:59], v[86:89]
	s_waitcnt lgkmcnt(1)
	v_mfma_f32_16x16x32_bf16 v[90:93], v[102:105], v[56:59], v[90:93]
	s_waitcnt lgkmcnt(0)
	v_mfma_f32_16x16x32_bf16 v[56:59], v[106:109], v[56:59], v[60:63]
	s_nop 2
	ds_read_b128 v[60:63], v81 offset:17536
	ds_read_b128 v[94:97], v81 offset:21888
	ds_read_b128 v[98:101], v81 offset:26240
	ds_read_b128 v[102:105], v81 offset:30592
	s_waitcnt lgkmcnt(3)
	v_mfma_f32_16x16x32_bf16 v[60:63], v[60:63], v[52:55], v[82:85]
	s_waitcnt lgkmcnt(2)
	v_mfma_f32_16x16x32_bf16 v[82:85], v[94:97], v[52:55], v[86:89]
	s_waitcnt lgkmcnt(1)
	v_mfma_f32_16x16x32_bf16 v[86:89], v[98:101], v[52:55], v[90:93]
	s_waitcnt lgkmcnt(0)
	v_mfma_f32_16x16x32_bf16 v[52:55], v[102:105], v[52:55], v[56:59]
	s_nop 2
	ds_read_b128 v[56:59], v81 offset:17600
	ds_read_b128 v[90:93], v81 offset:21952
	ds_read_b128 v[94:97], v81 offset:26304
	ds_read_b128 v[98:101], v81 offset:30656
	s_waitcnt lgkmcnt(3)
	v_mfma_f32_16x16x32_bf16 v[56:59], v[56:59], v[48:51], v[60:63]
	s_waitcnt lgkmcnt(2)
	v_mfma_f32_16x16x32_bf16 v[82:85], v[90:93], v[48:51], v[82:85]
	s_waitcnt lgkmcnt(1)
	v_mfma_f32_16x16x32_bf16 v[86:89], v[94:97], v[48:51], v[86:89]
	s_nop 3
	v_fma_f32 v60, v80, v58, v192
	v_fma_f32 v61, v80, v59, v193
	v_pk_fma_f32 v[62:63], v[80:81], v[56:57], v[194:195] op_sel_hi:[0,1,1]
	v_pk_fma_f32 v[56:57], v[80:81], v[84:85], v[196:197] op_sel_hi:[0,1,1]
	s_waitcnt lgkmcnt(0)
	v_mfma_f32_16x16x32_bf16 v[90:93], v[98:101], v[48:51], v[52:55]
	v_fma_f32 v58, v80, v82, v200
	v_fma_f32 v59, v80, v83, v201
	v_mov_b32_e32 v82, v79
	v_mov_b32_e32 v83, v75
	v_pk_fma_f32 v[52:53], v[80:81], v[88:89], v[202:203] op_sel_hi:[0,1,1]
	v_pk_fma_f32 v[54:55], v[80:81], v[86:87], v[204:205] op_sel_hi:[0,1,1]
	s_nop 1
	v_pk_fma_f32 v[48:49], v[80:81], v[92:93], v[206:207] op_sel_hi:[0,1,1]
	v_pk_fma_f32 v[50:51], v[80:81], v[90:91], v[208:209] op_sel_hi:[0,1,1]
	v_mov_b32_e32 v80, v78
	v_mov_b32_e32 v81, v74
	v_pk_add_f32 v[80:81], v[80:81], v[82:83]
	v_mov_b32_e32 v82, v76
	v_mov_b32_e32 v83, v72
	v_mov_b32_e32 v84, v77
	v_mov_b32_e32 v85, v73
	v_pk_add_f32 v[82:83], v[82:83], v[84:85]
	v_mov_b32_e32 v84, v70
	v_pk_add_f32 v[80:81], v[80:81], v[82:83]
	v_pk_mov_b32 v[82:83], v[70:71], v[68:69] op_sel:[1,0]
	v_mov_b32_e32 v85, v69
	v_pk_add_f32 v[82:83], v[82:83], v[84:85]
	v_add_f32_e32 v80, 0, v80
	v_pk_add_f32 v[82:83], v[82:83], v[82:83] op_sel:[0,1] op_sel_hi:[1,0]
	v_add_f32_e32 v80, v80, v81
	v_add_f32_e32 v84, v66, v67
	v_add_f32_e32 v86, v64, v65
	v_mov_b32_e32 v81, v62
	v_mov_b32_e32 v83, v63
	v_mov_b32_e32 v85, v60
	v_mov_b32_e32 v87, v61
	v_pk_add_f32 v[80:81], v[80:81], v[82:83]
	v_pk_add_f32 v[82:83], v[84:85], v[86:87]
	v_mov_b32_e32 v84, v58
	v_pk_add_f32 v[80:81], v[80:81], v[82:83]
	v_pk_mov_b32 v[82:83], v[58:59], v[56:57] op_sel:[1,0]
	v_mov_b32_e32 v85, v57
	v_pk_add_f32 v[82:83], v[82:83], v[84:85]
	v_pk_add_f32 v[80:81], v[80:81], v[80:81] op_sel:[0,1] op_sel_hi:[1,0]
	v_pk_add_f32 v[82:83], v[82:83], v[82:83] op_sel:[0,1] op_sel_hi:[1,0]
	v_add_f32_e32 v84, v54, v55
	v_add_f32_e32 v86, v52, v53
	v_mov_b32_e32 v81, v50
	v_mov_b32_e32 v83, v51
	v_mov_b32_e32 v85, v48
	v_mov_b32_e32 v87, v49
	v_pk_add_f32 v[80:81], v[80:81], v[82:83]
	v_pk_add_f32 v[82:83], v[84:85], v[86:87]
	s_nop 0
	v_pk_add_f32 v[80:81], v[80:81], v[82:83]
	v_and_b32_e32 v82, 64, v189
	v_add_f32_e32 v80, v80, v81
	v_xor_b32_e32 v81, 16, v189
	v_add_u32_e32 v82, 64, v82
	v_cmp_lt_i32_e32 vcc, v81, v82
	s_nop 1
	v_cndmask_b32_e32 v81, v189, v81, vcc
	v_lshlrev_b32_e32 v88, 2, v81
	ds_bpermute_b32 v81, v88, v80
	s_waitcnt lgkmcnt(0)
; __device__ __forceinline__ unsigned cvt_pk_bf16(float lo, float hi) { unsigned r; asm volatile("v_cvt_pk_bf16_f32 %0, %1, %2" : "=v"(r) : "v"(lo), "v"(hi)); return r; }
; __device__ __forceinline__ unsigned cvt_pk_bf16(float lo, float hi) { f32x2_t v = {lo, hi}; bf16x2_t b = __builtin_convertvector(v, bf16x2_t); return __builtin_bit_cast(unsigned, b); }
; __device__ __forceinline__ float silu_f(float x) { return x * __builtin_amdgcn_rcpf(1.0f + __builtin_amdgcn_exp2f(-1.4426950408889634f * x)); }
; __device__ __forceinline__ void ret_out_phase(const Params& p, LAS unsigned char* lds, int G) {
;     ...
;         sm += __shfl_xor(sm, 16); sm += __shfl_xor(sm, 32);
;         const float mu = sm * (1.0f / 128.0f); float sq = 0.f;
; #pragma unroll
;         for (int n = 0; n < 8; ++n) { o1[n] = o1[n] - mu; sq += (o1[n][0] * o1[n][0] + o1[n][1] * o1[n][1]) + (o1[n][2] * o1[n][2] + o1[n][3] * o1[n][3]); }
;         sq += __shfl_xor(sq, 16); sq += __shfl_xor(sq, 32);
;         const float rs = __builtin_amdgcn_rsqf(sq * (1.0f / 128.0f) + EPS);
;         bf16_t* dst = mix + (size_t)(row0 + il) * D + 512 + h * 128 + 4 * fq;
; #pragma unroll
;         for (int n = 0; n < 8; ++n) { const u32x2 g = gv[n];
;             const float g0 = bf2f((unsigned short)(g.x & 0xffffu)), g1 = bf2f((unsigned short)(g.x >> 16)), g2 = bf2f((unsigned short)(g.y & 0xffffu)), g3 = bf2f((unsigned short)(g.y >> 16));
;             u32x2 w; w.x = cvt_pk_bf16(silu_f(g0) * o1[n][0] * rs, silu_f(g1) * o1[n][1] * rs); w.y = cvt_pk_bf16(silu_f(g2) * o1[n][2] * rs, silu_f(g3) * o1[n][3] * rs);
;             *(u32x2*)(dst + 16 * n) = w; }
	v_add_f32_e32 v80, v80, v81
	v_xor_b32_e32 v81, 32, v189
	v_cmp_lt_i32_e32 vcc, v81, v82
	s_nop 1
	v_cndmask_b32_e32 v81, v189, v81, vcc
	v_lshlrev_b32_e32 v89, 2, v81
	ds_bpermute_b32 v81, v89, v80
	s_waitcnt lgkmcnt(0)
	v_add_f32_e32 v90, v80, v81
	v_fmamk_f32 v79, v90, 0xbc000000, v79
	v_fmamk_f32 v75, v90, 0xbc000000, v75
	v_fmamk_f32 v77, v90, 0xbc000000, v77
	v_fmac_f32_e32 v78, 0xbc000000, v90
	v_fmamk_f32 v73, v90, 0xbc000000, v73
	v_fmac_f32_e32 v74, 0xbc000000, v90
	v_mov_b32_e32 v82, v79
	v_mov_b32_e32 v83, v75
	v_fmac_f32_e32 v76, 0xbc000000, v90
	v_fmac_f32_e32 v72, 0xbc000000, v90
	v_mov_b32_e32 v80, v78
	v_mov_b32_e32 v81, v74
	v_pk_mul_f32 v[82:83], v[82:83], v[82:83]
	v_mov_b32_e32 v84, v77
	v_mov_b32_e32 v85, v73
	v_pk_fma_f32 v[80:81], v[80:81], v[80:81], v[82:83]
	v_mov_b32_e32 v82, v76
	v_mov_b32_e32 v83, v72
	v_pk_mul_f32 v[84:85], v[84:85], v[84:85]
	v_fmamk_f32 v71, v90, 0xbc000000, v71
	v_pk_fma_f32 v[82:83], v[82:83], v[82:83], v[84:85]
	v_fmac_f32_e32 v70, 0xbc000000, v90
	v_pk_add_f32 v[80:81], v[80:81], v[82:83]
	v_fmamk_f32 v69, v90, 0xbc000000, v69
	v_fmac_f32_e32 v68, 0xbc000000, v90
	v_pk_add_f32 v[80:81], v[80:81], v[80:81] op_sel_hi:[0,1]
	v_pk_mul_f32 v[82:83], v[68:69], v[68:69]
	v_pk_mul_f32 v[84:85], v[70:71], v[70:71]
	v_fmac_f32_e32 v66, 0xbc000000, v90
	v_pk_mov_b32 v[86:87], v[84:85], v[82:83] op_sel:[1,0]
	v_mov_b32_e32 v85, v83
	v_fmac_f32_e32 v64, 0xbc000000, v90
	v_fmamk_f32 v67, v90, 0xbc000000, v67
	v_mul_f32_e32 v80, v66, v66
	v_pk_add_f32 v[82:83], v[86:87], v[84:85]
	v_fmamk_f32 v65, v90, 0xbc000000, v65
	v_pk_fma_f32 v[84:85], v[66:67], v[66:67], v[80:81] op_sel_hi:[1,1,0]
	v_mul_f32_e32 v80, v64, v64
	v_pk_add_f32 v[82:83], v[82:83], v[82:83] op_sel_hi:[0,1]
	v_pk_fma_f32 v[86:87], v[64:65], v[64:65], v[80:81] op_sel_hi:[1,1,0]
	v_fmamk_f32 v61, v90, 0xbc000000, v61
	v_fmac_f32_e32 v60, 0xbc000000, v90
	v_fmamk_f32 v63, v90, 0xbc000000, v63
	v_fmac_f32_e32 v62, 0xbc000000, v90
	v_mul_f32_e32 v84, v62, v62
	v_mul_f32_e32 v86, v63, v63
	v_mul_f32_e32 v82, v60, v60
	v_mul_f32_e32 v80, v61, v61
	v_pk_add_f32 v[84:85], v[84:85], v[86:87]
	v_pk_add_f32 v[80:81], v[82:83], v[80:81]
	v_fmamk_f32 v59, v90, 0xbc000000, v59
	v_pk_add_f32 v[80:81], v[84:85], v[80:81]
	v_fmac_f32_e32 v58, 0xbc000000, v90
	v_fmamk_f32 v57, v90, 0xbc000000, v57
	v_fmac_f32_e32 v56, 0xbc000000, v90
	v_pk_add_f32 v[80:81], v[80:81], v[80:81] op_sel_hi:[0,1]
	v_pk_mul_f32 v[82:83], v[56:57], v[56:57]
	v_pk_mul_f32 v[84:85], v[58:59], v[58:59]
	v_fmac_f32_e32 v54, 0xbc000000, v90
	v_pk_mov_b32 v[86:87], v[84:85], v[82:83] op_sel:[1,0]
	v_mov_b32_e32 v85, v83
	v_fmac_f32_e32 v52, 0xbc000000, v90
	v_fmamk_f32 v55, v90, 0xbc000000, v55
	v_mul_f32_e32 v80, v54, v54
	v_pk_add_f32 v[82:83], v[86:87], v[84:85]
	v_fmamk_f32 v53, v90, 0xbc000000, v53
	v_pk_fma_f32 v[84:85], v[54:55], v[54:55], v[80:81] op_sel_hi:[1,1,0]
	v_mul_f32_e32 v80, v52, v52
	v_pk_add_f32 v[82:83], v[82:83], v[82:83] op_sel_hi:[0,1]
	v_pk_fma_f32 v[86:87], v[52:53], v[52:53], v[80:81] op_sel_hi:[1,1,0]
	v_fmamk_f32 v49, v90, 0xbc000000, v49
	v_fmac_f32_e32 v48, 0xbc000000, v90
	v_fmamk_f32 v51, v90, 0xbc000000, v51
	v_fmac_f32_e32 v50, 0xbc000000, v90
	v_mul_f32_e32 v84, v50, v50
	v_mul_f32_e32 v86, v51, v51
	v_mul_f32_e32 v82, v48, v48
	v_mul_f32_e32 v80, v49, v49
	v_pk_add_f32 v[84:85], v[84:85], v[86:87]
	v_pk_add_f32 v[80:81], v[82:83], v[80:81]
	v_lshlrev_b32_e32 v86, 16, v140
	v_pk_add_f32 v[80:81], v[84:85], v[80:81]
	v_and_b32_e32 v87, 0xffff0000, v140
	v_add_f32_e32 v80, v80, v81
	ds_bpermute_b32 v81, v88, v80
	v_lshlrev_b64 v[82:83], 11, v[142:143]
	v_lshl_add_u64 v[82:83], s[68:69], 0, v[82:83]
	v_lshl_add_u64 v[82:83], v[82:83], 0, s[52:53]
	v_lshl_add_u64 v[84:85], v[82:83], 0, v[120:121]
	s_waitcnt lgkmcnt(0)
	v_add_f32_e32 v80, v80, v81
	ds_bpermute_b32 v81, v89, v80
	s_mov_b32 s52, 0x9000000
	v_lshl_add_u64 v[82:83], v[84:85], 0, s[64:65]
	s_waitcnt lgkmcnt(0)
	v_add_f32_e32 v80, v80, v81
	v_mul_f32_e32 v81, 0xbfb8aa3b, v86
	v_exp_f32_e32 v81, v81
	v_fmamk_f32 v80, v80, 0x3c000000, v190
	v_rsq_f32_e32 v80, v80
	v_add_f32_e32 v81, 1.0, v81
	v_rcp_f32_e32 v88, v81
	v_mul_f32_e32 v81, 0xbfb8aa3b, v87
	v_exp_f32_e32 v81, v81
	s_nop 0
	v_add_f32_e32 v81, 1.0, v81
	v_rcp_f32_e32 v89, v81
	s_nop 0
	v_pk_mul_f32 v[86:87], v[88:89], v[86:87]
	s_nop 0
	v_pk_mul_f32 v[78:79], v[86:87], v[78:79]
	v_lshlrev_b32_e32 v86, 16, v141
	v_pk_mul_f32 v[78:79], v[78:79], v[80:81] op_sel_hi:[1,0]
	v_and_b32_e32 v87, 0xffff0000, v141
	v_cvt_pk_bf16_f32 v78, v78, v79
	v_mul_f32_e32 v79, 0xbfb8aa3b, v86
	v_exp_f32_e32 v79, v79
	s_nop 0
	v_add_f32_e32 v79, 1.0, v79
	v_rcp_f32_e32 v88, v79
	v_mul_f32_e32 v79, 0xbfb8aa3b, v87
	v_exp_f32_e32 v79, v79
	s_nop 0
	v_add_f32_e32 v79, 1.0, v79
	v_rcp_f32_e32 v89, v79
	s_nop 0
	v_pk_mul_f32 v[86:87], v[88:89], v[86:87]
	s_nop 0
	v_pk_mul_f32 v[76:77], v[86:87], v[76:77]
	s_nop 0
	v_pk_mul_f32 v[76:77], v[76:77], v[80:81] op_sel_hi:[1,0]
	s_nop 0
	v_cvt_pk_bf16_f32 v79, v76, v77
	v_add_co_u32_e32 v76, vcc, s52, v84
	s_nop 1
	v_addc_co_u32_e32 v77, vcc, 0, v85, vcc
	global_store_dwordx2 v[76:77], v[78:79], off offset:1024
	v_and_b32_e32 v77, 0xffff0000, v138
	v_lshlrev_b32_e32 v76, 16, v138
	v_mul_f32_e32 v78, 0xbfb8aa3b, v76
	v_mul_f32_e32 v79, 0xbfb8aa3b, v77
	v_exp_f32_e32 v78, v78
	v_exp_f32_e32 v79, v79
	s_andn2_b64 vcc, exec, s[56:57]
	v_add_f32_e32 v78, 1.0, v78
	v_add_f32_e32 v79, 1.0, v79
	v_rcp_f32_e32 v78, v78
	v_rcp_f32_e32 v79, v79
	s_nop 0
	v_pk_mul_f32 v[76:77], v[78:79], v[76:77]
	s_nop 0
	v_pk_mul_f32 v[74:75], v[76:77], v[74:75]
	v_lshlrev_b32_e32 v76, 16, v139
	v_pk_mul_f32 v[74:75], v[74:75], v[80:81] op_sel_hi:[1,0]
; __device__ __forceinline__ unsigned cvt_pk_bf16(float lo, float hi) { unsigned r; asm volatile("v_cvt_pk_bf16_f32 %0, %1, %2" : "=v"(r) : "v"(lo), "v"(hi)); return r; }
; __device__ __forceinline__ unsigned cvt_pk_bf16(float lo, float hi) { f32x2_t v = {lo, hi}; bf16x2_t b = __builtin_convertvector(v, bf16x2_t); return __builtin_bit_cast(unsigned, b); }
; __device__ __forceinline__ float silu_f(float x) { return x * __builtin_amdgcn_rcpf(1.0f + __builtin_amdgcn_exp2f(-1.4426950408889634f * x)); }
; __device__ __forceinline__ void ret_out_phase(const Params& p, LAS unsigned char* lds, int G) {
;     ...
;         for (int n = 0; n < 8; ++n) { const u32x2 g = gv[n];
;             const float g0 = bf2f((unsigned short)(g.x & 0xffffu)), g1 = bf2f((unsigned short)(g.x >> 16)), g2 = bf2f((unsigned short)(g.y & 0xffffu)), g3 = bf2f((unsigned short)(g.y >> 16));
;             u32x2 w; w.x = cvt_pk_bf16(silu_f(g0) * o1[n][0] * rs, silu_f(g1) * o1[n][1] * rs); w.y = cvt_pk_bf16(silu_f(g2) * o1[n][2] * rs, silu_f(g3) * o1[n][3] * rs);
;             *(u32x2*)(dst + 16 * n) = w; }
	v_and_b32_e32 v77, 0xffff0000, v139
	v_cvt_pk_bf16_f32 v74, v74, v75
	v_mul_f32_e32 v75, 0xbfb8aa3b, v76
	v_exp_f32_e32 v75, v75
	s_nop 0
	v_add_f32_e32 v75, 1.0, v75
	v_rcp_f32_e32 v78, v75
	v_mul_f32_e32 v75, 0xbfb8aa3b, v77
	v_exp_f32_e32 v75, v75
	s_nop 0
	v_add_f32_e32 v75, 1.0, v75
	v_rcp_f32_e32 v79, v75
	s_nop 0
	v_pk_mul_f32 v[76:77], v[78:79], v[76:77]
	s_nop 0
	v_pk_mul_f32 v[72:73], v[76:77], v[72:73]
	s_nop 0
	v_pk_mul_f32 v[72:73], v[72:73], v[80:81] op_sel_hi:[1,0]
	s_nop 0
	v_cvt_pk_bf16_f32 v75, v72, v73
	v_and_b32_e32 v73, 0xffff0000, v136
	v_lshlrev_b32_e32 v72, 16, v136
	global_store_dwordx2 v[82:83], v[74:75], off offset:32
	v_mul_f32_e32 v74, 0xbfb8aa3b, v72
	v_mul_f32_e32 v75, 0xbfb8aa3b, v73
	v_exp_f32_e32 v74, v74
	v_exp_f32_e32 v75, v75
	v_add_f32_e32 v74, 1.0, v74
	v_add_f32_e32 v75, 1.0, v75
	v_rcp_f32_e32 v74, v74
	v_rcp_f32_e32 v75, v75
	s_nop 0
	v_pk_mul_f32 v[72:73], v[74:75], v[72:73]
	s_nop 0
	v_pk_mul_f32 v[70:71], v[72:73], v[70:71]
	v_lshlrev_b32_e32 v72, 16, v137
	v_pk_mul_f32 v[70:71], v[70:71], v[80:81] op_sel_hi:[1,0]
	v_and_b32_e32 v73, 0xffff0000, v137
	v_cvt_pk_bf16_f32 v70, v70, v71
	v_mul_f32_e32 v71, 0xbfb8aa3b, v72
	v_exp_f32_e32 v71, v71
	s_nop 0
	v_add_f32_e32 v71, 1.0, v71
	v_rcp_f32_e32 v74, v71
	v_mul_f32_e32 v71, 0xbfb8aa3b, v73
	v_exp_f32_e32 v71, v71
	s_nop 0
	v_add_f32_e32 v71, 1.0, v71
	v_rcp_f32_e32 v75, v71
	s_nop 0
	v_pk_mul_f32 v[72:73], v[74:75], v[72:73]
	s_nop 0
	v_pk_mul_f32 v[68:69], v[72:73], v[68:69]
	s_nop 0
	v_pk_mul_f32 v[68:69], v[68:69], v[80:81] op_sel_hi:[1,0]
	s_nop 0
	v_cvt_pk_bf16_f32 v71, v68, v69
	v_and_b32_e32 v69, 0xffff0000, v134
	v_lshlrev_b32_e32 v68, 16, v134
	global_store_dwordx2 v[82:83], v[70:71], off offset:64
	v_mul_f32_e32 v70, 0xbfb8aa3b, v68
	v_mul_f32_e32 v71, 0xbfb8aa3b, v69
	v_exp_f32_e32 v70, v70
	v_exp_f32_e32 v71, v71
	v_add_f32_e32 v70, 1.0, v70
	v_add_f32_e32 v71, 1.0, v71
	v_rcp_f32_e32 v70, v70
	v_rcp_f32_e32 v71, v71
	s_nop 0
	v_pk_mul_f32 v[68:69], v[70:71], v[68:69]
	s_nop 0
	v_pk_mul_f32 v[66:67], v[68:69], v[66:67]
	v_lshlrev_b32_e32 v68, 16, v135
	v_pk_mul_f32 v[66:67], v[66:67], v[80:81] op_sel_hi:[1,0]
	v_and_b32_e32 v69, 0xffff0000, v135
	v_cvt_pk_bf16_f32 v66, v66, v67
	v_mul_f32_e32 v67, 0xbfb8aa3b, v68
	v_exp_f32_e32 v67, v67
	s_nop 0
	v_add_f32_e32 v67, 1.0, v67
	v_rcp_f32_e32 v70, v67
	v_mul_f32_e32 v67, 0xbfb8aa3b, v69
	v_exp_f32_e32 v67, v67
	s_nop 0
	v_add_f32_e32 v67, 1.0, v67
	v_rcp_f32_e32 v71, v67
	s_nop 0
	v_pk_mul_f32 v[68:69], v[70:71], v[68:69]
	s_nop 0
	v_pk_mul_f32 v[64:65], v[68:69], v[64:65]
	s_nop 0
	v_pk_mul_f32 v[64:65], v[64:65], v[80:81] op_sel_hi:[1,0]
	s_nop 0
	v_cvt_pk_bf16_f32 v67, v64, v65
	v_and_b32_e32 v65, 0xffff0000, v132
	v_lshlrev_b32_e32 v64, 16, v132
	global_store_dwordx2 v[82:83], v[66:67], off offset:96
	v_mul_f32_e32 v66, 0xbfb8aa3b, v64
	v_mul_f32_e32 v67, 0xbfb8aa3b, v65
	v_exp_f32_e32 v66, v66
	v_exp_f32_e32 v67, v67
	v_add_f32_e32 v66, 1.0, v66
	v_add_f32_e32 v67, 1.0, v67
	v_rcp_f32_e32 v66, v66
	v_rcp_f32_e32 v67, v67
	s_nop 0
	v_pk_mul_f32 v[64:65], v[66:67], v[64:65]
	s_nop 0
	v_pk_mul_f32 v[62:63], v[64:65], v[62:63]
	v_lshlrev_b32_e32 v64, 16, v133
	v_pk_mul_f32 v[62:63], v[62:63], v[80:81] op_sel_hi:[1,0]
	v_and_b32_e32 v65, 0xffff0000, v133
	v_cvt_pk_bf16_f32 v62, v62, v63
	v_mul_f32_e32 v63, 0xbfb8aa3b, v64
	v_exp_f32_e32 v63, v63
	s_nop 0
	v_add_f32_e32 v63, 1.0, v63
	v_rcp_f32_e32 v66, v63
	v_mul_f32_e32 v63, 0xbfb8aa3b, v65
	v_exp_f32_e32 v63, v63
	s_nop 0
	v_add_f32_e32 v63, 1.0, v63
	v_rcp_f32_e32 v67, v63
	s_nop 0
	v_pk_mul_f32 v[64:65], v[66:67], v[64:65]
	s_nop 0
	v_pk_mul_f32 v[60:61], v[64:65], v[60:61]
	s_nop 0
	v_pk_mul_f32 v[60:61], v[60:61], v[80:81] op_sel_hi:[1,0]
	s_nop 0
	v_cvt_pk_bf16_f32 v63, v60, v61
	v_and_b32_e32 v61, 0xffff0000, v130
	v_lshlrev_b32_e32 v60, 16, v130
	global_store_dwordx2 v[82:83], v[62:63], off offset:128
	v_mul_f32_e32 v62, 0xbfb8aa3b, v60
	v_mul_f32_e32 v63, 0xbfb8aa3b, v61
	v_exp_f32_e32 v62, v62
	v_exp_f32_e32 v63, v63
	v_add_f32_e32 v62, 1.0, v62
	v_add_f32_e32 v63, 1.0, v63
	v_rcp_f32_e32 v62, v62
	v_rcp_f32_e32 v63, v63
	s_nop 0
; __device__ __forceinline__ unsigned cvt_pk_bf16(float lo, float hi) { unsigned r; asm volatile("v_cvt_pk_bf16_f32 %0, %1, %2" : "=v"(r) : "v"(lo), "v"(hi)); return r; }
; #define LAS __attribute__((address_space(3)))
; __device__ __forceinline__ unsigned cvt_pk_bf16(float lo, float hi) { f32x2_t v = {lo, hi}; bf16x2_t b = __builtin_convertvector(v, bf16x2_t); return __builtin_bit_cast(unsigned, b); }
; __device__ __forceinline__ float silu_f(float x) { return x * __builtin_amdgcn_rcpf(1.0f + __builtin_amdgcn_exp2f(-1.4426950408889634f * x)); }
; #define R3_ISSUE(u_) do { const bf16_t* src_ = proj + (size_t)(((u_) >> 2) * 128 + stok) * DIN + 768 + ((u_) & 3) * 128 + sdch * 8; \
;         _Pragma("unroll") for (int i_ = 0; i_ < 4; ++i_) { pq[i_] = *(const u32x4*)(src_ + (size_t)i_ * 32 * DIN); pk[i_] = *(const u32x4*)(src_ + 512 + (size_t)i_ * 32 * DIN); pv[i_] = *(const u32x4*)(src_ + 1024 + (size_t)i_ * 32 * DIN); } } while (0)
; __device__ __forceinline__ void ret_out_phase(const Params& p, LAS unsigned char* lds, int G) {
;     ...
;     for (; unit < (T / 128) * 4; unit += G) {
;         const int c = unit >> 2, h = unit & 3, row0 = c * 128;
;         const float ldf = p.in[10][h], ldb = p.in[11][h]; const float ldf2 = ldf * 1.4426950408889634f, ldb2 = ldb * 1.4426950408889634f;
;         __syncthreads();
; #pragma unroll
;         for (int i = 0; i < 4; ++i) {
;             const int tok = stok + 32 * i;
;             *(LAS u32x4*)(Ql + tok * 136 + sdch * 8) = pq[i]; *(LAS u32x4*)(Kl + tok * 136 + sdch * 8) = pk[i]; *(LAS u32x4*)(Vl + tok * 136 + sdch * 8) = pv[i];
;         }
;         __syncthreads();
;         if (unit + G < (T / 128) * 4) R3_ISSUE(unit + G);
;     ...
;         for (int n = 0; n < 8; ++n) { const u32x2 g = gv[n];
;             const float g0 = bf2f((unsigned short)(g.x & 0xffffu)), g1 = bf2f((unsigned short)(g.x >> 16)), g2 = bf2f((unsigned short)(g.y & 0xffffu)), g3 = bf2f((unsigned short)(g.y >> 16));
;             u32x2 w; w.x = cvt_pk_bf16(silu_f(g0) * o1[n][0] * rs, silu_f(g1) * o1[n][1] * rs); w.y = cvt_pk_bf16(silu_f(g2) * o1[n][2] * rs, silu_f(g3) * o1[n][3] * rs);
;             *(u32x2*)(dst + 16 * n) = w; }
	v_pk_mul_f32 v[60:61], v[62:63], v[60:61]
	s_nop 0
	v_pk_mul_f32 v[58:59], v[60:61], v[58:59]
	v_lshlrev_b32_e32 v60, 16, v131
	v_pk_mul_f32 v[58:59], v[58:59], v[80:81] op_sel_hi:[1,0]
	v_and_b32_e32 v61, 0xffff0000, v131
	v_cvt_pk_bf16_f32 v58, v58, v59
	v_mul_f32_e32 v59, 0xbfb8aa3b, v60
	v_exp_f32_e32 v59, v59
	s_nop 0
	v_add_f32_e32 v59, 1.0, v59
	v_rcp_f32_e32 v62, v59
	v_mul_f32_e32 v59, 0xbfb8aa3b, v61
	v_exp_f32_e32 v59, v59
	s_nop 0
	v_add_f32_e32 v59, 1.0, v59
	v_rcp_f32_e32 v63, v59
	s_nop 0
	v_pk_mul_f32 v[60:61], v[62:63], v[60:61]
	s_nop 0
	v_pk_mul_f32 v[56:57], v[60:61], v[56:57]
	s_nop 0
	v_pk_mul_f32 v[56:57], v[56:57], v[80:81] op_sel_hi:[1,0]
	s_nop 0
	v_cvt_pk_bf16_f32 v59, v56, v57
	v_and_b32_e32 v57, 0xffff0000, v128
	v_lshlrev_b32_e32 v56, 16, v128
	global_store_dwordx2 v[82:83], v[58:59], off offset:160
	v_mul_f32_e32 v58, 0xbfb8aa3b, v56
	v_mul_f32_e32 v59, 0xbfb8aa3b, v57
	v_exp_f32_e32 v58, v58
	v_exp_f32_e32 v59, v59
	v_add_f32_e32 v58, 1.0, v58
	v_add_f32_e32 v59, 1.0, v59
	v_rcp_f32_e32 v58, v58
	v_rcp_f32_e32 v59, v59
	s_nop 0
	v_pk_mul_f32 v[56:57], v[58:59], v[56:57]
	s_nop 0
	v_pk_mul_f32 v[54:55], v[56:57], v[54:55]
	v_lshlrev_b32_e32 v56, 16, v129
	v_pk_mul_f32 v[54:55], v[54:55], v[80:81] op_sel_hi:[1,0]
	v_and_b32_e32 v57, 0xffff0000, v129
	v_cvt_pk_bf16_f32 v54, v54, v55
	v_mul_f32_e32 v55, 0xbfb8aa3b, v56
	v_exp_f32_e32 v55, v55
	s_nop 0
	v_add_f32_e32 v55, 1.0, v55
	v_rcp_f32_e32 v58, v55
	v_mul_f32_e32 v55, 0xbfb8aa3b, v57
	v_exp_f32_e32 v55, v55
	s_nop 0
	v_add_f32_e32 v55, 1.0, v55
	v_rcp_f32_e32 v59, v55
	s_nop 0
	v_pk_mul_f32 v[56:57], v[58:59], v[56:57]
	s_nop 0
	v_pk_mul_f32 v[52:53], v[56:57], v[52:53]
	s_nop 0
	v_pk_mul_f32 v[52:53], v[52:53], v[80:81] op_sel_hi:[1,0]
	s_nop 0
	v_cvt_pk_bf16_f32 v55, v52, v53
	v_and_b32_e32 v53, 0xffff0000, v126
	v_lshlrev_b32_e32 v52, 16, v126
	global_store_dwordx2 v[82:83], v[54:55], off offset:192
	v_mul_f32_e32 v54, 0xbfb8aa3b, v52
	v_mul_f32_e32 v55, 0xbfb8aa3b, v53
	v_exp_f32_e32 v54, v54
	v_exp_f32_e32 v55, v55
	v_add_f32_e32 v54, 1.0, v54
	v_add_f32_e32 v55, 1.0, v55
	v_rcp_f32_e32 v54, v54
	v_rcp_f32_e32 v55, v55
	s_nop 0
	v_pk_mul_f32 v[52:53], v[54:55], v[52:53]
	s_nop 0
	v_pk_mul_f32 v[50:51], v[52:53], v[50:51]
	v_lshlrev_b32_e32 v52, 16, v127
	v_pk_mul_f32 v[50:51], v[50:51], v[80:81] op_sel_hi:[1,0]
	v_and_b32_e32 v53, 0xffff0000, v127
	v_cvt_pk_bf16_f32 v50, v50, v51
	v_mul_f32_e32 v51, 0xbfb8aa3b, v52
	v_exp_f32_e32 v51, v51
	s_nop 0
	v_add_f32_e32 v51, 1.0, v51
	v_rcp_f32_e32 v54, v51
	v_mul_f32_e32 v51, 0xbfb8aa3b, v53
	v_exp_f32_e32 v51, v51
	s_nop 0
	v_add_f32_e32 v51, 1.0, v51
	v_rcp_f32_e32 v55, v51
	s_nop 0
	v_pk_mul_f32 v[52:53], v[54:55], v[52:53]
	s_nop 0
	v_pk_mul_f32 v[48:49], v[52:53], v[48:49]
	s_nop 0
	v_pk_mul_f32 v[48:49], v[48:49], v[80:81] op_sel_hi:[1,0]
	s_nop 0
	v_cvt_pk_bf16_f32 v51, v48, v49
	global_store_dwordx2 v[82:83], v[50:51], off offset:224
	s_cbranch_vccz .LBB0_702
.LBB0_698:
	s_and_b32 s64, s61, 3
	s_lshl_b32 s52, s64, 2
	v_mov_b32_e32 v48, s52
	global_load_dword v192, v48, s[40:41]
	global_load_dword v191, v48, s[42:43]
	s_barrier
	s_waitcnt vmcnt(13)
	ds_write_b128 v152, v[0:3]
	s_waitcnt vmcnt(12)
	ds_write_b128 v152, v[4:7] offset:34816
	s_waitcnt vmcnt(11)
	ds_write_b128 v153, v[8:11]
	s_waitcnt vmcnt(10)
	ds_write_b128 v152, v[12:15] offset:8704
	s_waitcnt vmcnt(9)
	ds_write_b128 v152, v[16:19] offset:43520
	s_waitcnt vmcnt(8)
	ds_write_b128 v153, v[20:23] offset:8704
	s_waitcnt vmcnt(7)
	ds_write_b128 v152, v[24:27] offset:17408
	s_waitcnt vmcnt(6)
	ds_write_b128 v152, v[28:31] offset:52224
	s_waitcnt vmcnt(5)
	ds_write_b128 v153, v[32:35] offset:17408
	s_waitcnt vmcnt(4)
	ds_write_b128 v152, v[36:39] offset:26112
	s_waitcnt vmcnt(3)
	ds_write_b128 v152, v[40:43] offset:60928
	s_waitcnt vmcnt(0)
	ds_write_b128 v153, v[44:47] offset:26112
	s_waitcnt lgkmcnt(0)
	s_barrier
	s_load_dwordx2 s[56:57], s[88:89], 0xa8
	s_mov_b64 vcc, -1
	s_waitcnt lgkmcnt(0)
	s_add_i32 s61, s61, s56
	s_cmpk_gt_i32 s61, 0x5ff
	s_cselect_b64 s[56:57], -1, 0
	s_cmpk_lt_i32 s61, 0x600
	s_cbranch_scc1 .LBB0_700
	s_add_i32 s62, s63, s58
	s_mov_b64 vcc, 0

; #define PG8_WAIT_V(n) asm volatile("s_waitcnt vmcnt(" #n ")" ::: "memory")
; template <class Epi, class Sched, bool ALIGN_EPI = false, bool SP2 = false>
; __device__ __forceinline__ void gemm_phase(PG8_LAS unsigned char* lds, const Gemm g, const Sched& S, const Epi& E) {
;     const int tid = threadIdx.x, wid = __builtin_amdgcn_readfirstlane(tid >> 6), lane = tid & 63, wr = wid >> 2, wc = wid & 3, fr = lane & 15, fq = lane >> 4;
;     const int K = g.K, nt = K / BK;
;     unsigned voffA[2], voffB[2];
; #pragma unroll
;     for (int i = 0; i < 2; ++i) { int R, C; stage_rc(tid * 16 + i * 8192, R, C); const int Rb = Epi::PERM ? ((R & ~31) + perm32(R & 31)) : R;
;         voffA[i] = (unsigned)(R * K + C) * 2u; voffB[i] = (unsigned)(Rb * K + C) * 2u; }
;     const size_t kstep = (size_t)(BK * 2);
;     const size_t hstep = (size_t)HALF * K * 2;
;     const size_t tstep = 2 * hstep;
;     const unsigned ldsw = (unsigned)wid * 1024u;
;     const int aoff = lds_byte(wr * 64 + fr, fq * 8), boff = lds_byte(wc * 32 + fr, fq * 8);
;     ...
;     Unit cur, nxt; int ui = 0;
;     if (!S.next(0, cur)) return;
;     f32x4 acc[2][2][4][2];
; #pragma unroll
;     for (int a = 0; a < 2; ++a)
; #pragma unroll
;         for (int b = 0; b < 2; ++b)
; #pragma unroll
;             for (int m = 0; m < 4; ++m)
; #pragma unroll
;                 for (int n = 0; n < 2; ++n) acc[a][b][m][n] = (f32x4){0.f, 0.f, 0.f, 0.f};
;     bf16x8 At[4][2], B0[2][2], B1[2][2];
;     const char* cA = (const char*)g.A + (size_t)cur.pm * tstep; const char* cB = (const char*)g.Bt + (size_t)cur.pn * tstep;
;     S.a_ready(cur);
;     if constexpr (SP2) {
;         PG8_STAGE(PG8_SB(0, 0), cB, voffB); PG8_STAGE(PG8_SB(0, 1), cB + hstep, voffB); PG8_STAGE(PG8_SA(0, 0), cA, voffA); PG8_STAGE(PG8_SA(0, 1), cA + hstep, voffA);
;         if (wr == 1) PG8_BAR;
;         PG8_WAIT_V(2); PG8_BAR;
;         PG8_STAGE(PG8_SB(1, 0), cB + kstep, voffB); PG8_STAGE(PG8_SA(1, 0), cA + kstep, voffA); PG8_STAGE(PG8_SB(1, 1), cB + hstep + kstep, voffB);
;         PG8_WAIT_V(6); PG8_BAR;
; __global__ void __launch_bounds__(NTHR, 2) mk_fwd(Params p) {
;     ...
;         pg8::Gemm g{ACTA, (const bf16_t*)(p.ws + WS_WGU2), T, 2 * FF, D}; pg8::StaticOrder S; S.init(T, 2 * FF, G, vc);
;         EpiSwiGLU<true> E{HID, SSQ};
;         pg8::gemm_phase<EpiSwiGLU<true>, pg8::StaticOrder, PG8_ALIGN, PG8_SP2>(lds, g, S, E);
.LBB0_846:
	v_readlane_b32 s2, v247, 4
	v_readlane_b32 s3, v247, 5
	s_cmp_lt_i32 s2, 9
	s_cselect_b64 s[2:3], -1, 0
	s_and_b64 s[2:3], s[2:3], s[0:1]
	s_andn2_b64 vcc, exec, s[2:3]
	s_cbranch_vccnz .LBB0_863
	s_mov_b32 s98, -1
	s_cmpk_gt_i32 s33, 0x107f
	v_readfirstlane_b32 s1, v198
	s_cbranch_scc1 .LBB0_863
	s_waitcnt vmcnt(0)
	v_lshrrev_b32_e32 v0, 5, v198
	v_lshrrev_b32_e32 v2, 1, v198
	v_and_b32_e32 v0, 4, v0
	s_waitcnt lgkmcnt(0)
	v_bfe_u32 v1, v198, 2, 2
	v_and_b32_e32 v2, 24, v2
	v_or3_b32 v0, v0, v1, v2
	v_lshlrev_b32_e32 v1, 4, v198
	v_add_u32_e32 v8, 0x2000, v1
	v_lshrrev_b32_e32 v2, 7, v8
	s_movk_i32 s0, 0xe0
	v_and_b32_e32 v4, 32, v198
	v_and_or_b32 v3, v2, s0, v0
	v_bitop3_b32 v9, v1, v4, 48 bitop3:0x6c
	v_and_b32_e32 v10, 64, v198
	v_bfe_u32 v11, v198, 2, 4
	s_movk_i32 s0, 0xf0
	v_or_b32_e32 v1, v9, v10
	v_and_or_b32 v2, v2, s0, v11
	s_add_u32 s26, s92, 0x1800000
	v_lshl_or_b32 v130, v2, 11, v1
	v_lshrrev_b32_e32 v2, 3, v198
	s_movk_i32 s0, 0x60
	s_addc_u32 s27, s93, 0
	v_and_or_b32 v0, v2, s0, v0
	s_movk_i32 s0, 0x70
	s_ashr_i32 s29, s33, 31
	v_lshl_or_b32 v132, v0, 11, v1
	v_and_or_b32 v0, v2, s0, v11
	s_lshr_b32 s0, s29, 29
	s_add_i32 s0, s33, s0
	s_lshr_b32 s6, s1, 6
	s_ashr_i32 s4, s0, 3
	s_and_b32 s0, s0, -8
	s_lshr_b32 s8, s1, 8
	s_lshl_b32 s28, s6, 10
	s_sub_i32 s0, s33, s0
	s_cmp_lt_i32 s0, 0
	s_movk_i32 s30, 0x211
	s_cselect_b32 s5, s30, 0x210
	s_mul_i32 s0, s0, s5
	s_add_i32 s0, s0, s4
	s_mul_hi_i32 s4, s0, 0x2e8ba2e9
	s_lshr_b32 s5, s4, 31
	s_ashr_i32 s4, s4, 5
	s_add_i32 s4, s4, s5
	s_lshl_b32 s5, s4, 3
	s_mulk_i32 s4, 0xb0
	s_sub_i32 s4, s0, s4
	s_bfe_u32 s0, s4, 0x3001c
	s_add_i32 s7, s4, s0
	s_sext_i32_i16 s0, s7
	s_and_b32 s7, s7, 0xfff8
	s_sub_i32 s4, s4, s7
	s_sext_i32_i16 s4, s4
	s_lshr_b32 s0, s0, 3
	s_add_i32 s18, s5, s4
	s_ashr_i32 s19, s18, 31
	s_bfe_i64 s[10:11], s[0:1], 0x100000
	s_lshl_b64 s[4:5], s[18:19], 19
	s_lshl_b64 s[10:11], s[10:11], 19
	s_add_u32 s22, s26, s10
	s_addc_u32 s23, s27, s11
	s_add_i32 s19, s28, 0
	s_add_i32 m0, s19, 0x10000
	v_lshl_or_b32 v128, v3, 11, v1
	global_load_lds_dwordx4 v132, s[22:23]
	s_add_i32 m0, s19, 0x12000
	s_add_u32 s10, s22, 0x40000
	global_load_lds_dwordx4 v128, s[22:23]
	s_addc_u32 s11, s23, 0
	s_add_i32 m0, s19, 0x14000
	v_lshl_or_b32 v134, v0, 11, v1
	global_load_lds_dwordx4 v132, s[10:11]
	s_add_i32 m0, s19, 0x16000
	s_add_u32 s20, s44, s4
	s_addc_u32 s21, s45, s5
	s_add_i32 s31, s19, 0x2000
	global_load_lds_dwordx4 v128, s[10:11]
	s_mov_b32 m0, s19
	s_add_u32 s4, s20, 0x40000
	global_load_lds_dwordx4 v134, s[20:21]
	s_mov_b32 m0, s31
	s_addc_u32 s5, s21, 0
	s_add_i32 s34, s19, 0x4000
	global_load_lds_dwordx4 v130, s[20:21]
	s_mov_b32 m0, s34
	s_add_i32 s35, s19, 0x6000
	global_load_lds_dwordx4 v134, s[4:5]
	s_mov_b32 m0, s35
	v_mov_b32_e32 v133, 0
	global_load_lds_dwordx4 v130, s[4:5]
	v_mov_b32_e32 v129, v133
	v_mov_b32_e32 v135, v133
	v_mov_b32_e32 v131, v133
	s_cmp_eq_u32 s8, 1
	s_mov_b32 s36, 0
	v_lshl_add_u64 v[6:7], s[22:23], 0, v[132:133]
	v_lshl_add_u64 v[4:5], s[22:23], 0, v[128:129]
	v_lshl_add_u64 v[0:1], s[20:21], 0, v[134:135]
	s_cselect_b64 s[4:5], -1, 0
	s_cmp_lg_u32 s8, 1
	v_lshl_add_u64 v[2:3], s[20:21], 0, v[130:131]
	s_cbranch_scc1 .LBB0_850
	s_barrier

; __device__ __forceinline__ void row_rstd8(const float* ssq, int row0, int fq, float (&r)[8]) {
;     f32x4 pp[8];
; #pragma unroll
;     for (int q = 0; q < 8; ++q) pp[q] = *(const f32x4*)(ssq + (size_t)(row0 + (q >> 2) * 128 + (q & 3) * 16) * 16 + 4 * fq);
; #pragma unroll
;     for (int q = 0; q < 8; ++q) { float s = (pp[q][0] + pp[q][1]) + (pp[q][2] + pp[q][3]); s += __shfl_xor(s, 16); s += __shfl_xor(s, 32); r[q] = __builtin_amdgcn_rsqf(s * (1.0f / 1024.0f) + EPS); }
; }
;     __device__ __forceinline__ void operator()(const f32x4 (&acc)[2][2][4][2], const pg8::Unit& u, int wr, int wc, int fr, int fq) const {
;         const int row0 = u.pm * 256 + wr * 64 + fr, col0 = u.pn * 128 + wc * 32 + 8 * fq;
;         float rr[8]; if (SCALE) row_rstd8(ssq, row0, fq, rr);
; #pragma unroll
;         for (int ai = 0; ai < 2; ++ai)
; #pragma unroll
;             for (int m = 0; m < 4; ++m) {
;                 const int row = row0 + ai * 128 + m * 16;
;                 float r = 1.f; if (SCALE) r = rr[ai * 4 + m];
;                 const f32x4 g0 = acc[ai][0][m][0] * r, g1 = acc[ai][0][m][1] * r, u0 = acc[ai][1][m][0] * r, u1 = acc[ai][1][m][1] * r;
.LBB0_859:
	s_cmp_eq_u32 s18, s98
	s_cbranch_scc1 .Lg8_hit
	s_mov_b32 s98, s18
	v_lshl_add_u32 v168, s18, 8, v155
	v_ashrrev_i32_e32 v169, 31, v168
	v_or_b32_e32 v164, 16, v168
	v_lshlrev_b64 v[146:147], 6, v[168:169]
	v_ashrrev_i32_e32 v165, 31, v164
	v_or_b32_e32 v160, 32, v168
	v_lshl_add_u64 v[146:147], v[136:137], 0, v[146:147]
	v_lshlrev_b64 v[148:149], 6, v[164:165]
	v_ashrrev_i32_e32 v161, 31, v160
	v_or_b32_e32 v156, 48, v168
	v_lshl_add_u64 v[148:149], v[136:137], 0, v[148:149]
	global_load_dwordx4 v[178:181], v[146:147], off
	global_load_dwordx4 v[182:185], v[148:149], off
	v_lshlrev_b64 v[146:147], 6, v[160:161]
	v_ashrrev_i32_e32 v157, 31, v156
	v_add_u32_e32 v152, 0x80, v168
	v_lshl_add_u64 v[146:147], v[136:137], 0, v[146:147]
	v_lshlrev_b64 v[148:149], 6, v[156:157]
	v_ashrrev_i32_e32 v153, 31, v152
	v_lshl_add_u64 v[148:149], v[136:137], 0, v[148:149]
	global_load_dwordx4 v[186:189], v[146:147], off
	global_load_dwordx4 v[190:193], v[148:149], off
	v_lshlrev_b64 v[146:147], 6, v[152:153]
	v_lshl_add_u64 v[146:147], v[136:137], 0, v[146:147]
	global_load_dwordx4 v[194:197], v[146:147], off
	v_add_u32_e32 v150, 0x90, v168
	v_ashrrev_i32_e32 v151, 31, v150
	v_lshlrev_b64 v[146:147], 6, v[150:151]
	v_add_u32_e32 v148, 0xa0, v168
	v_lshl_add_u64 v[146:147], v[136:137], 0, v[146:147]
	v_ashrrev_i32_e32 v149, 31, v148
	global_load_dwordx4 v[200:203], v[146:147], off
	v_lshlrev_b64 v[146:147], 6, v[148:149]
	v_lshl_add_u64 v[146:147], v[136:137], 0, v[146:147]
	global_load_dwordx4 v[204:207], v[146:147], off
	v_add_u32_e32 v146, 0xb0, v168
	v_ashrrev_i32_e32 v147, 31, v146
	v_lshlrev_b64 v[208:209], 6, v[146:147]
	v_lshl_add_u64 v[208:209], v[136:137], 0, v[208:209]
	global_load_dwordx4 v[208:211], v[208:209], off
	v_and_b32_e32 v149, 64, v175
	v_xor_b32_e32 v147, 16, v175
	v_add_u32_e32 v149, 64, v149
	v_xor_b32_e32 v151, 32, v175
	v_cmp_lt_i32_e32 vcc, v147, v149
	v_lshl_or_b32 v172, s50, 7, v163
	v_ashrrev_i32_e32 v173, 31, v172
	v_cndmask_b32_e32 v147, v175, v147, vcc
	v_cmp_lt_i32_e32 vcc, v151, v149
	v_lshlrev_b32_e32 v147, 2, v147
	s_waitcnt vmcnt(0)
	v_mov_b32_e32 v212, v179
	v_mov_b32_e32 v213, v180
	v_mov_b32_e32 v179, v181
	v_pk_add_f32 v[178:179], v[212:213], v[178:179]
	v_mov_b32_e32 v180, v183
	v_mov_b32_e32 v181, v184
	v_mov_b32_e32 v183, v185
	v_cndmask_b32_e32 v149, v175, v151, vcc
	v_mov_b32_e32 v184, v187
	v_mov_b32_e32 v185, v188
	v_mov_b32_e32 v187, v189
	v_add_f32_e32 v151, v178, v179
	v_pk_add_f32 v[178:179], v[180:181], v[182:183]
	v_mov_b32_e32 v188, v191
	v_mov_b32_e32 v189, v192
	v_mov_b32_e32 v191, v193
	v_pk_add_f32 v[180:181], v[184:185], v[186:187]
	ds_bpermute_b32 v153, v147, v151
	v_add_f32_e32 v154, v178, v179
	v_pk_add_f32 v[182:183], v[188:189], v[190:191]
	v_add_f32_e32 v157, v180, v181
	ds_bpermute_b32 v162, v147, v154
	v_mov_b32_e32 v192, v195
	v_mov_b32_e32 v193, v196
	v_mov_b32_e32 v195, v197
	v_add_f32_e32 v158, v182, v183
	ds_bpermute_b32 v165, v147, v157
	v_pk_add_f32 v[184:185], v[192:193], v[194:195]
	ds_bpermute_b32 v166, v147, v158
	v_add_f32_e32 v161, v184, v185
	v_lshlrev_b32_e32 v149, 2, v149
	ds_bpermute_b32 v169, v147, v161
	s_waitcnt lgkmcnt(4)
	v_add_f32_e32 v151, v151, v153
	ds_bpermute_b32 v153, v149, v151
	s_waitcnt lgkmcnt(4)
	v_add_f32_e32 v154, v154, v162
	s_waitcnt lgkmcnt(3)
	v_add_f32_e32 v157, v157, v165
	ds_bpermute_b32 v162, v149, v154
	s_waitcnt lgkmcnt(3)
	v_add_f32_e32 v158, v158, v166
	ds_bpermute_b32 v165, v149, v157
	ds_bpermute_b32 v166, v149, v158
	s_waitcnt lgkmcnt(4)
	v_add_f32_e32 v161, v161, v169
	ds_bpermute_b32 v169, v149, v161
	s_waitcnt lgkmcnt(4)
	v_add_f32_e32 v151, v151, v153
	v_fmamk_f32 v151, v151, 0x3a800000, v176
	s_waitcnt lgkmcnt(3)
	v_add_f32_e32 v153, v154, v162
	v_mov_b32_e32 v182, v201
	v_mov_b32_e32 v183, v202
	v_mov_b32_e32 v201, v203
	s_waitcnt lgkmcnt(2)
	v_add_f32_e32 v154, v157, v165
	v_rsq_f32_e32 v178, v151
	v_fmamk_f32 v151, v153, 0x3a800000, v176
	v_pk_add_f32 v[182:183], v[182:183], v[200:201]
	s_waitcnt lgkmcnt(1)
	v_add_f32_e32 v157, v158, v166
	v_fmamk_f32 v153, v154, 0x3a800000, v176
	v_rsq_f32_e32 v180, v151
	v_add_f32_e32 v151, v182, v183
	v_fmamk_f32 v154, v157, 0x3a800000, v176
	v_rsq_f32_e32 v170, v153
	ds_bpermute_b32 v153, v147, v151
	v_rsq_f32_e32 v166, v154
	s_waitcnt lgkmcnt(1)
	v_add_f32_e32 v154, v161, v169
	v_mov_b32_e32 v182, v205
	v_mov_b32_e32 v183, v206
	v_mov_b32_e32 v205, v207
	v_fmamk_f32 v154, v154, 0x3a800000, v176
	v_pk_add_f32 v[182:183], v[182:183], v[204:205]
	v_rsq_f32_e32 v162, v154
	v_add_f32_e32 v154, v182, v183
	v_mov_b32_e32 v182, v209
	v_mov_b32_e32 v183, v210
	v_mov_b32_e32 v209, v211
	v_pk_add_f32 v[182:183], v[182:183], v[208:209]
	s_waitcnt lgkmcnt(0)
	v_add_f32_e32 v151, v151, v153
	v_add_f32_e32 v158, v182, v183
	ds_bpermute_b32 v153, v149, v151
	ds_bpermute_b32 v157, v147, v154
	ds_bpermute_b32 v147, v147, v158
	v_mov_b32_e32 v236, v178
	v_pk_mul_f32 v[182:183], v[124:125], v[178:179] op_sel_hi:[1,0]
	v_pk_mul_f32 v[120:121], v[120:121], v[178:179] op_sel_hi:[1,0]
	s_waitcnt lgkmcnt(2)
	v_add_f32_e32 v151, v151, v153
	s_waitcnt lgkmcnt(1)
	v_add_f32_e32 v153, v154, v157
	s_waitcnt lgkmcnt(0)
	v_add_f32_e32 v147, v158, v147
	ds_bpermute_b32 v154, v149, v153
	ds_bpermute_b32 v149, v149, v147
	v_exp_f32_e64 v125, -v182
	v_pk_mul_f32 v[116:117], v[116:117], v[178:179] op_sel_hi:[1,0]
	v_pk_mul_f32 v[126:127], v[126:127], v[178:179] op_sel_hi:[1,0]
	v_pk_mul_f32 v[116:117], v[182:183], v[116:117]
	s_waitcnt lgkmcnt(0)
; __device__ __forceinline__ unsigned cvt_pk_bf16(float lo, float hi) { unsigned r; asm volatile("v_cvt_pk_bf16_f32 %0, %1, %2" : "=v"(r) : "v"(lo), "v"(hi)); return r; }
; __device__ __forceinline__ unsigned cvt_pk_bf16(float lo, float hi) { f32x2_t v = {lo, hi}; bf16x2_t b = __builtin_convertvector(v, bf16x2_t); return __builtin_bit_cast(unsigned, b); }
;     __device__ __forceinline__ void operator()(const f32x4 (&acc)[2][2][4][2], const pg8::Unit& u, int wr, int wc, int fr, int fq) const {
;     ...
;         for (int ai = 0; ai < 2; ++ai)
; #pragma unroll
;             for (int m = 0; m < 4; ++m) {
;                 const int row = row0 + ai * 128 + m * 16;
;                 float r = 1.f; if (SCALE) r = rr[ai * 4 + m];
;                 const f32x4 g0 = acc[ai][0][m][0] * r, g1 = acc[ai][0][m][1] * r, u0 = acc[ai][1][m][0] * r, u1 = acc[ai][1][m][1] * r;
;                 u32x4 w;
;                 f32x4 h0, h1;
; #pragma unroll
;                 for (int j = 0; j < 4; ++j) { h0[j] = g0[j] * u0[j] * __builtin_amdgcn_rcpf(1.0f + __builtin_amdgcn_exp2f(-g0[j])); h1[j] = g1[j] * u1[j] * __builtin_amdgcn_rcpf(1.0f + __builtin_amdgcn_exp2f(-g1[j])); }
;                 w.x = cvt_pk_bf16(h0[0], h0[1]); w.y = cvt_pk_bf16(h0[2], h0[3]); w.z = cvt_pk_bf16(h1[0], h1[1]); w.w = cvt_pk_bf16(h1[2], h1[3]);
;                 *(u32x4*)(O + (size_t)row * FF + col0) = w;
;             }
	v_add_f32_e32 v147, v147, v149
	v_fmamk_f32 v147, v147, 0x3a800000, v176
	v_rsq_f32_e32 v124, v147
	v_exp_f32_e64 v147, -v183
	v_add_f32_e32 v125, 1.0, v125
	v_rcp_f32_e32 v184, v125
	v_pk_mul_f32 v[112:113], v[112:113], v[178:179] op_sel_hi:[1,0]
	v_add_f32_e32 v125, 1.0, v147
	v_rcp_f32_e32 v185, v125
	v_exp_f32_e64 v125, -v120
	v_exp_f32_e64 v147, -v121
	v_pk_mul_f32 v[122:123], v[122:123], v[178:179] op_sel_hi:[1,0]
	v_pk_mul_f32 v[112:113], v[120:121], v[112:113]
	v_add_f32_e32 v125, 1.0, v125
	v_rcp_f32_e32 v182, v125
	v_add_f32_e32 v125, 1.0, v147
	v_rcp_f32_e32 v183, v125
	v_exp_f32_e64 v125, -v126
	v_pk_mul_f32 v[118:119], v[118:119], v[178:179] op_sel_hi:[1,0]
	v_exp_f32_e64 v121, -v127
	v_pk_mul_f32 v[118:119], v[126:127], v[118:119]
	v_add_f32_e32 v120, 1.0, v125
	v_exp_f32_e64 v125, -v122
	v_exp_f32_e64 v127, -v123
	v_add_f32_e32 v121, 1.0, v121
	v_rcp_f32_e32 v120, v120
	v_add_f32_e32 v125, 1.0, v125
	v_rcp_f32_e32 v121, v121
	v_rcp_f32_e32 v126, v125
	v_add_f32_e32 v125, 1.0, v127
	v_rcp_f32_e32 v127, v125
	v_pk_mul_f32 v[114:115], v[114:115], v[178:179] op_sel_hi:[1,0]
	v_pk_mul_f32 v[116:117], v[116:117], v[184:185]
	v_pk_mul_f32 v[112:113], v[112:113], v[182:183]
	v_pk_mul_f32 v[118:119], v[118:119], v[120:121]
	v_pk_mul_f32 v[114:115], v[122:123], v[114:115]
	v_cvt_pk_bf16_f32 v116, v116, v117
	v_pk_mul_f32 v[114:115], v[114:115], v[126:127]
	v_cvt_pk_bf16_f32 v117, v118, v119
	v_cvt_pk_bf16_f32 v118, v112, v113
	v_mov_b64_e32 v[112:113], s[46:47]
	v_cvt_pk_bf16_f32 v119, v114, v115
	v_mad_i64_i32 v[120:121], s[20:21], v168, s43, v[112:113]
	v_lshlrev_b64 v[114:115], 1, v[172:173]
	v_mov_b32_e32 v238, v180
	v_pk_mul_f32 v[108:109], v[108:109], v[180:181] op_sel_hi:[1,0]
	v_lshl_add_u64 v[120:121], v[120:121], 0, v[114:115]
	v_pk_mul_f32 v[100:101], v[100:101], v[180:181] op_sel_hi:[1,0]
	v_pk_mul_f32 v[104:105], v[104:105], v[180:181] op_sel_hi:[1,0]
	v_exp_f32_e64 v122, -v108
	global_store_dwordx4 v[120:121], v[116:119], off
	v_pk_mul_f32 v[100:101], v[108:109], v[100:101]
	v_pk_mul_f32 v[96:97], v[96:97], v[180:181] op_sel_hi:[1,0]
	v_exp_f32_e64 v117, -v109
	v_exp_f32_e64 v118, -v104
	v_exp_f32_e64 v109, -v105
	v_add_f32_e32 v116, 1.0, v122
	v_add_f32_e32 v117, 1.0, v117
	v_add_f32_e32 v108, 1.0, v118
	v_add_f32_e32 v109, 1.0, v109
	v_rcp_f32_e32 v116, v116
	v_rcp_f32_e32 v117, v117
	v_rcp_f32_e32 v108, v108
	v_rcp_f32_e32 v109, v109
	v_pk_mul_f32 v[110:111], v[110:111], v[180:181] op_sel_hi:[1,0]
	v_pk_mul_f32 v[96:97], v[104:105], v[96:97]
	v_pk_mul_f32 v[100:101], v[100:101], v[116:117]
	v_exp_f32_e64 v116, -v110
	v_pk_mul_f32 v[104:105], v[96:97], v[108:109]
	v_exp_f32_e64 v97, -v111
	v_pk_mul_f32 v[106:107], v[106:107], v[180:181] op_sel_hi:[1,0]
	v_add_f32_e32 v96, 1.0, v116
	v_exp_f32_e64 v108, -v106
	v_exp_f32_e64 v109, -v107
	v_add_f32_e32 v97, 1.0, v97
	v_rcp_f32_e32 v96, v96
	v_rcp_f32_e32 v97, v97
	v_add_f32_e32 v108, 1.0, v108
	v_add_f32_e32 v109, 1.0, v109
	v_pk_mul_f32 v[102:103], v[102:103], v[180:181] op_sel_hi:[1,0]
	v_rcp_f32_e32 v108, v108
	v_rcp_f32_e32 v109, v109
	v_pk_mul_f32 v[102:103], v[110:111], v[102:103]
	v_mov_b32_e32 v240, v170
	v_pk_mul_f32 v[92:93], v[92:93], v[170:171] op_sel_hi:[1,0]
	v_pk_mul_f32 v[102:103], v[102:103], v[96:97]
	v_pk_mul_f32 v[96:97], v[98:99], v[180:181] op_sel_hi:[1,0]
	v_cvt_pk_bf16_f32 v98, v104, v105
	v_pk_mul_f32 v[96:97], v[106:107], v[96:97]
	v_pk_mul_f32 v[84:85], v[84:85], v[170:171] op_sel_hi:[1,0]
	v_pk_mul_f32 v[106:107], v[96:97], v[108:109]
	v_cvt_pk_bf16_f32 v96, v100, v101
	v_mad_i64_i32 v[100:101], s[20:21], v164, s43, v[112:113]
	v_cvt_pk_bf16_f32 v97, v102, v103
	v_cvt_pk_bf16_f32 v99, v106, v107
	v_lshl_add_u64 v[100:101], v[100:101], 0, v[114:115]
	v_pk_mul_f32 v[88:89], v[88:89], v[170:171] op_sel_hi:[1,0]
	v_exp_f32_e64 v102, -v92
	global_store_dwordx4 v[100:101], v[96:99], off
	v_pk_mul_f32 v[84:85], v[92:93], v[84:85]
	v_pk_mul_f32 v[80:81], v[80:81], v[170:171] op_sel_hi:[1,0]
	v_exp_f32_e64 v97, -v93
	v_exp_f32_e64 v98, -v88
	v_exp_f32_e64 v93, -v89
	v_add_f32_e32 v96, 1.0, v102
	v_add_f32_e32 v97, 1.0, v97
	v_add_f32_e32 v92, 1.0, v98
	v_add_f32_e32 v93, 1.0, v93
	v_rcp_f32_e32 v96, v96
	v_rcp_f32_e32 v97, v97
	v_rcp_f32_e32 v92, v92
	v_rcp_f32_e32 v93, v93
	v_pk_mul_f32 v[94:95], v[94:95], v[170:171] op_sel_hi:[1,0]
	v_pk_mul_f32 v[80:81], v[88:89], v[80:81]
	v_pk_mul_f32 v[84:85], v[84:85], v[96:97]
	v_exp_f32_e64 v96, -v94
	v_pk_mul_f32 v[88:89], v[80:81], v[92:93]
	v_exp_f32_e64 v81, -v95
	v_pk_mul_f32 v[90:91], v[90:91], v[170:171] op_sel_hi:[1,0]
	v_add_f32_e32 v80, 1.0, v96
	v_exp_f32_e64 v92, -v90
	v_exp_f32_e64 v93, -v91
	v_add_f32_e32 v81, 1.0, v81
	v_rcp_f32_e32 v80, v80
	v_rcp_f32_e32 v81, v81
	v_add_f32_e32 v92, 1.0, v92
	v_add_f32_e32 v93, 1.0, v93
	v_pk_mul_f32 v[86:87], v[86:87], v[170:171] op_sel_hi:[1,0]
	v_rcp_f32_e32 v92, v92
	v_rcp_f32_e32 v93, v93
	v_pk_mul_f32 v[86:87], v[94:95], v[86:87]
	v_mov_b32_e32 v242, v166
	v_pk_mul_f32 v[76:77], v[76:77], v[166:167] op_sel_hi:[1,0]
	v_pk_mul_f32 v[86:87], v[86:87], v[80:81]
	v_pk_mul_f32 v[80:81], v[82:83], v[170:171] op_sel_hi:[1,0]
	v_cvt_pk_bf16_f32 v82, v88, v89
	v_pk_mul_f32 v[80:81], v[90:91], v[80:81]
	v_pk_mul_f32 v[68:69], v[68:69], v[166:167] op_sel_hi:[1,0]
	v_pk_mul_f32 v[90:91], v[80:81], v[92:93]
	v_cvt_pk_bf16_f32 v80, v84, v85
	v_mad_i64_i32 v[84:85], s[20:21], v160, s43, v[112:113]
	v_cvt_pk_bf16_f32 v81, v86, v87
	v_cvt_pk_bf16_f32 v83, v90, v91
	v_lshl_add_u64 v[84:85], v[84:85], 0, v[114:115]
	v_pk_mul_f32 v[72:73], v[72:73], v[166:167] op_sel_hi:[1,0]
	v_exp_f32_e64 v86, -v76
	global_store_dwordx4 v[84:85], v[80:83], off
	v_pk_mul_f32 v[68:69], v[76:77], v[68:69]
; __device__ __forceinline__ unsigned cvt_pk_bf16(float lo, float hi) { unsigned r; asm volatile("v_cvt_pk_bf16_f32 %0, %1, %2" : "=v"(r) : "v"(lo), "v"(hi)); return r; }
; __device__ __forceinline__ unsigned cvt_pk_bf16(float lo, float hi) { f32x2_t v = {lo, hi}; bf16x2_t b = __builtin_convertvector(v, bf16x2_t); return __builtin_bit_cast(unsigned, b); }
;     __device__ __forceinline__ void operator()(const f32x4 (&acc)[2][2][4][2], const pg8::Unit& u, int wr, int wc, int fr, int fq) const {
;     ...
;         for (int ai = 0; ai < 2; ++ai)
; #pragma unroll
;             for (int m = 0; m < 4; ++m) {
;                 const int row = row0 + ai * 128 + m * 16;
;                 float r = 1.f; if (SCALE) r = rr[ai * 4 + m];
;                 const f32x4 g0 = acc[ai][0][m][0] * r, g1 = acc[ai][0][m][1] * r, u0 = acc[ai][1][m][0] * r, u1 = acc[ai][1][m][1] * r;
;                 u32x4 w;
;                 f32x4 h0, h1;
; #pragma unroll
;                 for (int j = 0; j < 4; ++j) { h0[j] = g0[j] * u0[j] * __builtin_amdgcn_rcpf(1.0f + __builtin_amdgcn_exp2f(-g0[j])); h1[j] = g1[j] * u1[j] * __builtin_amdgcn_rcpf(1.0f + __builtin_amdgcn_exp2f(-g1[j])); }
;                 w.x = cvt_pk_bf16(h0[0], h0[1]); w.y = cvt_pk_bf16(h0[2], h0[3]); w.z = cvt_pk_bf16(h1[0], h1[1]); w.w = cvt_pk_bf16(h1[2], h1[3]);
;                 *(u32x4*)(O + (size_t)row * FF + col0) = w;
;             }
	v_pk_mul_f32 v[64:65], v[64:65], v[166:167] op_sel_hi:[1,0]
	v_exp_f32_e64 v81, -v77
	v_exp_f32_e64 v82, -v72
	v_exp_f32_e64 v77, -v73
	v_add_f32_e32 v80, 1.0, v86
	v_add_f32_e32 v81, 1.0, v81
	v_add_f32_e32 v76, 1.0, v82
	v_add_f32_e32 v77, 1.0, v77
	v_rcp_f32_e32 v80, v80
	v_rcp_f32_e32 v81, v81
	v_rcp_f32_e32 v76, v76
	v_rcp_f32_e32 v77, v77
	v_pk_mul_f32 v[78:79], v[78:79], v[166:167] op_sel_hi:[1,0]
	v_pk_mul_f32 v[64:65], v[72:73], v[64:65]
	v_pk_mul_f32 v[68:69], v[68:69], v[80:81]
	v_exp_f32_e64 v80, -v78
	v_pk_mul_f32 v[72:73], v[64:65], v[76:77]
	v_exp_f32_e64 v65, -v79
	v_pk_mul_f32 v[74:75], v[74:75], v[166:167] op_sel_hi:[1,0]
	v_add_f32_e32 v64, 1.0, v80
	v_exp_f32_e64 v76, -v74
	v_exp_f32_e64 v77, -v75
	v_add_f32_e32 v65, 1.0, v65
	v_rcp_f32_e32 v64, v64
	v_rcp_f32_e32 v65, v65
	v_add_f32_e32 v76, 1.0, v76
	v_add_f32_e32 v77, 1.0, v77
	v_pk_mul_f32 v[70:71], v[70:71], v[166:167] op_sel_hi:[1,0]
	v_rcp_f32_e32 v76, v76
	v_rcp_f32_e32 v77, v77
	v_pk_mul_f32 v[70:71], v[78:79], v[70:71]
	v_mov_b32_e32 v244, v162
	v_pk_mul_f32 v[60:61], v[60:61], v[162:163] op_sel_hi:[1,0]
	v_pk_mul_f32 v[70:71], v[70:71], v[64:65]
	v_pk_mul_f32 v[64:65], v[66:67], v[166:167] op_sel_hi:[1,0]
	v_cvt_pk_bf16_f32 v66, v72, v73
	v_pk_mul_f32 v[64:65], v[74:75], v[64:65]
	v_pk_mul_f32 v[52:53], v[52:53], v[162:163] op_sel_hi:[1,0]
	v_pk_mul_f32 v[74:75], v[64:65], v[76:77]
	v_cvt_pk_bf16_f32 v64, v68, v69
	v_mad_i64_i32 v[68:69], s[20:21], v156, s43, v[112:113]
	v_cvt_pk_bf16_f32 v65, v70, v71
	v_cvt_pk_bf16_f32 v67, v74, v75
	v_lshl_add_u64 v[68:69], v[68:69], 0, v[114:115]
	v_pk_mul_f32 v[56:57], v[56:57], v[162:163] op_sel_hi:[1,0]
	v_exp_f32_e64 v70, -v60
	global_store_dwordx4 v[68:69], v[64:67], off
	v_pk_mul_f32 v[52:53], v[60:61], v[52:53]
	v_pk_mul_f32 v[48:49], v[48:49], v[162:163] op_sel_hi:[1,0]
	v_exp_f32_e64 v65, -v61
	v_exp_f32_e64 v66, -v56
	v_exp_f32_e64 v61, -v57
	v_add_f32_e32 v64, 1.0, v70
	v_add_f32_e32 v65, 1.0, v65
	v_add_f32_e32 v60, 1.0, v66
	v_add_f32_e32 v61, 1.0, v61
	v_rcp_f32_e32 v64, v64
	v_rcp_f32_e32 v65, v65
	v_rcp_f32_e32 v60, v60
	v_rcp_f32_e32 v61, v61
	v_pk_mul_f32 v[62:63], v[62:63], v[162:163] op_sel_hi:[1,0]
	v_pk_mul_f32 v[48:49], v[56:57], v[48:49]
	v_pk_mul_f32 v[52:53], v[52:53], v[64:65]
	v_exp_f32_e64 v64, -v62
	v_pk_mul_f32 v[56:57], v[48:49], v[60:61]
	v_exp_f32_e64 v49, -v63
	v_pk_mul_f32 v[58:59], v[58:59], v[162:163] op_sel_hi:[1,0]
	v_add_f32_e32 v48, 1.0, v64
	v_exp_f32_e64 v60, -v58
	v_exp_f32_e64 v61, -v59
	v_add_f32_e32 v49, 1.0, v49
	v_rcp_f32_e32 v48, v48
	v_rcp_f32_e32 v49, v49
	v_add_f32_e32 v60, 1.0, v60
	v_add_f32_e32 v61, 1.0, v61
	v_fmamk_f32 v151, v151, 0x3a800000, v176
	v_pk_mul_f32 v[54:55], v[54:55], v[162:163] op_sel_hi:[1,0]
	v_rcp_f32_e32 v60, v60
	v_rcp_f32_e32 v61, v61
	v_rsq_f32_e32 v158, v151
	v_pk_mul_f32 v[54:55], v[62:63], v[54:55]
	v_add_f32_e32 v151, v153, v154
	v_pk_mul_f32 v[54:55], v[54:55], v[48:49]
	v_pk_mul_f32 v[48:49], v[50:51], v[162:163] op_sel_hi:[1,0]
	v_cvt_pk_bf16_f32 v50, v56, v57
	v_pk_mul_f32 v[48:49], v[58:59], v[48:49]
	v_mov_b32_e32 v250, v158
	v_pk_mul_f32 v[44:45], v[44:45], v[158:159] op_sel_hi:[1,0]
	v_pk_mul_f32 v[58:59], v[48:49], v[60:61]
	v_cvt_pk_bf16_f32 v48, v52, v53
	v_mad_i64_i32 v[52:53], s[20:21], v152, s43, v[112:113]
	v_cvt_pk_bf16_f32 v49, v54, v55
	v_cvt_pk_bf16_f32 v51, v58, v59
	v_lshl_add_u64 v[52:53], v[52:53], 0, v[114:115]
	v_pk_mul_f32 v[36:37], v[36:37], v[158:159] op_sel_hi:[1,0]
	v_pk_mul_f32 v[40:41], v[40:41], v[158:159] op_sel_hi:[1,0]
	v_exp_f32_e64 v54, -v44
	global_store_dwordx4 v[52:53], v[48:51], off
	v_pk_mul_f32 v[36:37], v[44:45], v[36:37]
	v_pk_mul_f32 v[32:33], v[32:33], v[158:159] op_sel_hi:[1,0]
	v_exp_f32_e64 v49, -v45
	v_exp_f32_e64 v50, -v40
	v_exp_f32_e64 v45, -v41
	v_add_f32_e32 v48, 1.0, v54
	v_add_f32_e32 v49, 1.0, v49
	v_add_f32_e32 v44, 1.0, v50
	v_add_f32_e32 v45, 1.0, v45
	v_rcp_f32_e32 v48, v48
	v_rcp_f32_e32 v49, v49
	v_rcp_f32_e32 v44, v44
	v_rcp_f32_e32 v45, v45
	v_pk_mul_f32 v[46:47], v[46:47], v[158:159] op_sel_hi:[1,0]
	v_pk_mul_f32 v[32:33], v[40:41], v[32:33]
	v_pk_mul_f32 v[36:37], v[36:37], v[48:49]
	v_exp_f32_e64 v48, -v46
	v_pk_mul_f32 v[40:41], v[32:33], v[44:45]
	v_exp_f32_e64 v33, -v47
	v_pk_mul_f32 v[42:43], v[42:43], v[158:159] op_sel_hi:[1,0]
	v_add_f32_e32 v32, 1.0, v48
	v_exp_f32_e64 v44, -v42
	v_exp_f32_e64 v45, -v43
	v_add_f32_e32 v33, 1.0, v33
	v_rcp_f32_e32 v32, v32
	v_rcp_f32_e32 v33, v33
	v_add_f32_e32 v44, 1.0, v44
	v_add_f32_e32 v45, 1.0, v45
	v_fmamk_f32 v151, v151, 0x3a800000, v176
	v_pk_mul_f32 v[38:39], v[38:39], v[158:159] op_sel_hi:[1,0]
	v_rcp_f32_e32 v44, v44
	v_rcp_f32_e32 v45, v45
	v_rsq_f32_e32 v154, v151
	v_pk_mul_f32 v[38:39], v[46:47], v[38:39]
	v_mov_b32_e32 v248, v124
	v_pk_mul_f32 v[12:13], v[12:13], v[124:125] op_sel_hi:[1,0]
	v_pk_mul_f32 v[38:39], v[38:39], v[32:33]
	v_pk_mul_f32 v[32:33], v[34:35], v[158:159] op_sel_hi:[1,0]
	v_cvt_pk_bf16_f32 v34, v40, v41
	v_pk_mul_f32 v[32:33], v[42:43], v[32:33]
	v_mov_b32_e32 v252, v154
	v_pk_mul_f32 v[28:29], v[28:29], v[154:155] op_sel_hi:[1,0]
	v_pk_mul_f32 v[42:43], v[32:33], v[44:45]
	v_cvt_pk_bf16_f32 v32, v36, v37
	v_mad_i64_i32 v[36:37], s[20:21], v150, s43, v[112:113]
	v_cvt_pk_bf16_f32 v33, v38, v39
	v_cvt_pk_bf16_f32 v35, v42, v43
	v_lshl_add_u64 v[36:37], v[36:37], 0, v[114:115]
	v_pk_mul_f32 v[20:21], v[20:21], v[154:155] op_sel_hi:[1,0]
	v_pk_mul_f32 v[24:25], v[24:25], v[154:155] op_sel_hi:[1,0]
	v_exp_f32_e64 v38, -v28
	global_store_dwordx4 v[36:37], v[32:35], off
	v_pk_mul_f32 v[20:21], v[28:29], v[20:21]
	v_pk_mul_f32 v[16:17], v[16:17], v[154:155] op_sel_hi:[1,0]
	v_exp_f32_e64 v33, -v29
; __device__ __forceinline__ unsigned cvt_pk_bf16(float lo, float hi) { unsigned r; asm volatile("v_cvt_pk_bf16_f32 %0, %1, %2" : "=v"(r) : "v"(lo), "v"(hi)); return r; }
; __device__ __forceinline__ unsigned cvt_pk_bf16(float lo, float hi) { f32x2_t v = {lo, hi}; bf16x2_t b = __builtin_convertvector(v, bf16x2_t); return __builtin_bit_cast(unsigned, b); }
; template <class Epi, class Sched, bool ALIGN_EPI = false, bool SP2 = false>
; __device__ __forceinline__ void gemm_phase(PG8_LAS unsigned char* lds, const Gemm g, const Sched& S, const Epi& E) {
;     ...
;         if constexpr (!Epi::AFTER_DRAIN) { E(acc, cur, wr, wc, fr, fq); S.done(cur); }
;         if (!has_next) break;
;     __device__ __forceinline__ void operator()(const f32x4 (&acc)[2][2][4][2], const pg8::Unit& u, int wr, int wc, int fr, int fq) const {
;     ...
;         for (int ai = 0; ai < 2; ++ai)
; #pragma unroll
;             for (int m = 0; m < 4; ++m) {
;                 const int row = row0 + ai * 128 + m * 16;
;                 float r = 1.f; if (SCALE) r = rr[ai * 4 + m];
;                 const f32x4 g0 = acc[ai][0][m][0] * r, g1 = acc[ai][0][m][1] * r, u0 = acc[ai][1][m][0] * r, u1 = acc[ai][1][m][1] * r;
;                 u32x4 w;
;                 f32x4 h0, h1;
; #pragma unroll
;                 for (int j = 0; j < 4; ++j) { h0[j] = g0[j] * u0[j] * __builtin_amdgcn_rcpf(1.0f + __builtin_amdgcn_exp2f(-g0[j])); h1[j] = g1[j] * u1[j] * __builtin_amdgcn_rcpf(1.0f + __builtin_amdgcn_exp2f(-g1[j])); }
;                 w.x = cvt_pk_bf16(h0[0], h0[1]); w.y = cvt_pk_bf16(h0[2], h0[3]); w.z = cvt_pk_bf16(h1[0], h1[1]); w.w = cvt_pk_bf16(h1[2], h1[3]);
;                 *(u32x4*)(O + (size_t)row * FF + col0) = w;
;             }
	v_exp_f32_e64 v34, -v24
	v_exp_f32_e64 v29, -v25
	v_add_f32_e32 v32, 1.0, v38
	v_add_f32_e32 v33, 1.0, v33
	v_add_f32_e32 v28, 1.0, v34
	v_add_f32_e32 v29, 1.0, v29
	v_rcp_f32_e32 v32, v32
	v_rcp_f32_e32 v33, v33
	v_rcp_f32_e32 v28, v28
	v_rcp_f32_e32 v29, v29
	v_pk_mul_f32 v[30:31], v[30:31], v[154:155] op_sel_hi:[1,0]
	v_pk_mul_f32 v[16:17], v[24:25], v[16:17]
	v_pk_mul_f32 v[20:21], v[20:21], v[32:33]
	v_exp_f32_e64 v32, -v30
	v_pk_mul_f32 v[24:25], v[16:17], v[28:29]
	v_exp_f32_e64 v17, -v31
	v_pk_mul_f32 v[26:27], v[26:27], v[154:155] op_sel_hi:[1,0]
	v_add_f32_e32 v16, 1.0, v32
	v_exp_f32_e64 v28, -v26
	v_exp_f32_e64 v29, -v27
	v_add_f32_e32 v17, 1.0, v17
	v_rcp_f32_e32 v16, v16
	v_rcp_f32_e32 v17, v17
	v_add_f32_e32 v28, 1.0, v28
	v_add_f32_e32 v29, 1.0, v29
	v_pk_mul_f32 v[22:23], v[22:23], v[154:155] op_sel_hi:[1,0]
	v_rcp_f32_e32 v28, v28
	v_rcp_f32_e32 v29, v29
	v_pk_mul_f32 v[22:23], v[30:31], v[22:23]
	v_pk_mul_f32 v[4:5], v[4:5], v[124:125] op_sel_hi:[1,0]
	v_pk_mul_f32 v[22:23], v[22:23], v[16:17]
	v_pk_mul_f32 v[16:17], v[18:19], v[154:155] op_sel_hi:[1,0]
	v_cvt_pk_bf16_f32 v18, v24, v25
	v_pk_mul_f32 v[16:17], v[26:27], v[16:17]
	v_pk_mul_f32 v[8:9], v[8:9], v[124:125] op_sel_hi:[1,0]
	v_pk_mul_f32 v[26:27], v[16:17], v[28:29]
	v_cvt_pk_bf16_f32 v16, v20, v21
	v_mad_i64_i32 v[20:21], s[20:21], v148, s43, v[112:113]
	v_cvt_pk_bf16_f32 v17, v22, v23
	v_cvt_pk_bf16_f32 v19, v26, v27
	v_lshl_add_u64 v[20:21], v[20:21], 0, v[114:115]
	v_exp_f32_e64 v22, -v12
	global_store_dwordx4 v[20:21], v[16:19], off
	v_pk_mul_f32 v[4:5], v[12:13], v[4:5]
	v_pk_mul_f32 v[0:1], v[0:1], v[124:125] op_sel_hi:[1,0]
	v_exp_f32_e64 v17, -v13
	v_exp_f32_e64 v18, -v8
	v_exp_f32_e64 v13, -v9
	v_add_f32_e32 v16, 1.0, v22
	v_add_f32_e32 v17, 1.0, v17
	v_add_f32_e32 v12, 1.0, v18
	v_add_f32_e32 v13, 1.0, v13
	v_rcp_f32_e32 v16, v16
	v_rcp_f32_e32 v17, v17
	v_rcp_f32_e32 v12, v12
	v_rcp_f32_e32 v13, v13
	v_pk_mul_f32 v[14:15], v[14:15], v[124:125] op_sel_hi:[1,0]
	v_pk_mul_f32 v[0:1], v[8:9], v[0:1]
	v_pk_mul_f32 v[4:5], v[4:5], v[16:17]
	v_exp_f32_e64 v16, -v14
	v_pk_mul_f32 v[8:9], v[0:1], v[12:13]
	v_exp_f32_e64 v1, -v15
	v_pk_mul_f32 v[10:11], v[10:11], v[124:125] op_sel_hi:[1,0]
	v_add_f32_e32 v0, 1.0, v16
	v_exp_f32_e64 v12, -v10
	v_exp_f32_e64 v13, -v11
	v_add_f32_e32 v1, 1.0, v1
	v_rcp_f32_e32 v0, v0
	v_rcp_f32_e32 v1, v1
	v_add_f32_e32 v12, 1.0, v12
	v_add_f32_e32 v13, 1.0, v13
	v_pk_mul_f32 v[6:7], v[6:7], v[124:125] op_sel_hi:[1,0]
	v_rcp_f32_e32 v12, v12
	v_rcp_f32_e32 v13, v13
	v_pk_mul_f32 v[6:7], v[14:15], v[6:7]
	s_andn2_b64 vcc, exec, s[0:1]
	v_pk_mul_f32 v[6:7], v[6:7], v[0:1]
	v_pk_mul_f32 v[0:1], v[2:3], v[124:125] op_sel_hi:[1,0]
	v_cvt_pk_bf16_f32 v2, v8, v9
	v_pk_mul_f32 v[0:1], v[10:11], v[0:1]
	s_mov_b64 s[0:1], -1
	v_pk_mul_f32 v[10:11], v[0:1], v[12:13]
	v_cvt_pk_bf16_f32 v0, v4, v5
	v_mad_i64_i32 v[4:5], s[20:21], v146, s43, v[112:113]
	v_cvt_pk_bf16_f32 v1, v6, v7
	v_cvt_pk_bf16_f32 v3, v10, v11
	v_lshl_add_u64 v[4:5], v[4:5], 0, v[114:115]
	global_store_dwordx4 v[4:5], v[0:3], off
.Lg8_tail:
	s_cbranch_vccnz .LBB0_852
	s_andn2_b64 vcc, exec, s[4:5]
	s_cbranch_vccnz .LBB0_851
	s_barrier
	s_branch .LBB0_851
.Lg8_hit:
	v_lshl_add_u32 v168, s18, 8, v155
	v_ashrrev_i32_e32 v169, 31, v168
	v_or_b32_e32 v164, 16, v168
	v_lshlrev_b64 v[146:147], 6, v[168:169]
	v_ashrrev_i32_e32 v165, 31, v164
	v_or_b32_e32 v160, 32, v168
	v_lshl_add_u64 v[146:147], v[136:137], 0, v[146:147]
	v_lshlrev_b64 v[148:149], 6, v[164:165]
	v_ashrrev_i32_e32 v161, 31, v160
	v_or_b32_e32 v156, 48, v168
	v_lshl_add_u64 v[148:149], v[136:137], 0, v[148:149]
	v_lshlrev_b64 v[146:147], 6, v[160:161]
	v_ashrrev_i32_e32 v157, 31, v156
	v_add_u32_e32 v152, 0x80, v168
	v_lshl_add_u64 v[146:147], v[136:137], 0, v[146:147]
	v_lshlrev_b64 v[148:149], 6, v[156:157]
	v_ashrrev_i32_e32 v153, 31, v152
	v_lshl_add_u64 v[148:149], v[136:137], 0, v[148:149]
	v_lshlrev_b64 v[146:147], 6, v[152:153]
	v_lshl_add_u64 v[146:147], v[136:137], 0, v[146:147]
	v_add_u32_e32 v150, 0x90, v168
	v_ashrrev_i32_e32 v151, 31, v150
	v_lshlrev_b64 v[146:147], 6, v[150:151]
	v_add_u32_e32 v148, 0xa0, v168
	v_lshl_add_u64 v[146:147], v[136:137], 0, v[146:147]
	v_ashrrev_i32_e32 v149, 31, v148
	v_lshlrev_b64 v[146:147], 6, v[148:149]
	v_lshl_add_u64 v[146:147], v[136:137], 0, v[146:147]
	v_add_u32_e32 v146, 0xb0, v168
	v_ashrrev_i32_e32 v147, 31, v146
	v_lshlrev_b64 v[208:209], 6, v[146:147]
	v_lshl_add_u64 v[208:209], v[136:137], 0, v[208:209]
	v_and_b32_e32 v149, 64, v175
	v_xor_b32_e32 v147, 16, v175
	v_add_u32_e32 v149, 64, v149
	v_xor_b32_e32 v151, 32, v175
	v_cmp_lt_i32_e32 vcc, v147, v149
	v_lshl_or_b32 v172, s50, 7, v163
	v_ashrrev_i32_e32 v173, 31, v172
	v_cndmask_b32_e32 v147, v175, v147, vcc
	v_cmp_lt_i32_e32 vcc, v151, v149
	v_lshlrev_b32_e32 v147, 2, v147
	s_nop 0
	v_cndmask_b32_e32 v149, v175, v151, vcc
	v_lshlrev_b32_e32 v149, 2, v149
	v_pk_mul_f32 v[182:183], v[124:125], v[236:237] op_sel_hi:[1,0]
	v_pk_mul_f32 v[120:121], v[120:121], v[236:237] op_sel_hi:[1,0]
	v_exp_f32_e64 v125, -v182
	v_pk_mul_f32 v[116:117], v[116:117], v[236:237] op_sel_hi:[1,0]
	v_pk_mul_f32 v[126:127], v[126:127], v[236:237] op_sel_hi:[1,0]
	v_pk_mul_f32 v[116:117], v[182:183], v[116:117]
	v_exp_f32_e64 v147, -v183
	v_add_f32_e32 v125, 1.0, v125
	v_rcp_f32_e32 v184, v125
	v_pk_mul_f32 v[112:113], v[112:113], v[236:237] op_sel_hi:[1,0]
	v_add_f32_e32 v125, 1.0, v147
	v_rcp_f32_e32 v185, v125
	v_exp_f32_e64 v125, -v120
	v_exp_f32_e64 v147, -v121
	v_pk_mul_f32 v[122:123], v[122:123], v[236:237] op_sel_hi:[1,0]
	v_pk_mul_f32 v[112:113], v[120:121], v[112:113]
	v_add_f32_e32 v125, 1.0, v125
	v_rcp_f32_e32 v182, v125
; __device__ __forceinline__ unsigned cvt_pk_bf16(float lo, float hi) { unsigned r; asm volatile("v_cvt_pk_bf16_f32 %0, %1, %2" : "=v"(r) : "v"(lo), "v"(hi)); return r; }
; __device__ __forceinline__ unsigned cvt_pk_bf16(float lo, float hi) { f32x2_t v = {lo, hi}; bf16x2_t b = __builtin_convertvector(v, bf16x2_t); return __builtin_bit_cast(unsigned, b); }
;     __device__ __forceinline__ void operator()(const f32x4 (&acc)[2][2][4][2], const pg8::Unit& u, int wr, int wc, int fr, int fq) const {
;     ...
;         for (int ai = 0; ai < 2; ++ai)
; #pragma unroll
;             for (int m = 0; m < 4; ++m) {
;                 const int row = row0 + ai * 128 + m * 16;
;                 float r = 1.f; if (SCALE) r = rr[ai * 4 + m];
;                 const f32x4 g0 = acc[ai][0][m][0] * r, g1 = acc[ai][0][m][1] * r, u0 = acc[ai][1][m][0] * r, u1 = acc[ai][1][m][1] * r;
;                 u32x4 w;
;                 f32x4 h0, h1;
; #pragma unroll
;                 for (int j = 0; j < 4; ++j) { h0[j] = g0[j] * u0[j] * __builtin_amdgcn_rcpf(1.0f + __builtin_amdgcn_exp2f(-g0[j])); h1[j] = g1[j] * u1[j] * __builtin_amdgcn_rcpf(1.0f + __builtin_amdgcn_exp2f(-g1[j])); }
;                 w.x = cvt_pk_bf16(h0[0], h0[1]); w.y = cvt_pk_bf16(h0[2], h0[3]); w.z = cvt_pk_bf16(h1[0], h1[1]); w.w = cvt_pk_bf16(h1[2], h1[3]);
;                 *(u32x4*)(O + (size_t)row * FF + col0) = w;
;             }
	v_add_f32_e32 v125, 1.0, v147
	v_rcp_f32_e32 v183, v125
	v_exp_f32_e64 v125, -v126
	v_pk_mul_f32 v[118:119], v[118:119], v[236:237] op_sel_hi:[1,0]
	v_exp_f32_e64 v121, -v127
	v_pk_mul_f32 v[118:119], v[126:127], v[118:119]
	v_add_f32_e32 v120, 1.0, v125
	v_exp_f32_e64 v125, -v122
	v_exp_f32_e64 v127, -v123
	v_add_f32_e32 v121, 1.0, v121
	v_rcp_f32_e32 v120, v120
	v_add_f32_e32 v125, 1.0, v125
	v_rcp_f32_e32 v121, v121
	v_rcp_f32_e32 v126, v125
	v_add_f32_e32 v125, 1.0, v127
	v_rcp_f32_e32 v127, v125
	v_pk_mul_f32 v[114:115], v[114:115], v[236:237] op_sel_hi:[1,0]
	v_pk_mul_f32 v[116:117], v[116:117], v[184:185]
	v_pk_mul_f32 v[112:113], v[112:113], v[182:183]
	v_pk_mul_f32 v[118:119], v[118:119], v[120:121]
	v_pk_mul_f32 v[114:115], v[122:123], v[114:115]
	v_cvt_pk_bf16_f32 v116, v116, v117
	v_pk_mul_f32 v[114:115], v[114:115], v[126:127]
	v_cvt_pk_bf16_f32 v117, v118, v119
	v_cvt_pk_bf16_f32 v118, v112, v113
	v_mov_b64_e32 v[112:113], s[46:47]
	v_cvt_pk_bf16_f32 v119, v114, v115
	v_mad_i64_i32 v[120:121], s[20:21], v168, s43, v[112:113]
	v_lshlrev_b64 v[114:115], 1, v[172:173]
	v_pk_mul_f32 v[108:109], v[108:109], v[238:239] op_sel_hi:[1,0]
	v_lshl_add_u64 v[120:121], v[120:121], 0, v[114:115]
	v_pk_mul_f32 v[100:101], v[100:101], v[238:239] op_sel_hi:[1,0]
	v_pk_mul_f32 v[104:105], v[104:105], v[238:239] op_sel_hi:[1,0]
	v_exp_f32_e64 v122, -v108
	global_store_dwordx4 v[120:121], v[116:119], off
	v_pk_mul_f32 v[100:101], v[108:109], v[100:101]
	v_pk_mul_f32 v[96:97], v[96:97], v[238:239] op_sel_hi:[1,0]
	v_exp_f32_e64 v117, -v109
	v_exp_f32_e64 v118, -v104
	v_exp_f32_e64 v109, -v105
	v_add_f32_e32 v116, 1.0, v122
	v_add_f32_e32 v117, 1.0, v117
	v_add_f32_e32 v108, 1.0, v118
	v_add_f32_e32 v109, 1.0, v109
	v_rcp_f32_e32 v116, v116
	v_rcp_f32_e32 v117, v117
	v_rcp_f32_e32 v108, v108
	v_rcp_f32_e32 v109, v109
	v_pk_mul_f32 v[110:111], v[110:111], v[238:239] op_sel_hi:[1,0]
	v_pk_mul_f32 v[96:97], v[104:105], v[96:97]
	v_pk_mul_f32 v[100:101], v[100:101], v[116:117]
	v_exp_f32_e64 v116, -v110
	v_pk_mul_f32 v[104:105], v[96:97], v[108:109]
	v_exp_f32_e64 v97, -v111
	v_pk_mul_f32 v[106:107], v[106:107], v[238:239] op_sel_hi:[1,0]
	v_add_f32_e32 v96, 1.0, v116
	v_exp_f32_e64 v108, -v106
	v_exp_f32_e64 v109, -v107
	v_add_f32_e32 v97, 1.0, v97
	v_rcp_f32_e32 v96, v96
	v_rcp_f32_e32 v97, v97
	v_add_f32_e32 v108, 1.0, v108
	v_add_f32_e32 v109, 1.0, v109
	v_pk_mul_f32 v[102:103], v[102:103], v[238:239] op_sel_hi:[1,0]
	v_rcp_f32_e32 v108, v108
	v_rcp_f32_e32 v109, v109
	v_pk_mul_f32 v[102:103], v[110:111], v[102:103]
	v_pk_mul_f32 v[92:93], v[92:93], v[240:241] op_sel_hi:[1,0]
	v_pk_mul_f32 v[102:103], v[102:103], v[96:97]
	v_pk_mul_f32 v[96:97], v[98:99], v[238:239] op_sel_hi:[1,0]
	v_cvt_pk_bf16_f32 v98, v104, v105
	v_pk_mul_f32 v[96:97], v[106:107], v[96:97]
	v_pk_mul_f32 v[84:85], v[84:85], v[240:241] op_sel_hi:[1,0]
	v_pk_mul_f32 v[106:107], v[96:97], v[108:109]
	v_cvt_pk_bf16_f32 v96, v100, v101
	v_mad_i64_i32 v[100:101], s[20:21], v164, s43, v[112:113]
	v_cvt_pk_bf16_f32 v97, v102, v103
	v_cvt_pk_bf16_f32 v99, v106, v107
	v_lshl_add_u64 v[100:101], v[100:101], 0, v[114:115]
	v_pk_mul_f32 v[88:89], v[88:89], v[240:241] op_sel_hi:[1,0]
	v_exp_f32_e64 v102, -v92
	global_store_dwordx4 v[100:101], v[96:99], off
	v_pk_mul_f32 v[84:85], v[92:93], v[84:85]
	v_pk_mul_f32 v[80:81], v[80:81], v[240:241] op_sel_hi:[1,0]
	v_exp_f32_e64 v97, -v93
	v_exp_f32_e64 v98, -v88
	v_exp_f32_e64 v93, -v89
	v_add_f32_e32 v96, 1.0, v102
	v_add_f32_e32 v97, 1.0, v97
	v_add_f32_e32 v92, 1.0, v98
	v_add_f32_e32 v93, 1.0, v93
	v_rcp_f32_e32 v96, v96
	v_rcp_f32_e32 v97, v97
	v_rcp_f32_e32 v92, v92
	v_rcp_f32_e32 v93, v93
	v_pk_mul_f32 v[94:95], v[94:95], v[240:241] op_sel_hi:[1,0]
	v_pk_mul_f32 v[80:81], v[88:89], v[80:81]
	v_pk_mul_f32 v[84:85], v[84:85], v[96:97]
	v_exp_f32_e64 v96, -v94
	v_pk_mul_f32 v[88:89], v[80:81], v[92:93]
	v_exp_f32_e64 v81, -v95
	v_pk_mul_f32 v[90:91], v[90:91], v[240:241] op_sel_hi:[1,0]
	v_add_f32_e32 v80, 1.0, v96
	v_exp_f32_e64 v92, -v90
	v_exp_f32_e64 v93, -v91
	v_add_f32_e32 v81, 1.0, v81
	v_rcp_f32_e32 v80, v80
	v_rcp_f32_e32 v81, v81
	v_add_f32_e32 v92, 1.0, v92
	v_add_f32_e32 v93, 1.0, v93
	v_pk_mul_f32 v[86:87], v[86:87], v[240:241] op_sel_hi:[1,0]
	v_rcp_f32_e32 v92, v92
	v_rcp_f32_e32 v93, v93
	v_pk_mul_f32 v[86:87], v[94:95], v[86:87]
	v_pk_mul_f32 v[76:77], v[76:77], v[242:243] op_sel_hi:[1,0]
	v_pk_mul_f32 v[86:87], v[86:87], v[80:81]
	v_pk_mul_f32 v[80:81], v[82:83], v[240:241] op_sel_hi:[1,0]
	v_cvt_pk_bf16_f32 v82, v88, v89
	v_pk_mul_f32 v[80:81], v[90:91], v[80:81]
	v_pk_mul_f32 v[68:69], v[68:69], v[242:243] op_sel_hi:[1,0]
	v_pk_mul_f32 v[90:91], v[80:81], v[92:93]
	v_cvt_pk_bf16_f32 v80, v84, v85
	v_mad_i64_i32 v[84:85], s[20:21], v160, s43, v[112:113]
	v_cvt_pk_bf16_f32 v81, v86, v87
	v_cvt_pk_bf16_f32 v83, v90, v91
	v_lshl_add_u64 v[84:85], v[84:85], 0, v[114:115]
	v_pk_mul_f32 v[72:73], v[72:73], v[242:243] op_sel_hi:[1,0]
	v_exp_f32_e64 v86, -v76
	global_store_dwordx4 v[84:85], v[80:83], off
	v_pk_mul_f32 v[68:69], v[76:77], v[68:69]
	v_pk_mul_f32 v[64:65], v[64:65], v[242:243] op_sel_hi:[1,0]
	v_exp_f32_e64 v81, -v77
	v_exp_f32_e64 v82, -v72
	v_exp_f32_e64 v77, -v73
	v_add_f32_e32 v80, 1.0, v86
	v_add_f32_e32 v81, 1.0, v81
	v_add_f32_e32 v76, 1.0, v82
	v_add_f32_e32 v77, 1.0, v77
	v_rcp_f32_e32 v80, v80
	v_rcp_f32_e32 v81, v81
	v_rcp_f32_e32 v76, v76
	v_rcp_f32_e32 v77, v77
	v_pk_mul_f32 v[78:79], v[78:79], v[242:243] op_sel_hi:[1,0]
	v_pk_mul_f32 v[64:65], v[72:73], v[64:65]
	v_pk_mul_f32 v[68:69], v[68:69], v[80:81]
	v_exp_f32_e64 v80, -v78
	v_pk_mul_f32 v[72:73], v[64:65], v[76:77]
	v_exp_f32_e64 v65, -v79
; __device__ __forceinline__ unsigned cvt_pk_bf16(float lo, float hi) { unsigned r; asm volatile("v_cvt_pk_bf16_f32 %0, %1, %2" : "=v"(r) : "v"(lo), "v"(hi)); return r; }
; __device__ __forceinline__ unsigned cvt_pk_bf16(float lo, float hi) { f32x2_t v = {lo, hi}; bf16x2_t b = __builtin_convertvector(v, bf16x2_t); return __builtin_bit_cast(unsigned, b); }
;     __device__ __forceinline__ void operator()(const f32x4 (&acc)[2][2][4][2], const pg8::Unit& u, int wr, int wc, int fr, int fq) const {
;     ...
;         for (int ai = 0; ai < 2; ++ai)
; #pragma unroll
;             for (int m = 0; m < 4; ++m) {
;                 const int row = row0 + ai * 128 + m * 16;
;                 float r = 1.f; if (SCALE) r = rr[ai * 4 + m];
;                 const f32x4 g0 = acc[ai][0][m][0] * r, g1 = acc[ai][0][m][1] * r, u0 = acc[ai][1][m][0] * r, u1 = acc[ai][1][m][1] * r;
;                 u32x4 w;
;                 f32x4 h0, h1;
; #pragma unroll
;                 for (int j = 0; j < 4; ++j) { h0[j] = g0[j] * u0[j] * __builtin_amdgcn_rcpf(1.0f + __builtin_amdgcn_exp2f(-g0[j])); h1[j] = g1[j] * u1[j] * __builtin_amdgcn_rcpf(1.0f + __builtin_amdgcn_exp2f(-g1[j])); }
;                 w.x = cvt_pk_bf16(h0[0], h0[1]); w.y = cvt_pk_bf16(h0[2], h0[3]); w.z = cvt_pk_bf16(h1[0], h1[1]); w.w = cvt_pk_bf16(h1[2], h1[3]);
;                 *(u32x4*)(O + (size_t)row * FF + col0) = w;
;             }
	v_pk_mul_f32 v[74:75], v[74:75], v[242:243] op_sel_hi:[1,0]
	v_add_f32_e32 v64, 1.0, v80
	v_exp_f32_e64 v76, -v74
	v_exp_f32_e64 v77, -v75
	v_add_f32_e32 v65, 1.0, v65
	v_rcp_f32_e32 v64, v64
	v_rcp_f32_e32 v65, v65
	v_add_f32_e32 v76, 1.0, v76
	v_add_f32_e32 v77, 1.0, v77
	v_pk_mul_f32 v[70:71], v[70:71], v[242:243] op_sel_hi:[1,0]
	v_rcp_f32_e32 v76, v76
	v_rcp_f32_e32 v77, v77
	v_pk_mul_f32 v[70:71], v[78:79], v[70:71]
	v_pk_mul_f32 v[60:61], v[60:61], v[244:245] op_sel_hi:[1,0]
	v_pk_mul_f32 v[70:71], v[70:71], v[64:65]
	v_pk_mul_f32 v[64:65], v[66:67], v[242:243] op_sel_hi:[1,0]
	v_cvt_pk_bf16_f32 v66, v72, v73
	v_pk_mul_f32 v[64:65], v[74:75], v[64:65]
	v_pk_mul_f32 v[52:53], v[52:53], v[244:245] op_sel_hi:[1,0]
	v_pk_mul_f32 v[74:75], v[64:65], v[76:77]
	v_cvt_pk_bf16_f32 v64, v68, v69
	v_mad_i64_i32 v[68:69], s[20:21], v156, s43, v[112:113]
	v_cvt_pk_bf16_f32 v65, v70, v71
	v_cvt_pk_bf16_f32 v67, v74, v75
	v_lshl_add_u64 v[68:69], v[68:69], 0, v[114:115]
	v_pk_mul_f32 v[56:57], v[56:57], v[244:245] op_sel_hi:[1,0]
	v_exp_f32_e64 v70, -v60
	global_store_dwordx4 v[68:69], v[64:67], off
	v_pk_mul_f32 v[52:53], v[60:61], v[52:53]
	v_pk_mul_f32 v[48:49], v[48:49], v[244:245] op_sel_hi:[1,0]
	v_exp_f32_e64 v65, -v61
	v_exp_f32_e64 v66, -v56
	v_exp_f32_e64 v61, -v57
	v_add_f32_e32 v64, 1.0, v70
	v_add_f32_e32 v65, 1.0, v65
	v_add_f32_e32 v60, 1.0, v66
	v_add_f32_e32 v61, 1.0, v61
	v_rcp_f32_e32 v64, v64
	v_rcp_f32_e32 v65, v65
	v_rcp_f32_e32 v60, v60
	v_rcp_f32_e32 v61, v61
	v_pk_mul_f32 v[62:63], v[62:63], v[244:245] op_sel_hi:[1,0]
	v_pk_mul_f32 v[48:49], v[56:57], v[48:49]
	v_pk_mul_f32 v[52:53], v[52:53], v[64:65]
	v_exp_f32_e64 v64, -v62
	v_pk_mul_f32 v[56:57], v[48:49], v[60:61]
	v_exp_f32_e64 v49, -v63
	v_pk_mul_f32 v[58:59], v[58:59], v[244:245] op_sel_hi:[1,0]
	v_add_f32_e32 v48, 1.0, v64
	v_exp_f32_e64 v60, -v58
	v_exp_f32_e64 v61, -v59
	v_add_f32_e32 v49, 1.0, v49
	v_rcp_f32_e32 v48, v48
	v_rcp_f32_e32 v49, v49
	v_add_f32_e32 v60, 1.0, v60
	v_add_f32_e32 v61, 1.0, v61
	v_pk_mul_f32 v[54:55], v[54:55], v[244:245] op_sel_hi:[1,0]
	v_rcp_f32_e32 v60, v60
	v_rcp_f32_e32 v61, v61
	v_pk_mul_f32 v[54:55], v[62:63], v[54:55]
	v_pk_mul_f32 v[54:55], v[54:55], v[48:49]
	v_pk_mul_f32 v[48:49], v[50:51], v[244:245] op_sel_hi:[1,0]
	v_cvt_pk_bf16_f32 v50, v56, v57
	v_pk_mul_f32 v[48:49], v[58:59], v[48:49]
	v_pk_mul_f32 v[44:45], v[44:45], v[250:251] op_sel_hi:[1,0]
	v_pk_mul_f32 v[58:59], v[48:49], v[60:61]
	v_cvt_pk_bf16_f32 v48, v52, v53
	v_mad_i64_i32 v[52:53], s[20:21], v152, s43, v[112:113]
	v_cvt_pk_bf16_f32 v49, v54, v55
	v_cvt_pk_bf16_f32 v51, v58, v59
	v_lshl_add_u64 v[52:53], v[52:53], 0, v[114:115]
	v_pk_mul_f32 v[36:37], v[36:37], v[250:251] op_sel_hi:[1,0]
	v_pk_mul_f32 v[40:41], v[40:41], v[250:251] op_sel_hi:[1,0]
	v_exp_f32_e64 v54, -v44
	global_store_dwordx4 v[52:53], v[48:51], off
	v_pk_mul_f32 v[36:37], v[44:45], v[36:37]
	v_pk_mul_f32 v[32:33], v[32:33], v[250:251] op_sel_hi:[1,0]
	v_exp_f32_e64 v49, -v45
	v_exp_f32_e64 v50, -v40
	v_exp_f32_e64 v45, -v41
	v_add_f32_e32 v48, 1.0, v54
	v_add_f32_e32 v49, 1.0, v49
	v_add_f32_e32 v44, 1.0, v50
	v_add_f32_e32 v45, 1.0, v45
	v_rcp_f32_e32 v48, v48
	v_rcp_f32_e32 v49, v49
	v_rcp_f32_e32 v44, v44
	v_rcp_f32_e32 v45, v45
	v_pk_mul_f32 v[46:47], v[46:47], v[250:251] op_sel_hi:[1,0]
	v_pk_mul_f32 v[32:33], v[40:41], v[32:33]
	v_pk_mul_f32 v[36:37], v[36:37], v[48:49]
	v_exp_f32_e64 v48, -v46
	v_pk_mul_f32 v[40:41], v[32:33], v[44:45]
	v_exp_f32_e64 v33, -v47
	v_pk_mul_f32 v[42:43], v[42:43], v[250:251] op_sel_hi:[1,0]
	v_add_f32_e32 v32, 1.0, v48
	v_exp_f32_e64 v44, -v42
	v_exp_f32_e64 v45, -v43
	v_add_f32_e32 v33, 1.0, v33
	v_rcp_f32_e32 v32, v32
	v_rcp_f32_e32 v33, v33
	v_add_f32_e32 v44, 1.0, v44
	v_add_f32_e32 v45, 1.0, v45
	v_pk_mul_f32 v[38:39], v[38:39], v[250:251] op_sel_hi:[1,0]
	v_rcp_f32_e32 v44, v44
	v_rcp_f32_e32 v45, v45
	v_pk_mul_f32 v[38:39], v[46:47], v[38:39]
; __device__ __forceinline__ unsigned cvt_pk_bf16(float lo, float hi) { unsigned r; asm volatile("v_cvt_pk_bf16_f32 %0, %1, %2" : "=v"(r) : "v"(lo), "v"(hi)); return r; }
; __device__ __forceinline__ unsigned cvt_pk_bf16(float lo, float hi) { f32x2_t v = {lo, hi}; bf16x2_t b = __builtin_convertvector(v, bf16x2_t); return __builtin_bit_cast(unsigned, b); }
;     __device__ __forceinline__ void operator()(const f32x4 (&acc)[2][2][4][2], const pg8::Unit& u, int wr, int wc, int fr, int fq) const {
;     ...
;         for (int ai = 0; ai < 2; ++ai)
; #pragma unroll
;             for (int m = 0; m < 4; ++m) {
;                 const int row = row0 + ai * 128 + m * 16;
;                 float r = 1.f; if (SCALE) r = rr[ai * 4 + m];
;                 const f32x4 g0 = acc[ai][0][m][0] * r, g1 = acc[ai][0][m][1] * r, u0 = acc[ai][1][m][0] * r, u1 = acc[ai][1][m][1] * r;
;                 u32x4 w;
;                 f32x4 h0, h1;
; #pragma unroll
;                 for (int j = 0; j < 4; ++j) { h0[j] = g0[j] * u0[j] * __builtin_amdgcn_rcpf(1.0f + __builtin_amdgcn_exp2f(-g0[j])); h1[j] = g1[j] * u1[j] * __builtin_amdgcn_rcpf(1.0f + __builtin_amdgcn_exp2f(-g1[j])); }
;                 w.x = cvt_pk_bf16(h0[0], h0[1]); w.y = cvt_pk_bf16(h0[2], h0[3]); w.z = cvt_pk_bf16(h1[0], h1[1]); w.w = cvt_pk_bf16(h1[2], h1[3]);
;                 *(u32x4*)(O + (size_t)row * FF + col0) = w;
;             }
	v_pk_mul_f32 v[12:13], v[12:13], v[248:249] op_sel_hi:[1,0]
	v_pk_mul_f32 v[38:39], v[38:39], v[32:33]
	v_pk_mul_f32 v[32:33], v[34:35], v[250:251] op_sel_hi:[1,0]
	v_cvt_pk_bf16_f32 v34, v40, v41
	v_pk_mul_f32 v[32:33], v[42:43], v[32:33]
	v_pk_mul_f32 v[28:29], v[28:29], v[252:253] op_sel_hi:[1,0]
	v_pk_mul_f32 v[42:43], v[32:33], v[44:45]
	v_cvt_pk_bf16_f32 v32, v36, v37
	v_mad_i64_i32 v[36:37], s[20:21], v150, s43, v[112:113]
	v_cvt_pk_bf16_f32 v33, v38, v39
	v_cvt_pk_bf16_f32 v35, v42, v43
	v_lshl_add_u64 v[36:37], v[36:37], 0, v[114:115]
	v_pk_mul_f32 v[20:21], v[20:21], v[252:253] op_sel_hi:[1,0]
	v_pk_mul_f32 v[24:25], v[24:25], v[252:253] op_sel_hi:[1,0]
	v_exp_f32_e64 v38, -v28
	global_store_dwordx4 v[36:37], v[32:35], off
	v_pk_mul_f32 v[20:21], v[28:29], v[20:21]
	v_pk_mul_f32 v[16:17], v[16:17], v[252:253] op_sel_hi:[1,0]
	v_exp_f32_e64 v33, -v29
	v_exp_f32_e64 v34, -v24
	v_exp_f32_e64 v29, -v25
	v_add_f32_e32 v32, 1.0, v38
	v_add_f32_e32 v33, 1.0, v33
	v_add_f32_e32 v28, 1.0, v34
	v_add_f32_e32 v29, 1.0, v29
	v_rcp_f32_e32 v32, v32
	v_rcp_f32_e32 v33, v33
	v_rcp_f32_e32 v28, v28
	v_rcp_f32_e32 v29, v29
	v_pk_mul_f32 v[30:31], v[30:31], v[252:253] op_sel_hi:[1,0]
	v_pk_mul_f32 v[16:17], v[24:25], v[16:17]
	v_pk_mul_f32 v[20:21], v[20:21], v[32:33]
	v_exp_f32_e64 v32, -v30
	v_pk_mul_f32 v[24:25], v[16:17], v[28:29]
	v_exp_f32_e64 v17, -v31
	v_pk_mul_f32 v[26:27], v[26:27], v[252:253] op_sel_hi:[1,0]
	v_add_f32_e32 v16, 1.0, v32
	v_exp_f32_e64 v28, -v26
	v_exp_f32_e64 v29, -v27
	v_add_f32_e32 v17, 1.0, v17
	v_rcp_f32_e32 v16, v16
	v_rcp_f32_e32 v17, v17
	v_add_f32_e32 v28, 1.0, v28
	v_add_f32_e32 v29, 1.0, v29
	v_pk_mul_f32 v[22:23], v[22:23], v[252:253] op_sel_hi:[1,0]
	v_rcp_f32_e32 v28, v28
	v_rcp_f32_e32 v29, v29
	v_pk_mul_f32 v[22:23], v[30:31], v[22:23]
	v_pk_mul_f32 v[4:5], v[4:5], v[248:249] op_sel_hi:[1,0]
	v_pk_mul_f32 v[22:23], v[22:23], v[16:17]
	v_pk_mul_f32 v[16:17], v[18:19], v[252:253] op_sel_hi:[1,0]
	v_cvt_pk_bf16_f32 v18, v24, v25
	v_pk_mul_f32 v[16:17], v[26:27], v[16:17]
	v_pk_mul_f32 v[8:9], v[8:9], v[248:249] op_sel_hi:[1,0]
	v_pk_mul_f32 v[26:27], v[16:17], v[28:29]
	v_cvt_pk_bf16_f32 v16, v20, v21
	v_mad_i64_i32 v[20:21], s[20:21], v148, s43, v[112:113]
	v_cvt_pk_bf16_f32 v17, v22, v23
	v_cvt_pk_bf16_f32 v19, v26, v27
	v_lshl_add_u64 v[20:21], v[20:21], 0, v[114:115]
	v_exp_f32_e64 v22, -v12
	global_store_dwordx4 v[20:21], v[16:19], off
	v_pk_mul_f32 v[4:5], v[12:13], v[4:5]
	v_pk_mul_f32 v[0:1], v[0:1], v[248:249] op_sel_hi:[1,0]
	v_exp_f32_e64 v17, -v13
	v_exp_f32_e64 v18, -v8
	v_exp_f32_e64 v13, -v9
	v_add_f32_e32 v16, 1.0, v22
	v_add_f32_e32 v17, 1.0, v17
	v_add_f32_e32 v12, 1.0, v18
	v_add_f32_e32 v13, 1.0, v13
	v_rcp_f32_e32 v16, v16
	v_rcp_f32_e32 v17, v17
	v_rcp_f32_e32 v12, v12
	v_rcp_f32_e32 v13, v13
	v_pk_mul_f32 v[14:15], v[14:15], v[248:249] op_sel_hi:[1,0]
	v_pk_mul_f32 v[0:1], v[8:9], v[0:1]
	v_pk_mul_f32 v[4:5], v[4:5], v[16:17]
	v_exp_f32_e64 v16, -v14
	v_pk_mul_f32 v[8:9], v[0:1], v[12:13]
	v_exp_f32_e64 v1, -v15
	v_pk_mul_f32 v[10:11], v[10:11], v[248:249] op_sel_hi:[1,0]
	v_add_f32_e32 v0, 1.0, v16
	v_exp_f32_e64 v12, -v10
	v_exp_f32_e64 v13, -v11
	v_add_f32_e32 v1, 1.0, v1
	v_rcp_f32_e32 v0, v0
	v_rcp_f32_e32 v1, v1
	v_add_f32_e32 v12, 1.0, v12
	v_add_f32_e32 v13, 1.0, v13
	v_pk_mul_f32 v[6:7], v[6:7], v[248:249] op_sel_hi:[1,0]
	v_rcp_f32_e32 v12, v12
	v_rcp_f32_e32 v13, v13
	v_pk_mul_f32 v[6:7], v[14:15], v[6:7]
	s_andn2_b64 vcc, exec, s[0:1]
	v_pk_mul_f32 v[6:7], v[6:7], v[0:1]
	v_pk_mul_f32 v[0:1], v[2:3], v[248:249] op_sel_hi:[1,0]
	v_cvt_pk_bf16_f32 v2, v8, v9
	v_pk_mul_f32 v[0:1], v[10:11], v[0:1]
	s_mov_b64 s[0:1], -1
	v_pk_mul_f32 v[10:11], v[0:1], v[12:13]
	v_cvt_pk_bf16_f32 v0, v4, v5
	v_mad_i64_i32 v[4:5], s[20:21], v146, s43, v[112:113]
	v_cvt_pk_bf16_f32 v1, v6, v7
	v_cvt_pk_bf16_f32 v3, v10, v11
	v_lshl_add_u64 v[4:5], v[4:5], 0, v[114:115]
	global_store_dwordx4 v[4:5], v[0:3], off
	s_branch .Lg8_tail

;     __device__ __forceinline__ void operator()(const f32x4 (&acc_)[2][2][4][2], const pg8::Unit& u, int wr, int wc, int fr, int fq) const {
;     ...
;         const int row0 = u.pm * 256 + wr * 64 + fr, col0 = u.pn * 256 + wc * 32 + 8 * fq, lane = threadIdx.x & 63;
; #pragma unroll
;         for (int ai = 0; ai < 2; ++ai)
; #pragma unroll
;             for (int m = 0; m < 4; ++m) {
;                 const int row = row0 + ai * 128 + m * 16; float ss = 0.f;
; #pragma unroll
;                 for (int bj = 0; bj < 2; ++bj) {
;                     const size_t off = (size_t)row * D + col0 + bj * 128;
;                     const u32x4 r = *(const u32x4*)(resb + off);
;                     const f32x4 x0 = (f32x4){__builtin_bit_cast(float, r.x << 16), __builtin_bit_cast(float, r.x & 0xffff0000u), __builtin_bit_cast(float, r.y << 16), __builtin_bit_cast(float, r.y & 0xffff0000u)};
;                     const f32x4 x1 = (f32x4){__builtin_bit_cast(float, r.z << 16), __builtin_bit_cast(float, r.z & 0xffff0000u), __builtin_bit_cast(float, r.w << 16), __builtin_bit_cast(float, r.w & 0xffff0000u)};
;                     const f32x4 v0 = x0 + A[ai][bj][m][0] * 0.5f, v1 = x1 + A[ai][bj][m][1] * 0.5f;
;                     A[ai][bj][m][0] = v0; A[ai][bj][m][1] = v1;
;                     ss += ((v0[0] * v0[0] + v0[1] * v0[1]) + (v0[2] * v0[2] + v0[3] * v0[3])) + ((v1[0] * v1[0] + v1[1] * v1[1]) + (v1[2] * v1[2] + v1[3] * v1[3]));
;                 }
;                 ss += __shfl_xor(ss, 16); ss += __shfl_xor(ss, 32);
;                 if (fq == 0) __hip_atomic_store(xch + (size_t)row * 16 + u.pn * 4 + wc, ss, __ATOMIC_RELAXED, __HIP_MEMORY_SCOPE_AGENT);
.LBB0_959:
	v_lshl_add_u32 v146, s62, 8, v196
	v_ashrrev_i32_e32 v147, 31, v146
	v_lshl_or_b32 v148, s63, 8, v199
	v_lshlrev_b64 v[150:151], 11, v[146:147]
	v_ashrrev_i32_e32 v149, 31, v148
	v_lshl_add_u64 v[150:151], s[44:45], 0, v[150:151]
	v_lshl_add_u64 v[154:155], v[148:149], 1, v[150:151]
	v_mov_b64_e32 v[248:249], v[154:155]
	global_load_dwordx4 v[214:217], v[248:249], off
	global_load_dwordx4 v[218:221], v[248:249], off offset:256
	s_mov_b32 s36, 0x8000
	s_mov_b32 s37, 0
	v_lshl_add_u64 v[226:227], v[248:249], 0, s[36:37]
	global_load_dwordx4 v[222:225], v[226:227], off
	s_nop 0
	global_load_dwordx4 v[226:229], v[226:227], off offset:256
	s_mov_b32 s36, 0x10000
	s_mov_b32 s37, 0
	v_lshl_add_u64 v[234:235], v[248:249], 0, s[36:37]
	global_load_dwordx4 v[230:233], v[234:235], off
	s_nop 0
	global_load_dwordx4 v[234:237], v[234:235], off offset:256
	s_mov_b32 s36, 0x18000
	s_mov_b32 s37, 0
	v_lshl_add_u64 v[242:243], v[248:249], 0, s[36:37]
	global_load_dwordx4 v[238:241], v[242:243], off
	s_nop 0
	global_load_dwordx4 v[242:245], v[242:243], off offset:256
	v_and_b32_e32 v159, 64, v203
	v_xor_b32_e32 v158, 16, v203
	v_add_u32_e32 v166, 64, v159
	v_cmp_lt_i32_e32 vcc, v158, v166
	s_lshl_b32 s30, s63, 2
	s_ashr_i32 s31, s30, 31
	v_cndmask_b32_e32 v158, v203, v158, vcc
	v_lshlrev_b32_e32 v205, 2, v158
	s_waitcnt vmcnt(6)
	v_lshlrev_b32_e32 v158, 16, v214
	v_and_b32_e32 v159, 0xffff0000, v214
	v_lshlrev_b32_e32 v150, 16, v215
	v_and_b32_e32 v151, 0xffff0000, v215
	v_lshlrev_b32_e32 v160, 16, v216
	v_and_b32_e32 v161, 0xffff0000, v216
	v_lshlrev_b32_e32 v152, 16, v217
	v_and_b32_e32 v153, 0xffff0000, v217
	v_lshlrev_b32_e32 v162, 16, v218
	v_and_b32_e32 v163, 0xffff0000, v218
	v_lshlrev_b32_e32 v154, 16, v219
	v_and_b32_e32 v155, 0xffff0000, v219
	v_lshlrev_b32_e32 v164, 16, v220
	v_and_b32_e32 v165, 0xffff0000, v220
	v_lshlrev_b32_e32 v156, 16, v221
	v_and_b32_e32 v157, 0xffff0000, v221
	s_mov_b32 s36, 0x40000
	s_mov_b32 s37, 0
	v_lshl_add_u64 v[218:219], v[248:249], 0, s[36:37]
	global_load_dwordx4 v[214:217], v[218:219], off
	s_nop 0
	global_load_dwordx4 v[218:221], v[218:219], off offset:256
	v_pk_fma_f32 v[126:127], v[126:127], 0.5, v[150:151] op_sel_hi:[1,0,1]
	v_pk_fma_f32 v[124:125], v[124:125], 0.5, v[158:159] op_sel_hi:[1,0,1]
	v_pk_fma_f32 v[122:123], v[122:123], 0.5, v[152:153] op_sel_hi:[1,0,1]
	v_pk_fma_f32 v[120:121], v[120:121], 0.5, v[160:161] op_sel_hi:[1,0,1]
	v_pk_fma_f32 v[118:119], v[118:119], 0.5, v[154:155] op_sel_hi:[1,0,1]
	v_pk_fma_f32 v[116:117], v[116:117], 0.5, v[162:163] op_sel_hi:[1,0,1]
	v_pk_fma_f32 v[114:115], v[114:115], 0.5, v[156:157] op_sel_hi:[1,0,1]
	v_pk_fma_f32 v[112:113], v[112:113], 0.5, v[164:165] op_sel_hi:[1,0,1]
	v_mul_f32_e32 v150, v125, v125
	v_mul_f32_e32 v151, v127, v127
	v_mul_f32_e32 v152, v121, v121
	v_mul_f32_e32 v153, v123, v123
	v_mul_f32_e32 v154, v117, v117
	v_mul_f32_e32 v155, v119, v119
	v_mul_f32_e32 v156, v113, v113
	v_mul_f32_e32 v157, v115, v115
	v_fmac_f32_e32 v150, v124, v124
	v_fmac_f32_e32 v151, v126, v126
	v_fmac_f32_e32 v152, v120, v120
	v_fmac_f32_e32 v153, v122, v122
	v_fmac_f32_e32 v154, v116, v116
	v_fmac_f32_e32 v155, v118, v118
	v_fmac_f32_e32 v156, v112, v112
	v_fmac_f32_e32 v157, v114, v114
	v_add_f32_e32 v150, v150, v151
	v_add_f32_e32 v151, v152, v153
	v_add_f32_e32 v152, v154, v155
	v_add_f32_e32 v153, v156, v157
	v_add_f32_e32 v150, v150, v151
	v_add_f32_e32 v151, v152, v153
	v_add_f32_e32 v150, v150, v151
	ds_bpermute_b32 v151, v205, v150
	v_xor_b32_e32 v152, 32, v203
	v_cmp_lt_i32_e32 vcc, v152, v166
	v_lshlrev_b64 v[156:157], 6, v[146:147]
	s_waitcnt lgkmcnt(0)
	v_add_f32_e32 v150, v150, v151
	v_cndmask_b32_e32 v152, v203, v152, vcc
	v_lshlrev_b32_e32 v206, 2, v152
	ds_bpermute_b32 v151, v206, v150
	s_and_saveexec_b64 s[34:35], s[0:1]
	s_cbranch_execz .LBB0_961
	s_waitcnt lgkmcnt(0)
	v_add_f32_e32 v152, v150, v151
	v_lshl_add_u64 v[150:151], s[48:49], 0, v[156:157]
	v_lshl_add_u64 v[150:151], s[30:31], 2, v[150:151]
	s_lshl_b32 s36, s53, 2
	s_mov_b32 s37, s21
	v_lshl_add_u64 v[150:151], v[150:151], 0, s[36:37]
	global_store_dword v[150:151], v152, off sc1
.LBB0_961:
	s_or_b64 exec, exec, s[34:35]
	v_or_b32_e32 v150, 16, v146
	s_waitcnt lgkmcnt(0)
	v_ashrrev_i32_e32 v151, 31, v150
	v_lshlrev_b64 v[152:153], 11, v[150:151]
	v_lshl_add_u64 v[152:153], s[44:45], 0, v[152:153]
	v_lshl_add_u64 v[158:159], v[148:149], 1, v[152:153]
	s_waitcnt vmcnt(7)
	v_lshlrev_b32_e32 v162, 16, v222
	v_and_b32_e32 v163, 0xffff0000, v222
	v_lshlrev_b32_e32 v152, 16, v223
	v_and_b32_e32 v153, 0xffff0000, v223
	v_lshlrev_b32_e32 v164, 16, v224
	v_and_b32_e32 v165, 0xffff0000, v224
	v_lshlrev_b32_e32 v154, 16, v225
	v_and_b32_e32 v155, 0xffff0000, v225
	v_lshlrev_b32_e32 v166, 16, v226
	v_and_b32_e32 v167, 0xffff0000, v226
	v_lshlrev_b32_e32 v158, 16, v227
	v_and_b32_e32 v159, 0xffff0000, v227
	v_lshlrev_b32_e32 v168, 16, v228
	v_and_b32_e32 v169, 0xffff0000, v228
	v_lshlrev_b32_e32 v160, 16, v229
	v_and_b32_e32 v161, 0xffff0000, v229
	s_mov_b32 s36, 0x48000
	s_mov_b32 s37, 0
	v_lshl_add_u64 v[226:227], v[248:249], 0, s[36:37]
	global_load_dwordx4 v[222:225], v[226:227], off
	s_nop 0
	global_load_dwordx4 v[226:229], v[226:227], off offset:256
	v_pk_fma_f32 v[110:111], v[110:111], 0.5, v[152:153] op_sel_hi:[1,0,1]
	v_pk_fma_f32 v[108:109], v[108:109], 0.5, v[162:163] op_sel_hi:[1,0,1]
	v_pk_fma_f32 v[106:107], v[106:107], 0.5, v[154:155] op_sel_hi:[1,0,1]
	v_pk_fma_f32 v[104:105], v[104:105], 0.5, v[164:165] op_sel_hi:[1,0,1]
	v_pk_fma_f32 v[102:103], v[102:103], 0.5, v[158:159] op_sel_hi:[1,0,1]
	v_pk_fma_f32 v[100:101], v[100:101], 0.5, v[166:167] op_sel_hi:[1,0,1]
	v_pk_fma_f32 v[98:99], v[98:99], 0.5, v[160:161] op_sel_hi:[1,0,1]
	v_pk_fma_f32 v[96:97], v[96:97], 0.5, v[168:169] op_sel_hi:[1,0,1]
	v_mul_f32_e32 v152, v109, v109
	v_mul_f32_e32 v153, v111, v111
	v_mul_f32_e32 v154, v105, v105
	v_mul_f32_e32 v155, v107, v107
	v_mul_f32_e32 v158, v101, v101
	v_mul_f32_e32 v159, v103, v103
	v_mul_f32_e32 v160, v97, v97
	v_mul_f32_e32 v161, v99, v99
	v_fmac_f32_e32 v152, v108, v108
	v_fmac_f32_e32 v153, v110, v110
	v_fmac_f32_e32 v154, v104, v104
	v_fmac_f32_e32 v155, v106, v106
	v_fmac_f32_e32 v158, v100, v100
	v_fmac_f32_e32 v159, v102, v102
	v_fmac_f32_e32 v160, v96, v96
	v_fmac_f32_e32 v161, v98, v98
	v_add_f32_e32 v152, v152, v153
	v_add_f32_e32 v153, v154, v155
	v_add_f32_e32 v154, v158, v159
	v_add_f32_e32 v155, v160, v161
	v_add_f32_e32 v152, v152, v153
	v_add_f32_e32 v153, v154, v155
	v_add_f32_e32 v152, v152, v153
	ds_bpermute_b32 v153, v205, v152
	v_lshlrev_b64 v[160:161], 6, v[150:151]
	s_waitcnt lgkmcnt(0)
	v_add_f32_e32 v152, v152, v153
	ds_bpermute_b32 v153, v206, v152
	s_and_saveexec_b64 s[34:35], s[0:1]
	s_cbranch_execz .LBB0_963
	s_waitcnt lgkmcnt(0)
	v_add_f32_e32 v154, v152, v153
	v_lshl_add_u64 v[152:153], s[48:49], 0, v[160:161]
	v_lshl_add_u64 v[152:153], s[30:31], 2, v[152:153]
	s_lshl_b32 s36, s53, 2
	s_mov_b32 s37, s21
	v_lshl_add_u64 v[152:153], v[152:153], 0, s[36:37]
	global_store_dword v[152:153], v154, off sc1
;     __device__ __forceinline__ void operator()(const f32x4 (&acc_)[2][2][4][2], const pg8::Unit& u, int wr, int wc, int fr, int fq) const {
;     ...
;         for (int ai = 0; ai < 2; ++ai)
; #pragma unroll
;             for (int m = 0; m < 4; ++m) {
;                 const int row = row0 + ai * 128 + m * 16; float ss = 0.f;
; #pragma unroll
;                 for (int bj = 0; bj < 2; ++bj) {
;                     const size_t off = (size_t)row * D + col0 + bj * 128;
;                     const u32x4 r = *(const u32x4*)(resb + off);
;                     const f32x4 x0 = (f32x4){__builtin_bit_cast(float, r.x << 16), __builtin_bit_cast(float, r.x & 0xffff0000u), __builtin_bit_cast(float, r.y << 16), __builtin_bit_cast(float, r.y & 0xffff0000u)};
;                     const f32x4 x1 = (f32x4){__builtin_bit_cast(float, r.z << 16), __builtin_bit_cast(float, r.z & 0xffff0000u), __builtin_bit_cast(float, r.w << 16), __builtin_bit_cast(float, r.w & 0xffff0000u)};
;                     const f32x4 v0 = x0 + A[ai][bj][m][0] * 0.5f, v1 = x1 + A[ai][bj][m][1] * 0.5f;
;                     A[ai][bj][m][0] = v0; A[ai][bj][m][1] = v1;
;                     ss += ((v0[0] * v0[0] + v0[1] * v0[1]) + (v0[2] * v0[2] + v0[3] * v0[3])) + ((v1[0] * v1[0] + v1[1] * v1[1]) + (v1[2] * v1[2] + v1[3] * v1[3]));
;                 }
;                 ss += __shfl_xor(ss, 16); ss += __shfl_xor(ss, 32);
;                 if (fq == 0) __hip_atomic_store(xch + (size_t)row * 16 + u.pn * 4 + wc, ss, __ATOMIC_RELAXED, __HIP_MEMORY_SCOPE_AGENT);
.LBB0_963:
	s_or_b64 exec, exec, s[34:35]
	v_or_b32_e32 v152, 32, v146
	s_waitcnt lgkmcnt(0)
	v_ashrrev_i32_e32 v153, 31, v152
	v_lshlrev_b64 v[154:155], 11, v[152:153]
	v_lshl_add_u64 v[154:155], s[44:45], 0, v[154:155]
	v_lshl_add_u64 v[154:155], v[148:149], 1, v[154:155]
	s_waitcnt vmcnt(8)
	v_lshlrev_b32_e32 v154, 16, v230
	v_and_b32_e32 v155, 0xffff0000, v230
	v_lshlrev_b32_e32 v158, 16, v231
	v_and_b32_e32 v159, 0xffff0000, v231
	v_lshlrev_b32_e32 v162, 16, v232
	v_and_b32_e32 v163, 0xffff0000, v232
	v_lshlrev_b32_e32 v164, 16, v233
	v_and_b32_e32 v165, 0xffff0000, v233
	v_lshlrev_b32_e32 v170, 16, v234
	v_and_b32_e32 v171, 0xffff0000, v234
	v_lshlrev_b32_e32 v166, 16, v235
	v_and_b32_e32 v167, 0xffff0000, v235
	v_lshlrev_b32_e32 v172, 16, v236
	v_and_b32_e32 v173, 0xffff0000, v236
	v_lshlrev_b32_e32 v168, 16, v237
	v_and_b32_e32 v169, 0xffff0000, v237
	s_mov_b32 s36, 0x50000
	s_mov_b32 s37, 0
	v_lshl_add_u64 v[234:235], v[248:249], 0, s[36:37]
	global_load_dwordx4 v[230:233], v[234:235], off
	s_nop 0
	global_load_dwordx4 v[234:237], v[234:235], off offset:256
	v_pk_fma_f32 v[94:95], v[94:95], 0.5, v[158:159] op_sel_hi:[1,0,1]
	v_pk_fma_f32 v[92:93], v[92:93], 0.5, v[154:155] op_sel_hi:[1,0,1]
	v_pk_fma_f32 v[90:91], v[90:91], 0.5, v[164:165] op_sel_hi:[1,0,1]
	v_pk_fma_f32 v[88:89], v[88:89], 0.5, v[162:163] op_sel_hi:[1,0,1]
	v_pk_fma_f32 v[86:87], v[86:87], 0.5, v[166:167] op_sel_hi:[1,0,1]
	v_pk_fma_f32 v[84:85], v[84:85], 0.5, v[170:171] op_sel_hi:[1,0,1]
	v_pk_fma_f32 v[82:83], v[82:83], 0.5, v[168:169] op_sel_hi:[1,0,1]
	v_pk_fma_f32 v[80:81], v[80:81], 0.5, v[172:173] op_sel_hi:[1,0,1]
	v_mul_f32_e32 v154, v93, v93
	v_mul_f32_e32 v155, v95, v95
	v_mul_f32_e32 v158, v89, v89
	v_mul_f32_e32 v159, v91, v91
	v_mul_f32_e32 v162, v85, v85
	v_mul_f32_e32 v163, v87, v87
	v_mul_f32_e32 v164, v81, v81
	v_mul_f32_e32 v165, v83, v83
	v_fmac_f32_e32 v154, v92, v92
	v_fmac_f32_e32 v155, v94, v94
	v_fmac_f32_e32 v158, v88, v88
	v_fmac_f32_e32 v159, v90, v90
	v_fmac_f32_e32 v162, v84, v84
	v_fmac_f32_e32 v163, v86, v86
	v_fmac_f32_e32 v164, v80, v80
	v_fmac_f32_e32 v165, v82, v82
	v_add_f32_e32 v154, v154, v155
	v_add_f32_e32 v155, v158, v159
	v_add_f32_e32 v158, v162, v163
	v_add_f32_e32 v159, v164, v165
	v_add_f32_e32 v154, v154, v155
	v_add_f32_e32 v155, v158, v159
	v_add_f32_e32 v154, v154, v155
	ds_bpermute_b32 v155, v205, v154
	v_lshlrev_b64 v[164:165], 6, v[152:153]
	s_waitcnt lgkmcnt(0)
	v_add_f32_e32 v154, v154, v155
	ds_bpermute_b32 v155, v206, v154
	s_and_saveexec_b64 s[34:35], s[0:1]
	s_cbranch_execz .LBB0_965
	s_waitcnt lgkmcnt(0)
	v_add_f32_e32 v158, v154, v155
	v_lshl_add_u64 v[154:155], s[48:49], 0, v[164:165]
	v_lshl_add_u64 v[154:155], s[30:31], 2, v[154:155]
	s_lshl_b32 s36, s53, 2
	s_mov_b32 s37, s21
	v_lshl_add_u64 v[154:155], v[154:155], 0, s[36:37]
	global_store_dword v[154:155], v158, off sc1
.LBB0_965:
	s_or_b64 exec, exec, s[34:35]
	v_or_b32_e32 v154, 48, v146
	s_waitcnt lgkmcnt(0)
	v_ashrrev_i32_e32 v155, 31, v154
	v_lshlrev_b64 v[158:159], 11, v[154:155]
	v_lshl_add_u64 v[158:159], s[44:45], 0, v[158:159]
	v_lshl_add_u64 v[158:159], v[148:149], 1, v[158:159]
	s_waitcnt vmcnt(9)
	v_lshlrev_b32_e32 v158, 16, v238
	v_and_b32_e32 v159, 0xffff0000, v238
	v_lshlrev_b32_e32 v162, 16, v239
	v_and_b32_e32 v163, 0xffff0000, v239
	v_lshlrev_b32_e32 v166, 16, v240
	v_and_b32_e32 v167, 0xffff0000, v240
	v_lshlrev_b32_e32 v168, 16, v241
	v_and_b32_e32 v169, 0xffff0000, v241
	v_lshlrev_b32_e32 v174, 16, v242
	v_and_b32_e32 v175, 0xffff0000, v242
	v_lshlrev_b32_e32 v170, 16, v243
	v_and_b32_e32 v171, 0xffff0000, v243
	v_lshlrev_b32_e32 v176, 16, v244
	v_and_b32_e32 v177, 0xffff0000, v244
	v_lshlrev_b32_e32 v172, 16, v245
	v_and_b32_e32 v173, 0xffff0000, v245
	s_mov_b32 s36, 0x58000
	s_mov_b32 s37, 0
	v_lshl_add_u64 v[242:243], v[248:249], 0, s[36:37]
	global_load_dwordx4 v[238:241], v[242:243], off
	s_nop 0
	global_load_dwordx4 v[242:245], v[242:243], off offset:256
	v_pk_fma_f32 v[78:79], v[78:79], 0.5, v[162:163] op_sel_hi:[1,0,1]
	v_pk_fma_f32 v[76:77], v[76:77], 0.5, v[158:159] op_sel_hi:[1,0,1]
	v_pk_fma_f32 v[74:75], v[74:75], 0.5, v[168:169] op_sel_hi:[1,0,1]
	v_pk_fma_f32 v[72:73], v[72:73], 0.5, v[166:167] op_sel_hi:[1,0,1]
	v_pk_fma_f32 v[70:71], v[70:71], 0.5, v[170:171] op_sel_hi:[1,0,1]
	v_pk_fma_f32 v[68:69], v[68:69], 0.5, v[174:175] op_sel_hi:[1,0,1]
	v_pk_fma_f32 v[66:67], v[66:67], 0.5, v[172:173] op_sel_hi:[1,0,1]
	v_pk_fma_f32 v[64:65], v[64:65], 0.5, v[176:177] op_sel_hi:[1,0,1]
	v_mul_f32_e32 v158, v77, v77
	v_mul_f32_e32 v159, v79, v79
	v_mul_f32_e32 v162, v73, v73
	v_mul_f32_e32 v163, v75, v75
	v_mul_f32_e32 v166, v69, v69
	v_mul_f32_e32 v167, v71, v71
	v_mul_f32_e32 v168, v65, v65
	v_mul_f32_e32 v169, v67, v67
	v_fmac_f32_e32 v158, v76, v76
	v_fmac_f32_e32 v159, v78, v78
	v_fmac_f32_e32 v162, v72, v72
	v_fmac_f32_e32 v163, v74, v74
	v_fmac_f32_e32 v166, v68, v68
	v_fmac_f32_e32 v167, v70, v70
	v_fmac_f32_e32 v168, v64, v64
	v_fmac_f32_e32 v169, v66, v66
	v_add_f32_e32 v158, v158, v159
	v_add_f32_e32 v159, v162, v163
	v_add_f32_e32 v162, v166, v167
	v_add_f32_e32 v163, v168, v169
	v_add_f32_e32 v158, v158, v159
	v_add_f32_e32 v159, v162, v163
	v_add_f32_e32 v158, v158, v159
	ds_bpermute_b32 v159, v205, v158
	v_lshlrev_b64 v[168:169], 6, v[154:155]
	s_waitcnt lgkmcnt(0)
	v_add_f32_e32 v158, v158, v159
	ds_bpermute_b32 v159, v206, v158
	s_and_saveexec_b64 s[34:35], s[0:1]
	s_cbranch_execz .LBB0_967
	s_waitcnt lgkmcnt(0)
	v_add_f32_e32 v162, v158, v159
	v_lshl_add_u64 v[158:159], s[48:49], 0, v[168:169]
	v_lshl_add_u64 v[158:159], s[30:31], 2, v[158:159]
	s_lshl_b32 s36, s53, 2
	s_mov_b32 s37, s21
	v_lshl_add_u64 v[158:159], v[158:159], 0, s[36:37]
	global_store_dword v[158:159], v162, off sc1
;     __device__ __forceinline__ void operator()(const f32x4 (&acc_)[2][2][4][2], const pg8::Unit& u, int wr, int wc, int fr, int fq) const {
;     ...
;         for (int ai = 0; ai < 2; ++ai)
; #pragma unroll
;             for (int m = 0; m < 4; ++m) {
;                 const int row = row0 + ai * 128 + m * 16; float ss = 0.f;
; #pragma unroll
;                 for (int bj = 0; bj < 2; ++bj) {
;                     const size_t off = (size_t)row * D + col0 + bj * 128;
;                     const u32x4 r = *(const u32x4*)(resb + off);
;                     const f32x4 x0 = (f32x4){__builtin_bit_cast(float, r.x << 16), __builtin_bit_cast(float, r.x & 0xffff0000u), __builtin_bit_cast(float, r.y << 16), __builtin_bit_cast(float, r.y & 0xffff0000u)};
;                     const f32x4 x1 = (f32x4){__builtin_bit_cast(float, r.z << 16), __builtin_bit_cast(float, r.z & 0xffff0000u), __builtin_bit_cast(float, r.w << 16), __builtin_bit_cast(float, r.w & 0xffff0000u)};
;                     const f32x4 v0 = x0 + A[ai][bj][m][0] * 0.5f, v1 = x1 + A[ai][bj][m][1] * 0.5f;
;                     A[ai][bj][m][0] = v0; A[ai][bj][m][1] = v1;
;                     ss += ((v0[0] * v0[0] + v0[1] * v0[1]) + (v0[2] * v0[2] + v0[3] * v0[3])) + ((v1[0] * v1[0] + v1[1] * v1[1]) + (v1[2] * v1[2] + v1[3] * v1[3]));
;                 }
;                 ss += __shfl_xor(ss, 16); ss += __shfl_xor(ss, 32);
;                 if (fq == 0) __hip_atomic_store(xch + (size_t)row * 16 + u.pn * 4 + wc, ss, __ATOMIC_RELAXED, __HIP_MEMORY_SCOPE_AGENT);
.LBB0_967:
	s_or_b64 exec, exec, s[34:35]
	v_add_u32_e32 v158, 0x80, v146
	s_waitcnt lgkmcnt(0)
	v_ashrrev_i32_e32 v159, 31, v158
	v_lshlrev_b64 v[162:163], 11, v[158:159]
	v_lshl_add_u64 v[162:163], s[44:45], 0, v[162:163]
	v_lshl_add_u64 v[162:163], v[148:149], 1, v[162:163]
	v_lshlrev_b64 v[186:187], 6, v[158:159]
	s_waitcnt vmcnt(10)
	v_lshlrev_b32_e32 v162, 16, v214
	v_and_b32_e32 v163, 0xffff0000, v214
	v_lshlrev_b32_e32 v166, 16, v215
	v_and_b32_e32 v167, 0xffff0000, v215
	v_lshlrev_b32_e32 v170, 16, v216
	v_and_b32_e32 v171, 0xffff0000, v216
	v_lshlrev_b32_e32 v172, 16, v217
	v_and_b32_e32 v173, 0xffff0000, v217
	v_lshlrev_b32_e32 v178, 16, v218
	v_and_b32_e32 v179, 0xffff0000, v218
	v_lshlrev_b32_e32 v174, 16, v219
	v_and_b32_e32 v175, 0xffff0000, v219
	v_lshlrev_b32_e32 v180, 16, v220
	v_and_b32_e32 v181, 0xffff0000, v220
	v_lshlrev_b32_e32 v176, 16, v221
	v_and_b32_e32 v177, 0xffff0000, v221
	v_pk_fma_f32 v[62:63], v[62:63], 0.5, v[166:167] op_sel_hi:[1,0,1]
	v_pk_fma_f32 v[60:61], v[60:61], 0.5, v[162:163] op_sel_hi:[1,0,1]
	v_pk_fma_f32 v[58:59], v[58:59], 0.5, v[172:173] op_sel_hi:[1,0,1]
	v_pk_fma_f32 v[56:57], v[56:57], 0.5, v[170:171] op_sel_hi:[1,0,1]
	v_pk_fma_f32 v[54:55], v[54:55], 0.5, v[174:175] op_sel_hi:[1,0,1]
	v_pk_fma_f32 v[52:53], v[52:53], 0.5, v[178:179] op_sel_hi:[1,0,1]
	v_pk_fma_f32 v[50:51], v[50:51], 0.5, v[176:177] op_sel_hi:[1,0,1]
	v_pk_fma_f32 v[48:49], v[48:49], 0.5, v[180:181] op_sel_hi:[1,0,1]
	v_mul_f32_e32 v162, v61, v61
	v_mul_f32_e32 v163, v63, v63
	v_mul_f32_e32 v166, v57, v57
	v_mul_f32_e32 v167, v59, v59
	v_mul_f32_e32 v170, v53, v53
	v_mul_f32_e32 v171, v55, v55
	v_mul_f32_e32 v172, v49, v49
	v_mul_f32_e32 v173, v51, v51
	v_fmac_f32_e32 v162, v60, v60
	v_fmac_f32_e32 v163, v62, v62
	v_fmac_f32_e32 v166, v56, v56
	v_fmac_f32_e32 v167, v58, v58
	v_fmac_f32_e32 v170, v52, v52
	v_fmac_f32_e32 v171, v54, v54
	v_fmac_f32_e32 v172, v48, v48
	v_fmac_f32_e32 v173, v50, v50
	v_add_f32_e32 v162, v162, v163
	v_add_f32_e32 v163, v166, v167
	v_add_f32_e32 v166, v170, v171
	v_add_f32_e32 v167, v172, v173
	v_add_f32_e32 v162, v162, v163
	v_add_f32_e32 v163, v166, v167
	v_add_f32_e32 v162, v162, v163
	ds_bpermute_b32 v163, v205, v162
	s_waitcnt lgkmcnt(0)
	v_add_f32_e32 v162, v162, v163
	ds_bpermute_b32 v163, v206, v162
	s_and_saveexec_b64 s[34:35], s[0:1]
	s_cbranch_execz .LBB0_969
	s_waitcnt lgkmcnt(0)
	v_add_f32_e32 v166, v162, v163
	v_lshl_add_u64 v[162:163], s[48:49], 0, v[186:187]
	v_lshl_add_u64 v[162:163], s[30:31], 2, v[162:163]
	s_lshl_b32 s36, s53, 2
	s_mov_b32 s37, s21
	v_lshl_add_u64 v[162:163], v[162:163], 0, s[36:37]
	global_store_dword v[162:163], v166, off sc1
.LBB0_969:
	s_or_b64 exec, exec, s[34:35]
	v_add_u32_e32 v162, 0x90, v146
	s_waitcnt lgkmcnt(0)
	v_ashrrev_i32_e32 v163, 31, v162
	v_lshlrev_b64 v[166:167], 11, v[162:163]
	v_lshl_add_u64 v[166:167], s[44:45], 0, v[166:167]
	v_lshl_add_u64 v[166:167], v[148:149], 1, v[166:167]
	v_lshlrev_b64 v[190:191], 6, v[162:163]
	s_waitcnt vmcnt(8)
	v_lshlrev_b32_e32 v166, 16, v222
	v_and_b32_e32 v167, 0xffff0000, v222
	v_lshlrev_b32_e32 v170, 16, v223
	v_and_b32_e32 v171, 0xffff0000, v223
	v_lshlrev_b32_e32 v178, 16, v224
	v_and_b32_e32 v179, 0xffff0000, v224
	v_lshlrev_b32_e32 v172, 16, v225
	v_and_b32_e32 v173, 0xffff0000, v225
	v_lshlrev_b32_e32 v180, 16, v226
	v_and_b32_e32 v181, 0xffff0000, v226
	v_lshlrev_b32_e32 v174, 16, v227
	v_and_b32_e32 v175, 0xffff0000, v227
	v_lshlrev_b32_e32 v182, 16, v228
	v_and_b32_e32 v183, 0xffff0000, v228
	v_lshlrev_b32_e32 v176, 16, v229
	v_and_b32_e32 v177, 0xffff0000, v229
	v_pk_fma_f32 v[46:47], v[46:47], 0.5, v[170:171] op_sel_hi:[1,0,1]
	v_pk_fma_f32 v[44:45], v[44:45], 0.5, v[166:167] op_sel_hi:[1,0,1]
	v_pk_fma_f32 v[42:43], v[42:43], 0.5, v[172:173] op_sel_hi:[1,0,1]
	v_pk_fma_f32 v[40:41], v[40:41], 0.5, v[178:179] op_sel_hi:[1,0,1]
	v_pk_fma_f32 v[38:39], v[38:39], 0.5, v[174:175] op_sel_hi:[1,0,1]
	v_pk_fma_f32 v[36:37], v[36:37], 0.5, v[180:181] op_sel_hi:[1,0,1]
	v_pk_fma_f32 v[34:35], v[34:35], 0.5, v[176:177] op_sel_hi:[1,0,1]
	v_pk_fma_f32 v[32:33], v[32:33], 0.5, v[182:183] op_sel_hi:[1,0,1]
	v_mul_f32_e32 v166, v45, v45
	v_mul_f32_e32 v167, v47, v47
	v_mul_f32_e32 v170, v41, v41
	v_mul_f32_e32 v171, v43, v43
	v_mul_f32_e32 v172, v37, v37
	v_mul_f32_e32 v173, v39, v39
	v_mul_f32_e32 v174, v33, v33
	v_mul_f32_e32 v175, v35, v35
	v_fmac_f32_e32 v166, v44, v44
	v_fmac_f32_e32 v167, v46, v46
	v_fmac_f32_e32 v170, v40, v40
	v_fmac_f32_e32 v171, v42, v42
	v_fmac_f32_e32 v172, v36, v36
	v_fmac_f32_e32 v173, v38, v38
	v_fmac_f32_e32 v174, v32, v32
	v_fmac_f32_e32 v175, v34, v34
	v_add_f32_e32 v166, v166, v167
	v_add_f32_e32 v167, v170, v171
	v_add_f32_e32 v170, v172, v173
	v_add_f32_e32 v171, v174, v175
	v_add_f32_e32 v166, v166, v167
	v_add_f32_e32 v167, v170, v171
	v_add_f32_e32 v166, v166, v167
	ds_bpermute_b32 v167, v205, v166
	s_waitcnt lgkmcnt(0)
	v_add_f32_e32 v166, v166, v167
	ds_bpermute_b32 v167, v206, v166
	s_and_saveexec_b64 s[34:35], s[0:1]
	s_cbranch_execz .LBB0_971
	s_waitcnt lgkmcnt(0)
	v_add_f32_e32 v170, v166, v167
	v_lshl_add_u64 v[166:167], s[48:49], 0, v[190:191]
	v_lshl_add_u64 v[166:167], s[30:31], 2, v[166:167]
	s_lshl_b32 s36, s53, 2
	s_mov_b32 s37, s21
	v_lshl_add_u64 v[166:167], v[166:167], 0, s[36:37]
	global_store_dword v[166:167], v170, off sc1
;     __device__ __forceinline__ void operator()(const f32x4 (&acc_)[2][2][4][2], const pg8::Unit& u, int wr, int wc, int fr, int fq) const {
;     ...
;         for (int ai = 0; ai < 2; ++ai)
; #pragma unroll
;             for (int m = 0; m < 4; ++m) {
;                 const int row = row0 + ai * 128 + m * 16; float ss = 0.f;
; #pragma unroll
;                 for (int bj = 0; bj < 2; ++bj) {
;                     const size_t off = (size_t)row * D + col0 + bj * 128;
;                     const u32x4 r = *(const u32x4*)(resb + off);
;                     const f32x4 x0 = (f32x4){__builtin_bit_cast(float, r.x << 16), __builtin_bit_cast(float, r.x & 0xffff0000u), __builtin_bit_cast(float, r.y << 16), __builtin_bit_cast(float, r.y & 0xffff0000u)};
;                     const f32x4 x1 = (f32x4){__builtin_bit_cast(float, r.z << 16), __builtin_bit_cast(float, r.z & 0xffff0000u), __builtin_bit_cast(float, r.w << 16), __builtin_bit_cast(float, r.w & 0xffff0000u)};
;                     const f32x4 v0 = x0 + A[ai][bj][m][0] * 0.5f, v1 = x1 + A[ai][bj][m][1] * 0.5f;
;                     A[ai][bj][m][0] = v0; A[ai][bj][m][1] = v1;
;                     ss += ((v0[0] * v0[0] + v0[1] * v0[1]) + (v0[2] * v0[2] + v0[3] * v0[3])) + ((v1[0] * v1[0] + v1[1] * v1[1]) + (v1[2] * v1[2] + v1[3] * v1[3]));
;                 }
;                 ss += __shfl_xor(ss, 16); ss += __shfl_xor(ss, 32);
;                 if (fq == 0) __hip_atomic_store(xch + (size_t)row * 16 + u.pn * 4 + wc, ss, __ATOMIC_RELAXED, __HIP_MEMORY_SCOPE_AGENT);
.LBB0_971:
	s_or_b64 exec, exec, s[34:35]
	v_add_u32_e32 v166, 0xa0, v146
	s_waitcnt lgkmcnt(0)
	v_ashrrev_i32_e32 v167, 31, v166
	v_lshlrev_b64 v[170:171], 11, v[166:167]
	v_lshl_add_u64 v[170:171], s[44:45], 0, v[170:171]
	v_lshl_add_u64 v[174:175], v[148:149], 1, v[170:171]
	v_lshlrev_b64 v[192:193], 6, v[166:167]
	s_waitcnt vmcnt(6)
	v_lshlrev_b32_e32 v178, 16, v230
	v_and_b32_e32 v179, 0xffff0000, v230
	v_lshlrev_b32_e32 v170, 16, v231
	v_and_b32_e32 v171, 0xffff0000, v231
	v_lshlrev_b32_e32 v180, 16, v232
	v_and_b32_e32 v181, 0xffff0000, v232
	v_lshlrev_b32_e32 v172, 16, v233
	v_and_b32_e32 v173, 0xffff0000, v233
	v_lshlrev_b32_e32 v182, 16, v234
	v_and_b32_e32 v183, 0xffff0000, v234
	v_lshlrev_b32_e32 v174, 16, v235
	v_and_b32_e32 v175, 0xffff0000, v235
	v_lshlrev_b32_e32 v184, 16, v236
	v_and_b32_e32 v185, 0xffff0000, v236
	v_lshlrev_b32_e32 v176, 16, v237
	v_and_b32_e32 v177, 0xffff0000, v237
	v_pk_fma_f32 v[30:31], v[30:31], 0.5, v[170:171] op_sel_hi:[1,0,1]
	v_pk_fma_f32 v[28:29], v[28:29], 0.5, v[178:179] op_sel_hi:[1,0,1]
	v_pk_fma_f32 v[26:27], v[26:27], 0.5, v[172:173] op_sel_hi:[1,0,1]
	v_pk_fma_f32 v[24:25], v[24:25], 0.5, v[180:181] op_sel_hi:[1,0,1]
	v_pk_fma_f32 v[22:23], v[22:23], 0.5, v[174:175] op_sel_hi:[1,0,1]
	v_pk_fma_f32 v[20:21], v[20:21], 0.5, v[182:183] op_sel_hi:[1,0,1]
	v_pk_fma_f32 v[18:19], v[18:19], 0.5, v[176:177] op_sel_hi:[1,0,1]
	v_pk_fma_f32 v[16:17], v[16:17], 0.5, v[184:185] op_sel_hi:[1,0,1]
	v_mul_f32_e32 v170, v29, v29
	v_mul_f32_e32 v171, v31, v31
	v_mul_f32_e32 v172, v25, v25
	v_mul_f32_e32 v173, v27, v27
	v_mul_f32_e32 v174, v21, v21
	v_mul_f32_e32 v175, v23, v23
	v_mul_f32_e32 v176, v17, v17
	v_mul_f32_e32 v177, v19, v19
	v_fmac_f32_e32 v170, v28, v28
	v_fmac_f32_e32 v171, v30, v30
	v_fmac_f32_e32 v172, v24, v24
	v_fmac_f32_e32 v173, v26, v26
	v_fmac_f32_e32 v174, v20, v20
	v_fmac_f32_e32 v175, v22, v22
	v_fmac_f32_e32 v176, v16, v16
	v_fmac_f32_e32 v177, v18, v18
	v_add_f32_e32 v170, v170, v171
	v_add_f32_e32 v171, v172, v173
	v_add_f32_e32 v172, v174, v175
	v_add_f32_e32 v173, v176, v177
	v_add_f32_e32 v170, v170, v171
	v_add_f32_e32 v171, v172, v173
	v_add_f32_e32 v170, v170, v171
	ds_bpermute_b32 v171, v205, v170
	s_waitcnt lgkmcnt(0)
	v_add_f32_e32 v170, v170, v171
	ds_bpermute_b32 v171, v206, v170
	s_and_saveexec_b64 s[34:35], s[0:1]
	s_cbranch_execz .LBB0_973
	s_waitcnt lgkmcnt(0)
	v_add_f32_e32 v172, v170, v171
	v_lshl_add_u64 v[170:171], s[48:49], 0, v[192:193]
	v_lshl_add_u64 v[170:171], s[30:31], 2, v[170:171]
	s_lshl_b32 s36, s53, 2
	s_mov_b32 s37, s21
	v_lshl_add_u64 v[170:171], v[170:171], 0, s[36:37]
	global_store_dword v[170:171], v172, off sc1
.LBB0_973:
	s_or_b64 exec, exec, s[34:35]
	v_add_u32_e32 v170, 0xb0, v146
	s_waitcnt lgkmcnt(0)
	v_ashrrev_i32_e32 v171, 31, v170
	v_lshlrev_b64 v[172:173], 11, v[170:171]
	v_lshl_add_u64 v[172:173], s[44:45], 0, v[172:173]
	v_lshl_add_u64 v[176:177], v[148:149], 1, v[172:173]
	s_waitcnt vmcnt(4)
	v_lshlrev_b32_e32 v180, 16, v238
	v_and_b32_e32 v181, 0xffff0000, v238
	v_lshlrev_b32_e32 v172, 16, v239
	v_and_b32_e32 v173, 0xffff0000, v239
	v_lshlrev_b32_e32 v182, 16, v240
	v_and_b32_e32 v183, 0xffff0000, v240
	v_lshlrev_b32_e32 v184, 16, v241
	v_and_b32_e32 v185, 0xffff0000, v241
	v_lshlrev_b32_e32 v188, 16, v242
	v_and_b32_e32 v189, 0xffff0000, v242
	v_lshlrev_b32_e32 v194, 16, v243
	v_and_b32_e32 v195, 0xffff0000, v243
	v_lshlrev_b32_e32 v208, 16, v244
	v_and_b32_e32 v209, 0xffff0000, v244
	v_lshlrev_b32_e32 v210, 16, v245
	v_and_b32_e32 v211, 0xffff0000, v245
	v_pk_fma_f32 v[174:175], v[14:15], 0.5, v[172:173] op_sel_hi:[1,0,1]
	v_pk_fma_f32 v[178:179], v[12:13], 0.5, v[180:181] op_sel_hi:[1,0,1]
	v_pk_fma_f32 v[172:173], v[10:11], 0.5, v[184:185] op_sel_hi:[1,0,1]
	v_pk_fma_f32 v[176:177], v[8:9], 0.5, v[182:183] op_sel_hi:[1,0,1]
	v_pk_fma_f32 v[180:181], v[6:7], 0.5, v[194:195] op_sel_hi:[1,0,1]
	v_pk_fma_f32 v[182:183], v[4:5], 0.5, v[188:189] op_sel_hi:[1,0,1]
	v_pk_fma_f32 v[184:185], v[2:3], 0.5, v[210:211] op_sel_hi:[1,0,1]
	v_pk_fma_f32 v[188:189], v[0:1], 0.5, v[208:209] op_sel_hi:[1,0,1]
	v_mul_f32_e32 v0, v179, v179
	v_mul_f32_e32 v1, v175, v175
	v_mul_f32_e32 v2, v177, v177
	v_mul_f32_e32 v3, v173, v173
	v_mul_f32_e32 v4, v183, v183
	v_mul_f32_e32 v5, v181, v181
	v_mul_f32_e32 v6, v189, v189
	v_mul_f32_e32 v7, v185, v185
	v_fmac_f32_e32 v0, v178, v178
	v_fmac_f32_e32 v1, v174, v174
	v_fmac_f32_e32 v2, v176, v176
	v_fmac_f32_e32 v3, v172, v172
	v_fmac_f32_e32 v4, v182, v182
	v_fmac_f32_e32 v5, v180, v180
	v_fmac_f32_e32 v6, v188, v188
	v_fmac_f32_e32 v7, v184, v184
	v_add_f32_e32 v0, v0, v1
	v_add_f32_e32 v1, v2, v3
	v_add_f32_e32 v2, v4, v5
	v_add_f32_e32 v3, v6, v7
	v_add_f32_e32 v0, v0, v1
	v_add_f32_e32 v1, v2, v3
	v_add_f32_e32 v0, v0, v1
	ds_bpermute_b32 v1, v205, v0
	v_lshlrev_b64 v[194:195], 6, v[170:171]
	s_waitcnt lgkmcnt(0)
	v_add_f32_e32 v0, v0, v1
	ds_bpermute_b32 v1, v206, v0
	s_and_saveexec_b64 s[34:35], s[0:1]
	s_cbranch_execz .LBB0_975
	s_waitcnt lgkmcnt(0)
	v_add_f32_e32 v2, v0, v1
	v_lshl_add_u64 v[0:1], s[48:49], 0, v[194:195]
	v_lshl_add_u64 v[0:1], s[30:31], 2, v[0:1]
	s_lshl_b32 s30, s53, 2
	s_mov_b32 s31, s21
	v_lshl_add_u64 v[0:1], v[0:1], 0, s[30:31]
	global_store_dword v[0:1], v2, off sc1

;     __device__ __forceinline__ void operator()(const f32x4 (&acc_)[2][2][4][2], const pg8::Unit& u, int wr, int wc, int fr, int fq) const {
;     ...
;         __builtin_amdgcn_fence(__ATOMIC_ACQUIRE, "agent");
;         asm volatile("s_waitcnt vmcnt(0)" ::: "memory");
;         f32x4 g[2][2];
; #pragma unroll
;         for (int bj = 0; bj < 2; ++bj) { g[bj][0] = *(const f32x4*)(gain + col0 + bj * 128); g[bj][1] = *(const f32x4*)(gain + col0 + bj * 128 + 4); }
; #pragma unroll
;         for (int ai = 0; ai < 2; ++ai)
; #pragma unroll
;             for (int m = 0; m < 4; ++m) {
;                 const int row = row0 + ai * 128 + m * 16; const float* xp = xch + (size_t)row * 16 + 4 * fq;
;                 float s = (__hip_atomic_load(xp + 0, __ATOMIC_RELAXED, __HIP_MEMORY_SCOPE_AGENT) + __hip_atomic_load(xp + 1, __ATOMIC_RELAXED, __HIP_MEMORY_SCOPE_AGENT))
;                         + (__hip_atomic_load(xp + 2, __ATOMIC_RELAXED, __HIP_MEMORY_SCOPE_AGENT) + __hip_atomic_load(xp + 3, __ATOMIC_RELAXED, __HIP_MEMORY_SCOPE_AGENT));
;                 s += __shfl_xor(s, 16); s += __shfl_xor(s, 32);
;                 const float rstd = __builtin_amdgcn_rsqf(s * (1.0f / 1024.0f) + EPS);
; #pragma unroll
;                 for (int bj = 0; bj < 2; ++bj) { const size_t off = (size_t)row * D + col0 + bj * 128;
;                     *(f32x4*)(out + off) = A[ai][bj][m][0] * rstd * g[bj][0]; *(f32x4*)(out + off + 4) = A[ai][bj][m][1] * rstd * g[bj][1]; }
;             }
.LBB0_982:
	v_lshlrev_b64 v[148:149], 2, v[148:149]
	buffer_inv sc1
	s_waitcnt vmcnt(0)
	v_lshl_add_u64 v[8:9], s[24:25], 0, v[148:149]
	v_lshl_add_u64 v[156:157], v[136:137], 0, v[156:157]
	global_load_dwordx4 v[4:7], v[8:9], off offset:16
	global_load_dwordx4 v[12:15], v[8:9], off
	global_load_dwordx4 v[0:3], v[8:9], off offset:528
	s_nop 0
	global_load_dwordx4 v[8:11], v[8:9], off offset:512
	s_nop 0
	global_load_dword v208, v[156:157], off sc1
	global_load_dword v210, v[156:157], off offset:4 sc1
	global_load_dword v209, v[156:157], off offset:8 sc1
	global_load_dword v211, v[156:157], off offset:12 sc1
	v_lshlrev_b64 v[146:147], 12, v[146:147]
	v_lshl_add_u64 v[146:147], s[8:9], 0, v[146:147]
	v_lshl_add_u64 v[146:147], v[146:147], 0, v[148:149]
	v_lshl_add_u64 v[160:161], v[136:137], 0, v[160:161]
	global_load_dword v214, v[160:161], off sc1
	global_load_dword v216, v[160:161], off offset:4 sc1
	global_load_dword v215, v[160:161], off offset:8 sc1
	global_load_dword v217, v[160:161], off offset:12 sc1
	v_lshl_add_u64 v[242:243], v[136:137], 0, v[164:165]
	global_load_dword v218, v[242:243], off sc1
	global_load_dword v220, v[242:243], off offset:4 sc1
	global_load_dword v219, v[242:243], off offset:8 sc1
	global_load_dword v221, v[242:243], off offset:12 sc1
	v_lshl_add_u64 v[244:245], v[136:137], 0, v[168:169]
	global_load_dword v222, v[244:245], off sc1
	global_load_dword v224, v[244:245], off offset:4 sc1
	global_load_dword v223, v[244:245], off offset:8 sc1
	global_load_dword v225, v[244:245], off offset:12 sc1
	v_lshl_add_u64 v[242:243], v[136:137], 0, v[186:187]
	global_load_dword v226, v[242:243], off sc1
	global_load_dword v228, v[242:243], off offset:4 sc1
	global_load_dword v227, v[242:243], off offset:8 sc1
	global_load_dword v229, v[242:243], off offset:12 sc1
	v_lshl_add_u64 v[244:245], v[136:137], 0, v[190:191]
	global_load_dword v230, v[244:245], off sc1
	global_load_dword v232, v[244:245], off offset:4 sc1
	global_load_dword v231, v[244:245], off offset:8 sc1
	global_load_dword v233, v[244:245], off offset:12 sc1
	v_lshl_add_u64 v[242:243], v[136:137], 0, v[192:193]
	global_load_dword v234, v[242:243], off sc1
	global_load_dword v236, v[242:243], off offset:4 sc1
	global_load_dword v235, v[242:243], off offset:8 sc1
	global_load_dword v237, v[242:243], off offset:12 sc1
	v_lshl_add_u64 v[244:245], v[136:137], 0, v[194:195]
	global_load_dword v238, v[244:245], off sc1
	global_load_dword v240, v[244:245], off offset:4 sc1
	global_load_dword v239, v[244:245], off offset:8 sc1
	global_load_dword v241, v[244:245], off offset:12 sc1
	s_and_b64 vcc, exec, s[4:5]
	s_mov_b64 s[4:5], -1
	s_waitcnt vmcnt(0)
	v_pk_add_f32 v[156:157], v[208:209], v[210:211]
	s_nop 0
	v_add_f32_e32 v156, v156, v157
	ds_bpermute_b32 v157, v205, v156
	s_waitcnt lgkmcnt(0)
	v_add_f32_e32 v156, v156, v157
	ds_bpermute_b32 v157, v206, v156
	s_waitcnt lgkmcnt(0)
	v_add_f32_e32 v156, v156, v157
	v_fmamk_f32 v156, v156, 0x3a800000, v204
	v_rsq_f32_e32 v156, v156
	s_nop 0
	v_pk_mul_f32 v[124:125], v[124:125], v[156:157] op_sel_hi:[1,0]
	v_pk_mul_f32 v[126:127], v[126:127], v[156:157] op_sel_hi:[1,0]
	v_pk_mul_f32 v[120:121], v[120:121], v[156:157] op_sel_hi:[1,0]
	v_pk_mul_f32 v[122:123], v[122:123], v[156:157] op_sel_hi:[1,0]
	v_pk_mul_f32 v[208:209], v[116:117], v[156:157] op_sel_hi:[1,0]
	v_pk_mul_f32 v[210:211], v[118:119], v[156:157] op_sel_hi:[1,0]
	v_pk_mul_f32 v[212:213], v[112:113], v[156:157] op_sel_hi:[1,0]
	v_pk_mul_f32 v[156:157], v[114:115], v[156:157] op_sel_hi:[1,0]
	v_pk_mul_f32 v[114:115], v[14:15], v[126:127]
	v_pk_mul_f32 v[112:113], v[12:13], v[124:125]
	v_pk_mul_f32 v[118:119], v[6:7], v[122:123]
	v_pk_mul_f32 v[116:117], v[4:5], v[120:121]
	v_pk_mul_f32 v[122:123], v[10:11], v[210:211]
	v_pk_mul_f32 v[120:121], v[8:9], v[208:209]
	v_pk_mul_f32 v[126:127], v[2:3], v[156:157]
	v_pk_mul_f32 v[124:125], v[0:1], v[212:213]
	global_store_dwordx4 v[146:147], v[112:115], off
	global_store_dwordx4 v[146:147], v[116:119], off offset:16
	global_store_dwordx4 v[146:147], v[120:123], off offset:512
	global_store_dwordx4 v[146:147], v[124:127], off offset:528
	v_pk_add_f32 v[112:113], v[214:215], v[216:217]
	s_nop 0
	v_add_f32_e32 v112, v112, v113
	ds_bpermute_b32 v113, v205, v112
	s_waitcnt lgkmcnt(0)
	v_add_f32_e32 v114, v112, v113
	ds_bpermute_b32 v115, v206, v114
	v_lshlrev_b64 v[112:113], 12, v[150:151]
	v_lshl_add_u64 v[112:113], s[8:9], 0, v[112:113]
	v_lshl_add_u64 v[112:113], v[112:113], 0, v[148:149]
	s_waitcnt lgkmcnt(0)
	v_add_f32_e32 v114, v114, v115
	v_fmamk_f32 v114, v114, 0x3a800000, v204
	v_rsq_f32_e32 v114, v114
	s_nop 0
	v_pk_mul_f32 v[108:109], v[108:109], v[114:115] op_sel_hi:[1,0]
	v_pk_mul_f32 v[110:111], v[110:111], v[114:115] op_sel_hi:[1,0]
	v_pk_mul_f32 v[104:105], v[104:105], v[114:115] op_sel_hi:[1,0]
	v_pk_mul_f32 v[106:107], v[106:107], v[114:115] op_sel_hi:[1,0]
	v_pk_mul_f32 v[118:119], v[100:101], v[114:115] op_sel_hi:[1,0]
	v_pk_mul_f32 v[120:121], v[102:103], v[114:115] op_sel_hi:[1,0]
	v_pk_mul_f32 v[122:123], v[96:97], v[114:115] op_sel_hi:[1,0]
	v_pk_mul_f32 v[114:115], v[98:99], v[114:115] op_sel_hi:[1,0]
	v_pk_mul_f32 v[98:99], v[14:15], v[110:111]
	v_pk_mul_f32 v[96:97], v[12:13], v[108:109]
	v_pk_mul_f32 v[102:103], v[6:7], v[106:107]
	v_pk_mul_f32 v[100:101], v[4:5], v[104:105]
	v_pk_mul_f32 v[106:107], v[10:11], v[120:121]
	v_pk_mul_f32 v[104:105], v[8:9], v[118:119]
	v_pk_mul_f32 v[110:111], v[2:3], v[114:115]
	v_pk_mul_f32 v[108:109], v[0:1], v[122:123]
	global_store_dwordx4 v[112:113], v[96:99], off
	global_store_dwordx4 v[112:113], v[100:103], off offset:16
	global_store_dwordx4 v[112:113], v[104:107], off offset:512
	global_store_dwordx4 v[112:113], v[108:111], off offset:528
	v_pk_add_f32 v[96:97], v[218:219], v[220:221]
	s_nop 0
	v_add_f32_e32 v96, v96, v97
	ds_bpermute_b32 v97, v205, v96
	s_waitcnt lgkmcnt(0)
;     __device__ __forceinline__ void operator()(const f32x4 (&acc_)[2][2][4][2], const pg8::Unit& u, int wr, int wc, int fr, int fq) const {
;     ...
;             for (int m = 0; m < 4; ++m) {
;                 const int row = row0 + ai * 128 + m * 16; const float* xp = xch + (size_t)row * 16 + 4 * fq;
;                 float s = (__hip_atomic_load(xp + 0, __ATOMIC_RELAXED, __HIP_MEMORY_SCOPE_AGENT) + __hip_atomic_load(xp + 1, __ATOMIC_RELAXED, __HIP_MEMORY_SCOPE_AGENT))
;                         + (__hip_atomic_load(xp + 2, __ATOMIC_RELAXED, __HIP_MEMORY_SCOPE_AGENT) + __hip_atomic_load(xp + 3, __ATOMIC_RELAXED, __HIP_MEMORY_SCOPE_AGENT));
;                 s += __shfl_xor(s, 16); s += __shfl_xor(s, 32);
;                 const float rstd = __builtin_amdgcn_rsqf(s * (1.0f / 1024.0f) + EPS);
; #pragma unroll
;                 for (int bj = 0; bj < 2; ++bj) { const size_t off = (size_t)row * D + col0 + bj * 128;
;                     *(f32x4*)(out + off) = A[ai][bj][m][0] * rstd * g[bj][0]; *(f32x4*)(out + off + 4) = A[ai][bj][m][1] * rstd * g[bj][1]; }
;             }
	v_add_f32_e32 v98, v96, v97
	ds_bpermute_b32 v99, v206, v98
	v_lshlrev_b64 v[96:97], 12, v[152:153]
	v_lshl_add_u64 v[96:97], s[8:9], 0, v[96:97]
	v_lshl_add_u64 v[96:97], v[96:97], 0, v[148:149]
	s_waitcnt lgkmcnt(0)
	v_add_f32_e32 v98, v98, v99
	v_fmamk_f32 v98, v98, 0x3a800000, v204
	v_rsq_f32_e32 v98, v98
	s_nop 0
	v_pk_mul_f32 v[92:93], v[92:93], v[98:99] op_sel_hi:[1,0]
	v_pk_mul_f32 v[94:95], v[94:95], v[98:99] op_sel_hi:[1,0]
	v_pk_mul_f32 v[88:89], v[88:89], v[98:99] op_sel_hi:[1,0]
	v_pk_mul_f32 v[90:91], v[90:91], v[98:99] op_sel_hi:[1,0]
	v_pk_mul_f32 v[102:103], v[84:85], v[98:99] op_sel_hi:[1,0]
	v_pk_mul_f32 v[104:105], v[86:87], v[98:99] op_sel_hi:[1,0]
	v_pk_mul_f32 v[106:107], v[80:81], v[98:99] op_sel_hi:[1,0]
	v_pk_mul_f32 v[98:99], v[82:83], v[98:99] op_sel_hi:[1,0]
	v_pk_mul_f32 v[82:83], v[14:15], v[94:95]
	v_pk_mul_f32 v[80:81], v[12:13], v[92:93]
	v_pk_mul_f32 v[86:87], v[6:7], v[90:91]
	v_pk_mul_f32 v[84:85], v[4:5], v[88:89]
	v_pk_mul_f32 v[90:91], v[10:11], v[104:105]
	v_pk_mul_f32 v[88:89], v[8:9], v[102:103]
	v_pk_mul_f32 v[94:95], v[2:3], v[98:99]
	v_pk_mul_f32 v[92:93], v[0:1], v[106:107]
	global_store_dwordx4 v[96:97], v[80:83], off
	global_store_dwordx4 v[96:97], v[84:87], off offset:16
	global_store_dwordx4 v[96:97], v[88:91], off offset:512
	global_store_dwordx4 v[96:97], v[92:95], off offset:528
	v_pk_add_f32 v[80:81], v[222:223], v[224:225]
	s_nop 0
	v_add_f32_e32 v80, v80, v81
	ds_bpermute_b32 v81, v205, v80
	s_waitcnt lgkmcnt(0)
	v_add_f32_e32 v82, v80, v81
	ds_bpermute_b32 v83, v206, v82
	v_lshlrev_b64 v[80:81], 12, v[154:155]
	v_lshl_add_u64 v[80:81], s[8:9], 0, v[80:81]
	v_lshl_add_u64 v[80:81], v[80:81], 0, v[148:149]
	s_waitcnt lgkmcnt(0)
	v_add_f32_e32 v82, v82, v83
	v_fmamk_f32 v82, v82, 0x3a800000, v204
	v_rsq_f32_e32 v82, v82
	s_nop 0
	v_pk_mul_f32 v[76:77], v[76:77], v[82:83] op_sel_hi:[1,0]
	v_pk_mul_f32 v[78:79], v[78:79], v[82:83] op_sel_hi:[1,0]
	v_pk_mul_f32 v[72:73], v[72:73], v[82:83] op_sel_hi:[1,0]
	v_pk_mul_f32 v[74:75], v[74:75], v[82:83] op_sel_hi:[1,0]
	v_pk_mul_f32 v[86:87], v[68:69], v[82:83] op_sel_hi:[1,0]
	v_pk_mul_f32 v[88:89], v[70:71], v[82:83] op_sel_hi:[1,0]
	v_pk_mul_f32 v[90:91], v[64:65], v[82:83] op_sel_hi:[1,0]
	v_pk_mul_f32 v[82:83], v[66:67], v[82:83] op_sel_hi:[1,0]
	v_pk_mul_f32 v[66:67], v[14:15], v[78:79]
	v_pk_mul_f32 v[64:65], v[12:13], v[76:77]
	v_pk_mul_f32 v[70:71], v[6:7], v[74:75]
	v_pk_mul_f32 v[68:69], v[4:5], v[72:73]
	v_pk_mul_f32 v[74:75], v[10:11], v[88:89]
	v_pk_mul_f32 v[72:73], v[8:9], v[86:87]
	v_pk_mul_f32 v[78:79], v[2:3], v[82:83]
	v_pk_mul_f32 v[76:77], v[0:1], v[90:91]
	global_store_dwordx4 v[80:81], v[64:67], off
	global_store_dwordx4 v[80:81], v[68:71], off offset:16
	global_store_dwordx4 v[80:81], v[72:75], off offset:512
	global_store_dwordx4 v[80:81], v[76:79], off offset:528
	v_pk_add_f32 v[64:65], v[226:227], v[228:229]
	s_nop 0
	v_add_f32_e32 v64, v64, v65
	ds_bpermute_b32 v65, v205, v64
	s_waitcnt lgkmcnt(0)
	v_add_f32_e32 v66, v64, v65
	ds_bpermute_b32 v67, v206, v66
	v_lshlrev_b64 v[64:65], 12, v[158:159]
	v_lshl_add_u64 v[64:65], s[8:9], 0, v[64:65]
	v_lshl_add_u64 v[64:65], v[64:65], 0, v[148:149]
	s_waitcnt lgkmcnt(0)
	v_add_f32_e32 v66, v66, v67
	v_fmamk_f32 v66, v66, 0x3a800000, v204
	v_rsq_f32_e32 v66, v66
	s_nop 0
	v_pk_mul_f32 v[60:61], v[60:61], v[66:67] op_sel_hi:[1,0]
	v_pk_mul_f32 v[62:63], v[62:63], v[66:67] op_sel_hi:[1,0]
	v_pk_mul_f32 v[56:57], v[56:57], v[66:67] op_sel_hi:[1,0]
	v_pk_mul_f32 v[58:59], v[58:59], v[66:67] op_sel_hi:[1,0]
	v_pk_mul_f32 v[70:71], v[52:53], v[66:67] op_sel_hi:[1,0]
	v_pk_mul_f32 v[72:73], v[54:55], v[66:67] op_sel_hi:[1,0]
	v_pk_mul_f32 v[74:75], v[48:49], v[66:67] op_sel_hi:[1,0]
	v_pk_mul_f32 v[66:67], v[50:51], v[66:67] op_sel_hi:[1,0]
	v_pk_mul_f32 v[50:51], v[14:15], v[62:63]
	v_pk_mul_f32 v[48:49], v[12:13], v[60:61]
	v_pk_mul_f32 v[54:55], v[6:7], v[58:59]
	v_pk_mul_f32 v[52:53], v[4:5], v[56:57]
	v_pk_mul_f32 v[58:59], v[10:11], v[72:73]
	v_pk_mul_f32 v[56:57], v[8:9], v[70:71]
	v_pk_mul_f32 v[62:63], v[2:3], v[66:67]
	v_pk_mul_f32 v[60:61], v[0:1], v[74:75]
	global_store_dwordx4 v[64:65], v[48:51], off
	global_store_dwordx4 v[64:65], v[52:55], off offset:16
	global_store_dwordx4 v[64:65], v[56:59], off offset:512
	global_store_dwordx4 v[64:65], v[60:63], off offset:528
	v_pk_add_f32 v[48:49], v[230:231], v[232:233]
	s_nop 0
	v_add_f32_e32 v48, v48, v49
	ds_bpermute_b32 v49, v205, v48
	s_waitcnt lgkmcnt(0)
;     __device__ __forceinline__ void operator()(const f32x4 (&acc_)[2][2][4][2], const pg8::Unit& u, int wr, int wc, int fr, int fq) const {
;     ...
;             for (int m = 0; m < 4; ++m) {
;                 const int row = row0 + ai * 128 + m * 16; const float* xp = xch + (size_t)row * 16 + 4 * fq;
;                 float s = (__hip_atomic_load(xp + 0, __ATOMIC_RELAXED, __HIP_MEMORY_SCOPE_AGENT) + __hip_atomic_load(xp + 1, __ATOMIC_RELAXED, __HIP_MEMORY_SCOPE_AGENT))
;                         + (__hip_atomic_load(xp + 2, __ATOMIC_RELAXED, __HIP_MEMORY_SCOPE_AGENT) + __hip_atomic_load(xp + 3, __ATOMIC_RELAXED, __HIP_MEMORY_SCOPE_AGENT));
;                 s += __shfl_xor(s, 16); s += __shfl_xor(s, 32);
;                 const float rstd = __builtin_amdgcn_rsqf(s * (1.0f / 1024.0f) + EPS);
; #pragma unroll
;                 for (int bj = 0; bj < 2; ++bj) { const size_t off = (size_t)row * D + col0 + bj * 128;
;                     *(f32x4*)(out + off) = A[ai][bj][m][0] * rstd * g[bj][0]; *(f32x4*)(out + off + 4) = A[ai][bj][m][1] * rstd * g[bj][1]; }
;             }
	v_add_f32_e32 v50, v48, v49
	ds_bpermute_b32 v51, v206, v50
	v_lshlrev_b64 v[48:49], 12, v[162:163]
	v_lshl_add_u64 v[48:49], s[8:9], 0, v[48:49]
	v_lshl_add_u64 v[48:49], v[48:49], 0, v[148:149]
	s_waitcnt lgkmcnt(0)
	v_add_f32_e32 v50, v50, v51
	v_fmamk_f32 v50, v50, 0x3a800000, v204
	v_rsq_f32_e32 v50, v50
	s_nop 0
	v_pk_mul_f32 v[44:45], v[44:45], v[50:51] op_sel_hi:[1,0]
	v_pk_mul_f32 v[46:47], v[46:47], v[50:51] op_sel_hi:[1,0]
	v_pk_mul_f32 v[40:41], v[40:41], v[50:51] op_sel_hi:[1,0]
	v_pk_mul_f32 v[42:43], v[42:43], v[50:51] op_sel_hi:[1,0]
	v_pk_mul_f32 v[54:55], v[36:37], v[50:51] op_sel_hi:[1,0]
	v_pk_mul_f32 v[56:57], v[38:39], v[50:51] op_sel_hi:[1,0]
	v_pk_mul_f32 v[58:59], v[32:33], v[50:51] op_sel_hi:[1,0]
	v_pk_mul_f32 v[50:51], v[34:35], v[50:51] op_sel_hi:[1,0]
	v_pk_mul_f32 v[34:35], v[14:15], v[46:47]
	v_pk_mul_f32 v[32:33], v[12:13], v[44:45]
	v_pk_mul_f32 v[38:39], v[6:7], v[42:43]
	v_pk_mul_f32 v[36:37], v[4:5], v[40:41]
	v_pk_mul_f32 v[42:43], v[10:11], v[56:57]
	v_pk_mul_f32 v[40:41], v[8:9], v[54:55]
	v_pk_mul_f32 v[46:47], v[2:3], v[50:51]
	v_pk_mul_f32 v[44:45], v[0:1], v[58:59]
	global_store_dwordx4 v[48:49], v[32:35], off
	global_store_dwordx4 v[48:49], v[36:39], off offset:16
	global_store_dwordx4 v[48:49], v[40:43], off offset:512
	global_store_dwordx4 v[48:49], v[44:47], off offset:528
	v_pk_add_f32 v[32:33], v[234:235], v[236:237]
	s_nop 0
	v_add_f32_e32 v32, v32, v33
	ds_bpermute_b32 v33, v205, v32
	s_waitcnt lgkmcnt(0)
	v_add_f32_e32 v34, v32, v33
	ds_bpermute_b32 v35, v206, v34
	v_lshlrev_b64 v[32:33], 12, v[166:167]
	v_lshl_add_u64 v[32:33], s[8:9], 0, v[32:33]
	v_lshl_add_u64 v[32:33], v[32:33], 0, v[148:149]
	s_waitcnt lgkmcnt(0)
	v_add_f32_e32 v34, v34, v35
	v_fmamk_f32 v34, v34, 0x3a800000, v204
	v_rsq_f32_e32 v34, v34
	s_nop 0
	v_pk_mul_f32 v[28:29], v[28:29], v[34:35] op_sel_hi:[1,0]
	v_pk_mul_f32 v[30:31], v[30:31], v[34:35] op_sel_hi:[1,0]
	v_pk_mul_f32 v[24:25], v[24:25], v[34:35] op_sel_hi:[1,0]
	v_pk_mul_f32 v[26:27], v[26:27], v[34:35] op_sel_hi:[1,0]
	v_pk_mul_f32 v[38:39], v[20:21], v[34:35] op_sel_hi:[1,0]
	v_pk_mul_f32 v[40:41], v[22:23], v[34:35] op_sel_hi:[1,0]
	v_pk_mul_f32 v[42:43], v[16:17], v[34:35] op_sel_hi:[1,0]
	v_pk_mul_f32 v[34:35], v[18:19], v[34:35] op_sel_hi:[1,0]
	v_pk_mul_f32 v[18:19], v[14:15], v[30:31]
	v_pk_mul_f32 v[16:17], v[12:13], v[28:29]
	v_pk_mul_f32 v[22:23], v[6:7], v[26:27]
	v_pk_mul_f32 v[20:21], v[4:5], v[24:25]
	v_pk_mul_f32 v[26:27], v[10:11], v[40:41]
	v_pk_mul_f32 v[24:25], v[8:9], v[38:39]
	v_pk_mul_f32 v[30:31], v[2:3], v[34:35]
	v_pk_mul_f32 v[28:29], v[0:1], v[42:43]
	global_store_dwordx4 v[32:33], v[16:19], off
	global_store_dwordx4 v[32:33], v[20:23], off offset:16
	global_store_dwordx4 v[32:33], v[24:27], off offset:512
	global_store_dwordx4 v[32:33], v[28:31], off offset:528
	v_pk_add_f32 v[16:17], v[238:239], v[240:241]
	s_nop 0
	v_add_f32_e32 v16, v16, v17
	ds_bpermute_b32 v17, v205, v16
	s_waitcnt lgkmcnt(0)
	v_add_f32_e32 v18, v16, v17
	ds_bpermute_b32 v19, v206, v18
	v_lshlrev_b64 v[16:17], 12, v[170:171]
	v_lshl_add_u64 v[16:17], s[8:9], 0, v[16:17]
	v_lshl_add_u64 v[16:17], v[16:17], 0, v[148:149]
	s_waitcnt lgkmcnt(0)
	v_add_f32_e32 v18, v18, v19
	v_fmamk_f32 v18, v18, 0x3a800000, v204
	v_rsq_f32_e32 v18, v18
	s_nop 0
	v_pk_mul_f32 v[20:21], v[178:179], v[18:19] op_sel_hi:[1,0]
	v_pk_mul_f32 v[22:23], v[174:175], v[18:19] op_sel_hi:[1,0]
	v_pk_mul_f32 v[24:25], v[176:177], v[18:19] op_sel_hi:[1,0]
	v_pk_mul_f32 v[26:27], v[172:173], v[18:19] op_sel_hi:[1,0]
	v_pk_mul_f32 v[28:29], v[182:183], v[18:19] op_sel_hi:[1,0]
	v_pk_mul_f32 v[30:31], v[180:181], v[18:19] op_sel_hi:[1,0]
	v_pk_mul_f32 v[32:33], v[188:189], v[18:19] op_sel_hi:[1,0]
	v_pk_mul_f32 v[18:19], v[184:185], v[18:19] op_sel_hi:[1,0]
	v_pk_mul_f32 v[14:15], v[14:15], v[22:23]
	v_pk_mul_f32 v[12:13], v[12:13], v[20:21]
	v_pk_mul_f32 v[6:7], v[6:7], v[26:27]
	v_pk_mul_f32 v[4:5], v[4:5], v[24:25]
	v_pk_mul_f32 v[10:11], v[10:11], v[30:31]
	v_pk_mul_f32 v[8:9], v[8:9], v[28:29]
	v_pk_mul_f32 v[2:3], v[2:3], v[18:19]
	v_pk_mul_f32 v[0:1], v[0:1], v[32:33]
	global_store_dwordx4 v[16:17], v[12:15], off
	global_store_dwordx4 v[16:17], v[4:7], off offset:16
	global_store_dwordx4 v[16:17], v[8:11], off offset:512
	global_store_dwordx4 v[16:17], v[0:3], off offset:528
	s_cbranch_vccnz .LBB0_948
	s_andn2_b64 vcc, exec, s[22:23]
	s_cbranch_vccnz .LBB0_947
	s_barrier
	s_branch .LBB0_947

; #define LAS __attribute__((address_space(3)))
; __global__ void __launch_bounds__(NTHR, 2) mk_fwd(Params p) {
;     extern __shared__ __attribute__((aligned(16))) unsigned char lds_raw[];
;     LAS unsigned char* lds = (LAS unsigned char*)lds_raw;
	.amdhsa_kernel _Z6mk_fwd6Params
		.amdhsa_group_segment_fixed_size 0
		.amdhsa_private_segment_fixed_size 0
		.amdhsa_kernarg_size 424
		.amdhsa_user_sgpr_count 2
		.amdhsa_user_sgpr_dispatch_ptr 0
		.amdhsa_user_sgpr_queue_ptr 0
		.amdhsa_user_sgpr_kernarg_segment_ptr 1
		.amdhsa_user_sgpr_dispatch_id 0
		.amdhsa_user_sgpr_kernarg_preload_length 0
		.amdhsa_user_sgpr_kernarg_preload_offset 0
		.amdhsa_user_sgpr_private_segment_size 0
		.amdhsa_uses_dynamic_stack 0
		.amdhsa_enable_private_segment 0
		.amdhsa_system_sgpr_workgroup_id_x 1
		.amdhsa_system_sgpr_workgroup_id_y 0
		.amdhsa_system_sgpr_workgroup_id_z 0
		.amdhsa_system_sgpr_workgroup_info 0
		.amdhsa_system_vgpr_workitem_id 2
		.amdhsa_next_free_vgpr 256
		.amdhsa_next_free_sgpr 100
		.amdhsa_accum_offset 256
		.amdhsa_reserve_vcc 1
		.amdhsa_float_round_mode_32 0
		.amdhsa_float_round_mode_16_64 0
		.amdhsa_float_denorm_mode_32 3
		.amdhsa_float_denorm_mode_16_64 3
		.amdhsa_dx10_clamp 1
		.amdhsa_ieee_mode 1
		.amdhsa_fp16_overflow 0
		.amdhsa_tg_split 0
		.amdhsa_exception_fp_ieee_invalid_op 0
		.amdhsa_exception_fp_denorm_src 0
		.amdhsa_exception_fp_ieee_div_zero 0
		.amdhsa_exception_fp_ieee_overflow 0
		.amdhsa_exception_fp_ieee_underflow 0
		.amdhsa_exception_fp_ieee_inexact 0
		.amdhsa_exception_int_div_zero 0
	.end_amdhsa_kernel

; #define LAS __attribute__((address_space(3)))
; __global__ void __launch_bounds__(NTHR, 2) mk_fwd(Params p) {
;     extern __shared__ __attribute__((aligned(16))) unsigned char lds_raw[];
;     LAS unsigned char* lds = (LAS unsigned char*)lds_raw;
.Lfunc_end0:
	.size	_Z6mk_fwd6Params, .Lfunc_end0-_Z6mk_fwd6Params
	.set _Z6mk_fwd6Params.num_vgpr, 256
	.set _Z6mk_fwd6Params.num_agpr, 0
	.set _Z6mk_fwd6Params.numbered_sgpr, 100
	.set _Z6mk_fwd6Params.num_named_barrier, 0
	.set _Z6mk_fwd6Params.private_seg_size, 0
	.set _Z6mk_fwd6Params.uses_vcc, 1
	.set _Z6mk_fwd6Params.uses_flat_scratch, 0
	.set _Z6mk_fwd6Params.has_dyn_sized_stack, 0
	.set _Z6mk_fwd6Params.has_recursion, 0
	.set _Z6mk_fwd6Params.has_indirect_call, 0

; #define LAS __attribute__((address_space(3)))
; __global__ void __launch_bounds__(NTHR, 2) mk_fwd(Params p) {
;     extern __shared__ __attribute__((aligned(16))) unsigned char lds_raw[];
;     LAS unsigned char* lds = (LAS unsigned char*)lds_raw;
amdhsa.kernels:
  - .agpr_count:     0
    .args:
      - .offset:         0
        .size:           168
        .value_kind:     by_value
      - .offset:         168
        .size:           4
        .value_kind:     hidden_block_count_x
      - .offset:         172
        .size:           4
        .value_kind:     hidden_block_count_y
      - .offset:         176
        .size:           4
        .value_kind:     hidden_block_count_z
      - .offset:         180
        .size:           2
        .value_kind:     hidden_group_size_x
      - .offset:         182
        .size:           2
        .value_kind:     hidden_group_size_y
      - .offset:         184
        .size:           2
        .value_kind:     hidden_group_size_z
      - .offset:         186
        .size:           2
        .value_kind:     hidden_remainder_x
      - .offset:         188
        .size:           2
        .value_kind:     hidden_remainder_y
      - .offset:         190
        .size:           2
        .value_kind:     hidden_remainder_z
      - .offset:         208
        .size:           8
        .value_kind:     hidden_global_offset_x
      - .offset:         216
        .size:           8
        .value_kind:     hidden_global_offset_y
      - .offset:         224
        .size:           8
        .value_kind:     hidden_global_offset_z
      - .offset:         232
        .size:           2
        .value_kind:     hidden_grid_dims
      - .offset:         256
        .size:           8
        .value_kind:     hidden_multigrid_sync_arg
      - .offset:         288
        .size:           4
        .value_kind:     hidden_dynamic_lds_size
    .group_segment_fixed_size: 0
    .kernarg_segment_align: 8
    .kernarg_segment_size: 424
    .language:       OpenCL C
    .language_version:
      - 2
      - 0
    .max_flat_workgroup_size: 512
    .name:           _Z6mk_fwd6Params
    .private_segment_fixed_size: 0
    .sgpr_count:     106
    .sgpr_spill_count: 76
    .symbol:         _Z6mk_fwd6Params.kd
    .uniform_work_group_size: 1
    .uses_dynamic_stack: false
    .vgpr_count:     256
    .vgpr_spill_count: 0
    .wavefront_size: 64
